# GEMM k-loops: scalar-base LDS-DMA addressing (no per-load 64-bit VALU adds / readfirstlane) on top of up-front fragment reads
# speedup vs baseline: 1.0207x; 1.0207x over previous
.LBB0_230:
	s_ashr_i32 s24, s26, 3
	s_add_i32 s27, s27, s24
	s_mul_hi_i32 s24, s27, 0x4bda12f7
	s_lshr_b32 s25, s24, 31
	s_ashr_i32 s24, s24, 6
	s_add_i32 s24, s24, s25
	s_lshl_b32 s49, s24, 3
	s_mul_i32 s47, s24, 0xd8
	s_sub_i32 s24, 0x84, s49
	s_min_u32 s48, s24, 8
	s_sub_i32 s46, s27, s47
	v_cvt_f32_ubyte0_e32 v1, s48
	v_cvt_f32_i32_e32 v0, s46
	v_rcp_iflag_f32_e32 v2, v1
	s_ashr_i32 s24, s46, 30
	s_or_b32 s26, s24, 1
	v_mul_f32_e32 v2, v0, v2
	v_trunc_f32_e32 v2, v2
	v_fma_f32 v0, -v2, v1, v0
	v_cvt_i32_f32_e32 v2, v2
	v_cmp_ge_f32_e64 s[24:25], |v0|, v1
	s_and_b64 s[24:25], s[24:25], exec
	s_cselect_b32 s24, s26, 0
	v_readfirstlane_b32 s45, v2
	s_add_i32 s45, s45, s24
	s_mul_i32 s50, s45, s48
	s_sub_i32 s24, s46, s50
	s_sext_i32_i16 s24, s24
	s_sext_i32_i16 s26, s45
	s_add_i32 s46, s49, s24
	v_mad_i64_i32 v[0:1], s[24:25], s46, v91, v[66:67]
	v_mad_i64_i32 v[2:3], s[24:25], s26, v91, v[68:69]
	v_readfirstlane_b32 s24, v92
	s_mov_b32 m0, s24
	v_readfirstlane_b32 s24, v93
	s_barrier
	global_load_lds_dwordx4 v[0:1], off
	s_mov_b32 m0, s24
	v_readfirstlane_b32 s24, v94
	global_load_lds_dwordx4 v[2:3], off
	v_lshl_add_u64 v[4:5], v[0:1], 0, s[4:5]
	s_mov_b32 m0, s24
	v_readfirstlane_b32 s24, v95
	global_load_lds_dwordx4 v[4:5], off
	v_lshl_add_u64 v[4:5], v[2:3], 0, s[4:5]
	s_mov_b32 m0, s24
	v_readfirstlane_b32 s24, v96
	global_load_lds_dwordx4 v[4:5], off
	v_lshl_add_u64 v[4:5], v[0:1], 0, s[6:7]
	s_mov_b32 m0, s24
	v_readfirstlane_b32 s24, v97
	global_load_lds_dwordx4 v[4:5], off
	v_lshl_add_u64 v[4:5], v[2:3], 0, s[6:7]
	s_mov_b32 m0, s24
	v_readfirstlane_b32 s24, v98
	global_load_lds_dwordx4 v[4:5], off
	v_lshl_add_u64 v[0:1], v[0:1], 0, s[8:9]
	s_mov_b32 m0, s24
	v_readfirstlane_b32 s24, v99
	global_load_lds_dwordx4 v[0:1], off
	v_lshl_add_u64 v[0:1], v[2:3], 0, s[8:9]
	s_mov_b32 m0, s24
	s_sub_i32 s24, s27, s50
	global_load_lds_dwordx4 v[0:1], off
	s_sub_i32 s24, s24, s47
	s_sext_i32_i16 s24, s24
	s_add_i32 s49, s49, s24
	v_mov_b32_e32 v28, 0
	s_mov_b32 s48, 0
	s_mov_b64 s[24:25], 0
	v_mov_b32_e32 v29, v28
	v_mov_b32_e32 v30, v28
	v_mov_b32_e32 v31, v28
	v_mov_b32_e32 v0, v28
	v_mov_b32_e32 v1, v28
	v_mov_b32_e32 v2, v28
	v_mov_b32_e32 v3, v28
	v_mov_b32_e32 v4, v28
	v_mov_b32_e32 v5, v28
	v_mov_b32_e32 v6, v28
	v_mov_b32_e32 v7, v28
	v_mov_b32_e32 v8, v28
	v_mov_b32_e32 v9, v28
	v_mov_b32_e32 v10, v28
	v_mov_b32_e32 v11, v28
	v_mov_b32_e32 v12, v28
	v_mov_b32_e32 v13, v28
	v_mov_b32_e32 v14, v28
	v_mov_b32_e32 v15, v28
	v_mov_b32_e32 v16, v28
	v_mov_b32_e32 v17, v28
	v_mov_b32_e32 v18, v28
	v_mov_b32_e32 v19, v28
	v_mov_b32_e32 v20, v28
	v_mov_b32_e32 v21, v28
	v_mov_b32_e32 v22, v28
	v_mov_b32_e32 v23, v28
	v_mov_b32_e32 v24, v28
	v_mov_b32_e32 v25, v28
	v_mov_b32_e32 v26, v28
	v_mov_b32_e32 v27, v28
	v_mov_b32_e32 v32, v28
	v_mov_b32_e32 v33, v28
	v_mov_b32_e32 v34, v28
	v_mov_b32_e32 v35, v28
	v_mov_b32_e32 v36, v28
	v_mov_b32_e32 v37, v28
	v_mov_b32_e32 v38, v28
	v_mov_b32_e32 v39, v28
	v_mov_b32_e32 v40, v28
	v_mov_b32_e32 v41, v28
	v_mov_b32_e32 v42, v28
	v_mov_b32_e32 v43, v28
	v_mov_b32_e32 v44, v28
	v_mov_b32_e32 v45, v28
	v_mov_b32_e32 v46, v28
	v_mov_b32_e32 v47, v28
	v_mov_b32_e32 v48, v28
	v_mov_b32_e32 v49, v28
	v_mov_b32_e32 v50, v28
	v_mov_b32_e32 v51, v28
	v_mov_b32_e32 v52, v28
	v_mov_b32_e32 v53, v28
	v_mov_b32_e32 v54, v28
	v_mov_b32_e32 v55, v28
	v_mov_b32_e32 v56, v28
	v_mov_b32_e32 v57, v28
	v_mov_b32_e32 v58, v28
	v_mov_b32_e32 v59, v28
	v_mov_b32_e32 v60, v28
	v_mov_b32_e32 v61, v28
	v_mov_b32_e32 v62, v28
	v_mov_b32_e32 v63, v28
	v_mad_i64_i32 v[80:81], s[50:51], s49, v91, v[76:77]
	v_mad_i64_i32 v[82:83], s[50:51], s26, v91, v[78:79]
	v_readfirstlane_b32 s96, v80
	v_readfirstlane_b32 s97, v81
	v_readfirstlane_b32 s72, v82
	v_readfirstlane_b32 s73, v83
	v_readfirstlane_b32 s71, v84
	s_nop 1
	v_subrev_u32_e32 v244, s96, v80
	v_subrev_u32_e32 v245, s72, v82
	v_add_u32_e32 v246, 0x11000, v244
	v_add_u32_e32 v247, 0x11000, v245
	v_add_u32_e32 v248, 0x22000, v244
	v_add_u32_e32 v249, 0x22000, v245
	v_add_u32_e32 v250, 0x33000, v244
	v_add_u32_e32 v251, 0x33000, v245
	s_add_u32 s96, s96, 0x2200080
	s_addc_u32 s97, s97, 0
	s_add_u32 s72, s72, 0x700080
	s_addc_u32 s73, s73, 0
.LBB0_231:
	s_add_i32 s47, s48, 0x8000
	s_and_b32 s27, s48, 0x8000
	s_and_b32 s50, s47, 0x8000
	s_add_i32 s48, s27, 0
	s_add_i32 s27, s50, 0
	s_add_u32 s70, s27, s71
	s_mov_b32 m0, s70
	s_waitcnt vmcnt(0) lgkmcnt(0)
	s_barrier
	global_load_lds_dwordx4 v244, s[96:97]
	s_add_u32 m0, s70, 0x4000
	s_nop 0
	global_load_lds_dwordx4 v245, s[72:73]
	s_add_u32 m0, s70, 0x1000
	s_nop 0
	global_load_lds_dwordx4 v246, s[96:97]
	s_add_u32 m0, s70, 0x5000
	s_nop 0
	global_load_lds_dwordx4 v247, s[72:73]
	s_add_u32 m0, s70, 0x2000
	s_nop 0
	global_load_lds_dwordx4 v248, s[96:97]
	s_add_u32 m0, s70, 0x6000
	s_nop 0
	global_load_lds_dwordx4 v249, s[72:73]
	s_add_u32 m0, s70, 0x3000
	s_nop 0
	global_load_lds_dwordx4 v250, s[96:97]
	s_add_u32 m0, s70, 0x7000
	s_nop 0
	global_load_lds_dwordx4 v251, s[72:73]
	s_add_u32 s96, s96, 0x80
	s_addc_u32 s97, s97, 0
	s_add_u32 s72, s72, 0x80
	s_addc_u32 s73, s73, 0
	v_add3_u32 v145, s48, v86, v87
	v_add3_u32 v208, s48, v87, v88
	v_add3_u32 v209, s48, v86, v89
	v_add3_u32 v210, s48, v88, v89
	ds_read_b128 v[104:107], v208
	ds_read_b128 v[100:103], v145 offset:16384
	ds_read_b128 v[108:111], v145 offset:18432
	ds_read_b128 v[164:167], v208 offset:2048
	ds_read_b128 v[112:115], v145 offset:20480
	ds_read_b128 v[116:119], v145 offset:22528
	ds_read_b128 v[120:123], v145 offset:24576
	ds_read_b128 v[124:127], v145 offset:26624
	ds_read_b128 v[128:131], v145 offset:28672
	ds_read_b128 v[132:135], v145 offset:30720
	ds_read_b128 v[200:203], v210
	ds_read_b128 v[168:171], v209 offset:16384
	ds_read_b128 v[172:175], v209 offset:18432
	ds_read_b128 v[204:207], v210 offset:2048
	ds_read_b128 v[176:179], v209 offset:20480
	ds_read_b128 v[180:183], v209 offset:22528
	ds_read_b128 v[184:187], v209 offset:24576
	ds_read_b128 v[188:191], v209 offset:26624
	ds_read_b128 v[192:195], v209 offset:28672
	ds_read_b128 v[196:199], v209 offset:30720
	s_add_u32 s24, s24, 0x80
	s_addc_u32 s25, s25, 0
	s_cmpk_eq_i32 s24, 0x780
	s_mov_b32 s48, s47
	s_waitcnt lgkmcnt(15)
	v_mfma_f32_16x16x32_bf16 v[60:63], v[100:103], v[104:107], v[60:63]
	v_mfma_f32_16x16x32_bf16 v[56:59], v[108:111], v[104:107], v[56:59]
	v_mfma_f32_16x16x32_bf16 v[24:27], v[100:103], v[164:167], v[24:27]
	v_mfma_f32_16x16x32_bf16 v[20:23], v[108:111], v[164:167], v[20:23]
	v_mfma_f32_16x16x32_bf16 v[52:55], v[112:115], v[104:107], v[52:55]
	v_mfma_f32_16x16x32_bf16 v[16:19], v[112:115], v[164:167], v[16:19]
	s_waitcnt lgkmcnt(14)
	v_mfma_f32_16x16x32_bf16 v[48:51], v[116:119], v[104:107], v[48:51]
	v_mfma_f32_16x16x32_bf16 v[12:15], v[116:119], v[164:167], v[12:15]
	s_waitcnt lgkmcnt(13)
	v_mfma_f32_16x16x32_bf16 v[44:47], v[120:123], v[104:107], v[44:47]
	v_mfma_f32_16x16x32_bf16 v[8:11], v[120:123], v[164:167], v[8:11]
	s_waitcnt lgkmcnt(12)
	v_mfma_f32_16x16x32_bf16 v[40:43], v[124:127], v[104:107], v[40:43]
	v_mfma_f32_16x16x32_bf16 v[4:7], v[124:127], v[164:167], v[4:7]
	s_waitcnt lgkmcnt(11)
	v_mfma_f32_16x16x32_bf16 v[36:39], v[128:131], v[104:107], v[36:39]
	v_mfma_f32_16x16x32_bf16 v[0:3], v[128:131], v[164:167], v[0:3]
	s_waitcnt lgkmcnt(10)
	v_mfma_f32_16x16x32_bf16 v[32:35], v[132:135], v[104:107], v[32:35]
	v_mfma_f32_16x16x32_bf16 v[28:31], v[132:135], v[164:167], v[28:31]
	s_waitcnt lgkmcnt(8)
	v_mfma_f32_16x16x32_bf16 v[60:63], v[168:171], v[200:203], v[60:63]
	s_waitcnt lgkmcnt(7)
	v_mfma_f32_16x16x32_bf16 v[56:59], v[172:175], v[200:203], v[56:59]
	s_waitcnt lgkmcnt(6)
	v_mfma_f32_16x16x32_bf16 v[24:27], v[168:171], v[204:207], v[24:27]
	v_mfma_f32_16x16x32_bf16 v[20:23], v[172:175], v[204:207], v[20:23]
	s_waitcnt lgkmcnt(5)
	v_mfma_f32_16x16x32_bf16 v[52:55], v[176:179], v[200:203], v[52:55]
	v_mfma_f32_16x16x32_bf16 v[16:19], v[176:179], v[204:207], v[16:19]
	s_waitcnt lgkmcnt(4)
	v_mfma_f32_16x16x32_bf16 v[48:51], v[180:183], v[200:203], v[48:51]
	v_mfma_f32_16x16x32_bf16 v[12:15], v[180:183], v[204:207], v[12:15]
	s_waitcnt lgkmcnt(3)
	v_mfma_f32_16x16x32_bf16 v[44:47], v[184:187], v[200:203], v[44:47]
	v_mfma_f32_16x16x32_bf16 v[8:11], v[184:187], v[204:207], v[8:11]
	s_waitcnt lgkmcnt(2)
	v_mfma_f32_16x16x32_bf16 v[40:43], v[188:191], v[200:203], v[40:43]
	v_mfma_f32_16x16x32_bf16 v[4:7], v[188:191], v[204:207], v[4:7]
	s_waitcnt lgkmcnt(1)
	v_mfma_f32_16x16x32_bf16 v[36:39], v[192:195], v[200:203], v[36:39]
	v_mfma_f32_16x16x32_bf16 v[0:3], v[192:195], v[204:207], v[0:3]
	s_waitcnt lgkmcnt(0)
	v_mfma_f32_16x16x32_bf16 v[32:35], v[196:199], v[200:203], v[32:35]
	v_mfma_f32_16x16x32_bf16 v[28:31], v[196:199], v[204:207], v[28:31]
	s_cbranch_scc0 .LBB0_231
	v_add_u32_e32 v64, s27, v86
	v_add_u32_e32 v136, v64, v87
	v_add3_u32 v108, s27, v87, v88
	s_waitcnt vmcnt(0)
	s_barrier
	ds_read_b128 v[80:83], v136 offset:16384
	ds_read_b128 v[100:103], v136 offset:18432
	ds_read_b128 v[104:107], v108
	ds_read_b128 v[108:111], v108 offset:2048
	ds_read_b128 v[112:115], v136 offset:20480
	ds_read_b128 v[116:119], v136 offset:22528
	ds_read_b128 v[128:131], v136 offset:28672
	s_waitcnt lgkmcnt(2)
	v_mfma_f32_16x16x32_bf16 v[120:123], v[112:115], v[104:107], v[52:55]
	s_nop 2
	ds_read_b128 v[52:55], v136 offset:24576
	ds_read_b128 v[124:127], v136 offset:26624
	s_cmp_gt_i32 s26, 11
	s_waitcnt lgkmcnt(0)
	v_mfma_f32_16x16x32_bf16 v[132:135], v[124:127], v[104:107], v[40:43]
	s_nop 2
	ds_read_b128 v[40:43], v136 offset:30720
	s_cselect_b64 s[24:25], -1, 0
	s_cmp_lt_i32 s26, 12
	v_mfma_f32_16x16x32_bf16 v[60:63], v[80:83], v[104:107], v[60:63]
	s_cselect_b64 s[48:49], -1, 0
	v_mfma_f32_16x16x32_bf16 v[56:59], v[100:103], v[104:107], v[56:59]
	v_mfma_f32_16x16x32_bf16 v[48:51], v[116:119], v[104:107], v[48:51]
	v_mfma_f32_16x16x32_bf16 v[44:47], v[52:55], v[104:107], v[44:47]
	v_mfma_f32_16x16x32_bf16 v[136:139], v[128:131], v[104:107], v[36:39]
	s_waitcnt lgkmcnt(0)
	v_mfma_f32_16x16x32_bf16 v[32:35], v[40:43], v[104:107], v[32:35]
	v_mfma_f32_16x16x32_bf16 v[104:107], v[52:55], v[108:111], v[8:11]
	s_nop 2
	v_add_u32_e32 v8, v64, v89
	v_mfma_f32_16x16x32_bf16 v[24:27], v[80:83], v[108:111], v[24:27]
	v_add3_u32 v9, s27, v89, v88
	v_lshl_or_b32 v64, s26, 7, v90
	s_sub_i32 s26, s26, 18
	v_mfma_f32_16x16x32_bf16 v[80:83], v[112:115], v[108:111], v[16:19]
	s_cmp_lt_u32 s26, 8
	s_cselect_b64 s[26:27], -1, 0
	s_or_b64 s[48:49], s[48:49], s[26:27]
	v_mfma_f32_16x16x32_bf16 v[112:115], v[124:127], v[108:111], v[4:7]
	s_mov_b64 s[26:27], -1
	s_andn2_b64 vcc, exec, s[48:49]
	s_nop 0
	ds_read_b128 v[4:7], v8 offset:16384
	v_mfma_f32_16x16x32_bf16 v[20:23], v[100:103], v[108:111], v[20:23]
	v_mfma_f32_16x16x32_bf16 v[100:103], v[116:119], v[108:111], v[12:15]
	v_mfma_f32_16x16x32_bf16 v[116:119], v[128:131], v[108:111], v[0:3]
	ds_read_b128 v[124:127], v8 offset:18432
	s_nop 1
	ds_read_b128 v[0:3], v9
	ds_read_b128 v[128:131], v9 offset:2048
	ds_read_b128 v[140:143], v8 offset:22528
	ds_read_b128 v[146:149], v8 offset:28672
	s_waitcnt lgkmcnt(3)
	v_mfma_f32_16x16x32_bf16 v[52:55], v[4:7], v[0:3], v[60:63]
	s_nop 2
	ds_read_b128 v[60:63], v8 offset:20480
	v_mfma_f32_16x16x32_bf16 v[108:111], v[40:43], v[108:111], v[28:31]
	s_waitcnt lgkmcnt(0)
	v_mfma_f32_16x16x32_bf16 v[36:39], v[60:63], v[0:3], v[120:123]
	s_nop 2
	ds_read_b128 v[120:123], v8 offset:24576
	v_mfma_f32_16x16x32_bf16 v[40:43], v[140:143], v[0:3], v[48:51]
	s_nop 2
	ds_read_b128 v[48:51], v8 offset:26624
	s_waitcnt lgkmcnt(0)
	v_mfma_f32_16x16x32_bf16 v[16:19], v[48:51], v[0:3], v[132:135]
	s_nop 2
	ds_read_b128 v[132:135], v8 offset:30720
	v_mfma_f32_16x16x32_bf16 v[56:59], v[124:127], v[0:3], v[56:59]
	v_mfma_f32_16x16x32_bf16 v[12:15], v[120:123], v[0:3], v[44:47]
	v_mfma_f32_16x16x32_bf16 v[8:11], v[146:149], v[0:3], v[136:139]
	s_waitcnt lgkmcnt(0)
	v_mfma_f32_16x16x32_bf16 v[0:3], v[132:135], v[0:3], v[32:35]
	v_mfma_f32_16x16x32_bf16 v[28:31], v[4:7], v[128:131], v[24:27]
	v_mfma_f32_16x16x32_bf16 v[20:23], v[124:127], v[128:131], v[20:23]
	v_mfma_f32_16x16x32_bf16 v[4:7], v[60:63], v[128:131], v[80:83]
	v_mfma_f32_16x16x32_bf16 v[24:27], v[140:143], v[128:131], v[100:103]
	s_nop 1
	v_lshl_add_u32 v80, s46, 7, v85
	v_mfma_f32_16x16x32_bf16 v[32:35], v[120:123], v[128:131], v[104:107]
	v_mfma_f32_16x16x32_bf16 v[44:47], v[48:51], v[128:131], v[112:115]
	v_mfma_f32_16x16x32_bf16 v[48:51], v[146:149], v[128:131], v[116:119]
	v_mfma_f32_16x16x32_bf16 v[60:63], v[132:135], v[128:131], v[108:111]
	s_cbranch_vccz .LBB0_240
	s_and_b32 s47, 0xffff, s45
	s_cmp_gt_u32 s47, 17
	s_cbranch_scc0 .LBB0_237
	s_cmp_eq_u32 s47, 26
	s_cselect_b64 s[26:27], -1, 0
	s_and_b64 s[48:49], s[10:11], s[26:27]
	s_and_saveexec_b64 s[26:27], s[48:49]
	s_cbranch_execz .LBB0_236
	global_load_dwordx4 v[100:103], v[72:73], off
	v_mad_i64_i32 v[82:83], s[48:49], v80, s28, v[70:71]
	v_or_b32_e32 v81, 16, v80
	s_waitcnt vmcnt(0)
	v_pk_add_f32 v[102:103], v[54:55], v[102:103]
	v_pk_add_f32 v[100:101], v[52:53], v[100:101]
	global_store_dwordx4 v[82:83], v[100:103], off
	global_load_dwordx4 v[100:103], v[72:73], off offset:16
	v_mad_i64_i32 v[82:83], s[48:49], v80, s28, v[74:75]
	s_waitcnt vmcnt(0)
	v_pk_add_f32 v[102:103], v[58:59], v[102:103]
	v_pk_add_f32 v[100:101], v[56:57], v[100:101]
	global_store_dwordx4 v[82:83], v[100:103], off
	global_load_dwordx4 v[100:103], v[72:73], off
	v_mad_i64_i32 v[82:83], s[48:49], v81, s28, v[70:71]
	s_waitcnt vmcnt(0)
	v_pk_add_f32 v[102:103], v[30:31], v[102:103]
	v_pk_add_f32 v[100:101], v[28:29], v[100:101]
	global_store_dwordx4 v[82:83], v[100:103], off
	global_load_dwordx4 v[100:103], v[72:73], off offset:16
	v_mad_i64_i32 v[82:83], s[48:49], v81, s28, v[74:75]
	s_waitcnt vmcnt(0)
	v_pk_add_f32 v[102:103], v[22:23], v[102:103]
	v_pk_add_f32 v[100:101], v[20:21], v[100:101]
	global_store_dwordx4 v[82:83], v[100:103], off

.LBB0_854:
	s_ashr_i32 s34, s41, 3
	s_add_i32 s34, s43, s34
	s_ashr_i32 s35, s34, 31
	s_lshr_b32 s35, s35, 26
	s_add_i32 s35, s34, s35
	s_ashr_i32 s42, s35, 6
	s_and_b32 s35, s35, 0xffc0
	s_sub_i32 s34, s34, s35
	s_bfe_i32 s35, s34, 0x80000
	s_bfe_u32 s35, s35, 0x3000c
	s_add_i32 s35, s34, s35
	s_bfe_i32 s41, s35, 0x80000
	s_and_b32 s35, s35, 0xf8
	s_sub_i32 s34, s34, s35
	s_lshl_b32 s42, s42, 3
	s_sext_i32_i8 s34, s34
	s_add_i32 s34, s42, s34
	s_ashr_i32 s35, s34, 31
	s_lshr_b32 s35, s35, 26
	s_add_i32 s35, s34, s35
	s_sext_i32_i16 s41, s41
	s_ashr_i32 s42, s35, 6
	s_andn2_b32 s35, s35, 63
	s_ashr_i32 s41, s41, 3
	s_mulk_i32 s42, 0x42
	s_sub_i32 s34, s34, s35
	s_add_i32 s42, s34, s42
	s_mul_i32 s34, s41, 0x22000
	s_add_i32 s42, s42, 2
	s_ashr_i32 s35, s34, 31
	v_readfirstlane_b32 s43, v94
	v_mad_i64_i32 v[0:1], s[44:45], s42, v93, v[64:65]
	s_lshl_b64 s[34:35], s[34:35], 1
	s_mov_b32 m0, s43
	v_readfirstlane_b32 s43, v95
	v_lshl_add_u64 v[2:3], v[66:67], 0, s[34:35]
	s_waitcnt vmcnt(63) expcnt(7) lgkmcnt(15)
	s_barrier
	global_load_lds_dwordx4 v[0:1], off
	s_mov_b32 m0, s43
	v_readfirstlane_b32 s43, v96
	global_load_lds_dwordx4 v[2:3], off
	v_lshl_add_u64 v[4:5], v[0:1], 0, s[8:9]
	s_mov_b32 m0, s43
	v_readfirstlane_b32 s43, v97
	global_load_lds_dwordx4 v[4:5], off
	v_lshl_add_u64 v[4:5], v[2:3], 0, s[8:9]
	s_mov_b32 m0, s43
	v_readfirstlane_b32 s43, v98
	global_load_lds_dwordx4 v[4:5], off
	v_lshl_add_u64 v[4:5], v[0:1], 0, s[10:11]
	s_mov_b32 m0, s43
	v_readfirstlane_b32 s43, v99
	global_load_lds_dwordx4 v[4:5], off
	v_lshl_add_u64 v[4:5], v[2:3], 0, s[10:11]
	s_mov_b32 m0, s43
	v_readfirstlane_b32 s43, v100
	global_load_lds_dwordx4 v[4:5], off
	v_lshl_add_u64 v[0:1], v[0:1], 0, s[12:13]
	s_mov_b32 m0, s43
	v_readfirstlane_b32 s43, v101
	global_load_lds_dwordx4 v[0:1], off
	v_lshl_add_u64 v[0:1], v[2:3], 0, s[12:13]
	s_mov_b32 m0, s43
	v_mov_b32_e32 v36, 0
	global_load_lds_dwordx4 v[0:1], off
	v_mad_i64_i32 v[72:73], s[44:45], s42, v93, v[68:69]
	v_lshl_add_u64 v[74:75], v[70:71], 0, s[34:35]
	s_mov_b64 s[34:35], 0
	s_mov_b32 s43, 0
	v_mov_b32_e32 v37, v36
	v_mov_b32_e32 v38, v36
	v_mov_b32_e32 v39, v36
	v_mov_b32_e32 v0, v36
	v_mov_b32_e32 v1, v36
	v_mov_b32_e32 v2, v36
	v_mov_b32_e32 v3, v36
	v_mov_b32_e32 v4, v36
	v_mov_b32_e32 v5, v36
	v_mov_b32_e32 v6, v36
	v_mov_b32_e32 v7, v36
	v_mov_b32_e32 v8, v36
	v_mov_b32_e32 v9, v36
	v_mov_b32_e32 v10, v36
	v_mov_b32_e32 v11, v36
	v_mov_b32_e32 v12, v36
	v_mov_b32_e32 v13, v36
	v_mov_b32_e32 v14, v36
	v_mov_b32_e32 v15, v36
	v_mov_b32_e32 v16, v36
	v_mov_b32_e32 v17, v36
	v_mov_b32_e32 v18, v36
	v_mov_b32_e32 v19, v36
	v_mov_b32_e32 v20, v36
	v_mov_b32_e32 v21, v36
	v_mov_b32_e32 v22, v36
	v_mov_b32_e32 v23, v36
	v_mov_b32_e32 v24, v36
	v_mov_b32_e32 v25, v36
	v_mov_b32_e32 v26, v36
	v_mov_b32_e32 v27, v36
	v_mov_b32_e32 v28, v36
	v_mov_b32_e32 v29, v36
	v_mov_b32_e32 v30, v36
	v_mov_b32_e32 v31, v36
	v_mov_b32_e32 v32, v36
	v_mov_b32_e32 v33, v36
	v_mov_b32_e32 v34, v36
	v_mov_b32_e32 v35, v36
	v_mov_b32_e32 v40, v36
	v_mov_b32_e32 v41, v36
	v_mov_b32_e32 v42, v36
	v_mov_b32_e32 v43, v36
	v_mov_b32_e32 v44, v36
	v_mov_b32_e32 v45, v36
	v_mov_b32_e32 v46, v36
	v_mov_b32_e32 v47, v36
	v_mov_b32_e32 v48, v36
	v_mov_b32_e32 v49, v36
	v_mov_b32_e32 v50, v36
	v_mov_b32_e32 v51, v36
	v_mov_b32_e32 v52, v36
	v_mov_b32_e32 v53, v36
	v_mov_b32_e32 v54, v36
	v_mov_b32_e32 v55, v36
	v_mov_b32_e32 v56, v36
	v_mov_b32_e32 v57, v36
	v_mov_b32_e32 v58, v36
	v_mov_b32_e32 v59, v36
	v_mov_b32_e32 v60, v36
	v_mov_b32_e32 v61, v36
	v_mov_b32_e32 v62, v36
	v_mov_b32_e32 v63, v36
	v_readfirstlane_b32 s96, v72
	v_readfirstlane_b32 s97, v73
	v_readfirstlane_b32 s88, v74
	v_readfirstlane_b32 s89, v75
	v_readfirstlane_b32 s87, v87
	s_nop 1
	v_subrev_u32_e32 v244, s96, v72
	v_subrev_u32_e32 v245, s88, v74
	v_add_u32_e32 v246, 0x11000, v244
	v_add_u32_e32 v247, 0x11000, v245
	v_add_u32_e32 v248, 0x22000, v244
	v_add_u32_e32 v249, 0x22000, v245
	v_add_u32_e32 v250, 0x33000, v244
	v_add_u32_e32 v251, 0x33000, v245
	s_add_u32 s96, s96, 0x2200080
	s_addc_u32 s97, s97, 0
	s_add_u32 s88, s88, 0xe70080
	s_addc_u32 s89, s89, 0
.LBB0_855:
	s_add_i32 s45, s43, 0x8000
	s_and_b32 s44, s45, 0x8000
	s_add_i32 s44, s44, 0
	s_add_u32 s86, s44, s87
	s_mov_b32 m0, s86
	s_waitcnt vmcnt(0) lgkmcnt(0)
	s_barrier
	global_load_lds_dwordx4 v244, s[96:97]
	s_add_u32 m0, s86, 0x4000
	s_nop 0
	global_load_lds_dwordx4 v245, s[88:89]
	s_add_u32 m0, s86, 0x1000
	s_nop 0
	global_load_lds_dwordx4 v246, s[96:97]
	s_add_u32 m0, s86, 0x5000
	s_nop 0
	global_load_lds_dwordx4 v247, s[88:89]
	s_add_u32 m0, s86, 0x2000
	s_nop 0
	global_load_lds_dwordx4 v248, s[96:97]
	s_add_u32 m0, s86, 0x6000
	s_nop 0
	global_load_lds_dwordx4 v249, s[88:89]
	s_add_u32 m0, s86, 0x3000
	s_nop 0
	global_load_lds_dwordx4 v250, s[96:97]
	s_add_u32 m0, s86, 0x7000
	s_nop 0
	global_load_lds_dwordx4 v251, s[88:89]
	s_add_u32 s96, s96, 0x80
	s_addc_u32 s97, s97, 0
	s_add_u32 s88, s88, 0x80
	s_addc_u32 s89, s89, 0
	s_and_b32 s43, s43, 0x8000
	s_add_i32 s43, s43, 0
	v_add3_u32 v212, s43, v88, v89
	v_add3_u32 v213, s43, v89, v90
	v_add3_u32 v214, s43, v88, v91
	v_add3_u32 v215, s43, v90, v91
	ds_read_b128 v[106:109], v213
	ds_read_b128 v[76:79], v212 offset:16384
	ds_read_b128 v[102:105], v212 offset:18432
	ds_read_b128 v[110:113], v213 offset:2048
	ds_read_b128 v[114:117], v212 offset:20480
	ds_read_b128 v[118:121], v212 offset:22528
	ds_read_b128 v[122:125], v212 offset:24576
	ds_read_b128 v[126:129], v212 offset:26624
	ds_read_b128 v[130:133], v212 offset:28672
	ds_read_b128 v[134:137], v212 offset:30720
	ds_read_b128 v[180:183], v215
	ds_read_b128 v[172:175], v214 offset:16384
	ds_read_b128 v[176:179], v214 offset:18432
	ds_read_b128 v[184:187], v215 offset:2048
	ds_read_b128 v[188:191], v214 offset:20480
	ds_read_b128 v[192:195], v214 offset:22528
	ds_read_b128 v[196:199], v214 offset:24576
	ds_read_b128 v[200:203], v214 offset:26624
	ds_read_b128 v[204:207], v214 offset:28672
	ds_read_b128 v[208:211], v214 offset:30720
	s_add_u32 s34, s34, 0x80
	s_addc_u32 s35, s35, 0
	s_cmpk_eq_i32 s34, 0x780
	s_mov_b32 s43, s45
	s_waitcnt lgkmcnt(15)
	v_mfma_f32_16x16x32_bf16 v[60:63], v[76:79], v[106:109], v[60:63]
	v_mfma_f32_16x16x32_bf16 v[56:59], v[102:105], v[106:109], v[56:59]
	v_mfma_f32_16x16x32_bf16 v[24:27], v[76:79], v[110:113], v[24:27]
	v_mfma_f32_16x16x32_bf16 v[20:23], v[102:105], v[110:113], v[20:23]
	v_mfma_f32_16x16x32_bf16 v[52:55], v[114:117], v[106:109], v[52:55]
	v_mfma_f32_16x16x32_bf16 v[16:19], v[114:117], v[110:113], v[16:19]
	s_waitcnt lgkmcnt(14)
	v_mfma_f32_16x16x32_bf16 v[48:51], v[118:121], v[106:109], v[48:51]
	v_mfma_f32_16x16x32_bf16 v[12:15], v[118:121], v[110:113], v[12:15]
	s_waitcnt lgkmcnt(13)
	v_mfma_f32_16x16x32_bf16 v[44:47], v[122:125], v[106:109], v[44:47]
	v_mfma_f32_16x16x32_bf16 v[8:11], v[122:125], v[110:113], v[8:11]
	s_waitcnt lgkmcnt(12)
	v_mfma_f32_16x16x32_bf16 v[40:43], v[126:129], v[106:109], v[40:43]
	v_mfma_f32_16x16x32_bf16 v[4:7], v[126:129], v[110:113], v[4:7]
	s_waitcnt lgkmcnt(11)
	v_mfma_f32_16x16x32_bf16 v[32:35], v[130:133], v[106:109], v[32:35]
	v_mfma_f32_16x16x32_bf16 v[0:3], v[130:133], v[110:113], v[0:3]
	s_waitcnt lgkmcnt(10)
	v_mfma_f32_16x16x32_bf16 v[28:31], v[134:137], v[106:109], v[28:31]
	v_mfma_f32_16x16x32_bf16 v[36:39], v[134:137], v[110:113], v[36:39]
	s_waitcnt lgkmcnt(8)
	v_mfma_f32_16x16x32_bf16 v[60:63], v[172:175], v[180:183], v[60:63]
	s_waitcnt lgkmcnt(7)
	v_mfma_f32_16x16x32_bf16 v[56:59], v[176:179], v[180:183], v[56:59]
	s_waitcnt lgkmcnt(6)
	v_mfma_f32_16x16x32_bf16 v[24:27], v[172:175], v[184:187], v[24:27]
	v_mfma_f32_16x16x32_bf16 v[20:23], v[176:179], v[184:187], v[20:23]
	s_waitcnt lgkmcnt(5)
	v_mfma_f32_16x16x32_bf16 v[52:55], v[188:191], v[180:183], v[52:55]
	v_mfma_f32_16x16x32_bf16 v[16:19], v[188:191], v[184:187], v[16:19]
	s_waitcnt lgkmcnt(4)
	v_mfma_f32_16x16x32_bf16 v[48:51], v[192:195], v[180:183], v[48:51]
	v_mfma_f32_16x16x32_bf16 v[12:15], v[192:195], v[184:187], v[12:15]
	s_waitcnt lgkmcnt(3)
	v_mfma_f32_16x16x32_bf16 v[44:47], v[196:199], v[180:183], v[44:47]
	v_mfma_f32_16x16x32_bf16 v[8:11], v[196:199], v[184:187], v[8:11]
	s_waitcnt lgkmcnt(2)
	v_mfma_f32_16x16x32_bf16 v[40:43], v[200:203], v[180:183], v[40:43]
	v_mfma_f32_16x16x32_bf16 v[4:7], v[200:203], v[184:187], v[4:7]
	s_waitcnt lgkmcnt(1)
	v_mfma_f32_16x16x32_bf16 v[32:35], v[204:207], v[180:183], v[32:35]
	v_mfma_f32_16x16x32_bf16 v[0:3], v[204:207], v[184:187], v[0:3]
	s_waitcnt lgkmcnt(0)
	v_mfma_f32_16x16x32_bf16 v[28:31], v[208:211], v[180:183], v[28:31]
	v_mfma_f32_16x16x32_bf16 v[36:39], v[208:211], v[184:187], v[36:39]
	s_cbranch_scc0 .LBB0_855
	v_add_u32_e32 v80, s44, v88
	v_add_u32_e32 v81, v80, v89
	v_add3_u32 v106, s44, v89, v90
	s_waitcnt vmcnt(0)
	s_barrier
	ds_read_b128 v[72:75], v81 offset:16384
	ds_read_b128 v[76:79], v81 offset:18432
	ds_read_b128 v[102:105], v106
	ds_read_b128 v[106:109], v106 offset:2048
	ds_read_b128 v[110:113], v81 offset:20480
	ds_read_b128 v[114:117], v81 offset:22528
	ds_read_b128 v[118:121], v81 offset:24576
	ds_read_b128 v[122:125], v81 offset:26624
	ds_read_b128 v[126:129], v81 offset:28672
	ds_read_b128 v[130:133], v81 offset:30720
	v_add_u32_e32 v80, v80, v91
	s_waitcnt lgkmcnt(7)
	v_mfma_f32_16x16x32_bf16 v[60:63], v[72:75], v[102:105], v[60:63]
	s_lshl_b32 s42, s42, 7
	v_mfma_f32_16x16x32_bf16 v[56:59], v[76:79], v[102:105], v[56:59]
	s_waitcnt lgkmcnt(4)
	v_mfma_f32_16x16x32_bf16 v[48:51], v[114:117], v[102:105], v[48:51]
	s_waitcnt lgkmcnt(3)
	v_mfma_f32_16x16x32_bf16 v[44:47], v[118:121], v[102:105], v[44:47]
	s_waitcnt lgkmcnt(2)
	v_mfma_f32_16x16x32_bf16 v[40:43], v[122:125], v[102:105], v[40:43]
	s_waitcnt lgkmcnt(1)
	v_mfma_f32_16x16x32_bf16 v[32:35], v[126:129], v[102:105], v[32:35]
	s_waitcnt lgkmcnt(0)
	v_mfma_f32_16x16x32_bf16 v[28:31], v[130:133], v[102:105], v[28:31]
	v_mfma_f32_16x16x32_bf16 v[24:27], v[72:75], v[106:109], v[24:27]
	ds_read_b128 v[72:75], v80 offset:16384
	v_mfma_f32_16x16x32_bf16 v[52:55], v[110:113], v[102:105], v[52:55]
	v_mfma_f32_16x16x32_bf16 v[20:23], v[76:79], v[106:109], v[20:23]
	v_mfma_f32_16x16x32_bf16 v[16:19], v[110:113], v[106:109], v[16:19]
	v_mfma_f32_16x16x32_bf16 v[12:15], v[114:117], v[106:109], v[12:15]
	v_mfma_f32_16x16x32_bf16 v[8:11], v[118:121], v[106:109], v[8:11]
	v_mfma_f32_16x16x32_bf16 v[4:7], v[122:125], v[106:109], v[4:7]
	v_mfma_f32_16x16x32_bf16 v[0:3], v[126:129], v[106:109], v[0:3]
	v_mfma_f32_16x16x32_bf16 v[102:105], v[130:133], v[106:109], v[36:39]
	s_nop 2
	v_add3_u32 v36, s44, v91, v90
	ds_read_b128 v[76:79], v80 offset:18432
	ds_read_b128 v[106:109], v36
	ds_read_b128 v[110:113], v36 offset:2048
	ds_read_b128 v[130:133], v80 offset:28672
	ds_read_b128 v[134:137], v80 offset:30720
	ds_read_b128 v[114:117], v80 offset:20480
	ds_read_b128 v[118:121], v80 offset:22528
	ds_read_b128 v[122:125], v80 offset:24576
	ds_read_b128 v[126:129], v80 offset:26624
	s_waitcnt lgkmcnt(7)
	v_mfma_f32_16x16x32_bf16 v[60:63], v[72:75], v[106:109], v[60:63]
	v_readlane_b32 s44, v252, 5
	v_readlane_b32 s48, v252, 9
	v_readlane_b32 s49, v252, 10
	s_waitcnt lgkmcnt(5)
	v_mfma_f32_16x16x32_bf16 v[36:39], v[130:133], v[106:109], v[32:35]
	v_readlane_b32 s45, v252, 6
	v_readlane_b32 s46, v252, 7
	v_readlane_b32 s47, v252, 8
	s_waitcnt lgkmcnt(4)
	v_mfma_f32_16x16x32_bf16 v[32:35], v[134:137], v[106:109], v[28:31]
	v_readlane_b32 s50, v252, 11
	v_readlane_b32 s51, v252, 12
	v_readlane_b32 s52, v252, 13
	v_mfma_f32_16x16x32_bf16 v[28:31], v[72:75], v[110:113], v[24:27]
	v_add_u32_e32 v72, s42, v82
	v_mul_hi_i32 v73, v72, s36
	v_lshrrev_b32_e32 v74, 31, v73
	v_mfma_f32_16x16x32_bf16 v[24:27], v[76:79], v[110:113], v[20:23]
	v_readlane_b32 s53, v252, 14
	v_readlane_b32 s54, v252, 15
	v_readlane_b32 s55, v252, 16
	s_waitcnt lgkmcnt(3)
	v_mfma_f32_16x16x32_bf16 v[20:23], v[114:117], v[110:113], v[16:19]
	v_readlane_b32 s56, v252, 17
	v_readlane_b32 s57, v252, 18
	v_readlane_b32 s58, v252, 19
	s_waitcnt lgkmcnt(2)
	v_mfma_f32_16x16x32_bf16 v[16:19], v[118:121], v[110:113], v[12:15]
	v_readlane_b32 s59, v252, 20
	s_waitcnt lgkmcnt(1)
	v_mfma_f32_16x16x32_bf16 v[12:15], v[122:125], v[110:113], v[8:11]
	s_waitcnt lgkmcnt(0)
	v_mfma_f32_16x16x32_bf16 v[8:11], v[126:129], v[110:113], v[4:7]
	s_nop 2
	v_ashrrev_i32_e32 v4, 11, v73
	v_mfma_f32_16x16x32_bf16 v[56:59], v[76:79], v[106:109], v[56:59]
	v_add_u32_e32 v73, v4, v74
	v_mad_i32_i24 v75, v73, s37, v72
	v_lshlrev_b32_e32 v78, 13, v73
	v_mfma_f32_16x16x32_bf16 v[52:55], v[114:117], v[106:109], v[52:55]
	v_cmp_lt_i32_e32 vcc, s38, v75
	v_mov_b64_e32 v[76:77], s[48:49]
	v_add3_u32 v74, v78, v75, s39
	v_mfma_f32_16x16x32_bf16 v[48:51], v[118:121], v[106:109], v[48:51]
	v_mfma_f32_16x16x32_bf16 v[44:47], v[122:125], v[106:109], v[44:47]
	v_mfma_f32_16x16x32_bf16 v[40:43], v[126:129], v[106:109], v[40:43]
	v_mfma_f32_16x16x32_bf16 v[0:3], v[130:133], v[110:113], v[0:3]
	v_mfma_f32_16x16x32_bf16 v[4:7], v[134:137], v[110:113], v[102:105]
	s_and_saveexec_b64 s[34:35], vcc
	s_xor_b64 s[34:35], exec, s[34:35]
	s_cbranch_execz .LBB0_858
	v_readlane_b32 s44, v252, 5
	v_readlane_b32 s45, v252, 6
	v_add3_u32 v72, v78, v75, s39
	v_readlane_b32 s46, v252, 7
	v_readlane_b32 s47, v252, 8
	v_readlane_b32 s48, v252, 9
	v_readlane_b32 s49, v252, 10
	v_readlane_b32 s50, v252, 11
	v_readlane_b32 s51, v252, 12
	v_readlane_b32 s52, v252, 13
	v_readlane_b32 s53, v252, 14
	v_readlane_b32 s54, v252, 15
	v_readlane_b32 s55, v252, 16
	v_readlane_b32 s56, v252, 17
	v_readlane_b32 s57, v252, 18
	v_readlane_b32 s58, v252, 19
	v_readlane_b32 s59, v252, 20
	v_mov_b64_e32 v[76:77], s[44:45]
	s_or_saveexec_b64 s[34:35], s[34:35]
	v_lshl_add_u32 v102, v73, 8, v75
	s_xor_b64 exec, exec, s[34:35]
	s_branch .LBB0_859

.LBB0_1006:
	s_add_i32 s37, s35, 0x8000
	s_and_b32 s36, s37, 0x8000
	s_add_i32 s36, s36, 0
	s_add_u32 s86, s36, s87
	s_mov_b32 m0, s86
	s_waitcnt vmcnt(0) lgkmcnt(0)
	s_barrier
	global_load_lds_dwordx4 v244, s[96:97]
	s_add_u32 m0, s86, 0x4000
	s_nop 0
	global_load_lds_dwordx4 v245, s[88:89]
	s_add_u32 m0, s86, 0x1000
	s_nop 0
	global_load_lds_dwordx4 v246, s[96:97]
	s_add_u32 m0, s86, 0x5000
	s_nop 0
	global_load_lds_dwordx4 v247, s[88:89]
	s_add_u32 m0, s86, 0x2000
	s_nop 0
	global_load_lds_dwordx4 v248, s[96:97]
	s_add_u32 m0, s86, 0x6000
	s_nop 0
	global_load_lds_dwordx4 v249, s[88:89]
	s_add_u32 m0, s86, 0x3000
	s_nop 0
	global_load_lds_dwordx4 v250, s[96:97]
	s_add_u32 m0, s86, 0x7000
	s_nop 0
	global_load_lds_dwordx4 v251, s[88:89]
	s_add_u32 s96, s96, 0x80
	s_addc_u32 s97, s97, 0
	s_add_u32 s88, s88, 0x80
	s_addc_u32 s89, s89, 0
	s_and_b32 s35, s35, 0x8000
	s_add_i32 s35, s35, 0
	v_add3_u32 v143, s35, v80, v81
	v_add3_u32 v145, s35, v81, v82
	v_add3_u32 v206, s35, v80, v83
	v_add3_u32 v207, s35, v82, v83
	ds_read_b128 v[102:105], v145
	ds_read_b128 v[94:97], v143 offset:16384
	ds_read_b128 v[98:101], v143 offset:18432
	ds_read_b128 v[106:109], v145 offset:2048
	ds_read_b128 v[110:113], v143 offset:20480
	ds_read_b128 v[114:117], v143 offset:22528
	ds_read_b128 v[118:121], v143 offset:24576
	ds_read_b128 v[122:125], v143 offset:26624
	ds_read_b128 v[126:129], v143 offset:28672
	ds_read_b128 v[130:133], v143 offset:30720
	ds_read_b128 v[174:177], v207
	ds_read_b128 v[166:169], v206 offset:16384
	ds_read_b128 v[170:173], v206 offset:18432
	ds_read_b128 v[178:181], v207 offset:2048
	ds_read_b128 v[182:185], v206 offset:20480
	ds_read_b128 v[186:189], v206 offset:22528
	ds_read_b128 v[190:193], v206 offset:24576
	ds_read_b128 v[194:197], v206 offset:26624
	ds_read_b128 v[198:201], v206 offset:28672
	ds_read_b128 v[202:205], v206 offset:30720
	s_add_u32 s26, s26, 0x80
	s_addc_u32 s27, s27, 0
	s_cmpk_eq_i32 s26, 0x780
	s_mov_b32 s35, s37
	s_waitcnt lgkmcnt(15)
	v_mfma_f32_16x16x32_bf16 v[60:63], v[94:97], v[102:105], v[60:63]
	v_mfma_f32_16x16x32_bf16 v[56:59], v[98:101], v[102:105], v[56:59]
	v_mfma_f32_16x16x32_bf16 v[28:31], v[94:97], v[106:109], v[28:31]
	v_mfma_f32_16x16x32_bf16 v[24:27], v[98:101], v[106:109], v[24:27]
	v_mfma_f32_16x16x32_bf16 v[52:55], v[110:113], v[102:105], v[52:55]
	v_mfma_f32_16x16x32_bf16 v[16:19], v[110:113], v[106:109], v[16:19]
	s_waitcnt lgkmcnt(14)
	v_mfma_f32_16x16x32_bf16 v[48:51], v[114:117], v[102:105], v[48:51]
	v_mfma_f32_16x16x32_bf16 v[12:15], v[114:117], v[106:109], v[12:15]
	s_waitcnt lgkmcnt(13)
	v_mfma_f32_16x16x32_bf16 v[44:47], v[118:121], v[102:105], v[44:47]
	v_mfma_f32_16x16x32_bf16 v[8:11], v[118:121], v[106:109], v[8:11]
	s_waitcnt lgkmcnt(12)
	v_mfma_f32_16x16x32_bf16 v[40:43], v[122:125], v[102:105], v[40:43]
	v_mfma_f32_16x16x32_bf16 v[4:7], v[122:125], v[106:109], v[4:7]
	s_waitcnt lgkmcnt(11)
	v_mfma_f32_16x16x32_bf16 v[36:39], v[126:129], v[102:105], v[36:39]
	v_mfma_f32_16x16x32_bf16 v[0:3], v[126:129], v[106:109], v[0:3]
	s_waitcnt lgkmcnt(10)
	v_mfma_f32_16x16x32_bf16 v[32:35], v[130:133], v[102:105], v[32:35]
	v_mfma_f32_16x16x32_bf16 v[20:23], v[130:133], v[106:109], v[20:23]
	s_waitcnt lgkmcnt(8)
	v_mfma_f32_16x16x32_bf16 v[60:63], v[166:169], v[174:177], v[60:63]
	s_waitcnt lgkmcnt(7)
	v_mfma_f32_16x16x32_bf16 v[56:59], v[170:173], v[174:177], v[56:59]
	s_waitcnt lgkmcnt(6)
	v_mfma_f32_16x16x32_bf16 v[28:31], v[166:169], v[178:181], v[28:31]
	v_mfma_f32_16x16x32_bf16 v[24:27], v[170:173], v[178:181], v[24:27]
	s_waitcnt lgkmcnt(5)
	v_mfma_f32_16x16x32_bf16 v[52:55], v[182:185], v[174:177], v[52:55]
	v_mfma_f32_16x16x32_bf16 v[16:19], v[182:185], v[178:181], v[16:19]
	s_waitcnt lgkmcnt(4)
	v_mfma_f32_16x16x32_bf16 v[48:51], v[186:189], v[174:177], v[48:51]
	v_mfma_f32_16x16x32_bf16 v[12:15], v[186:189], v[178:181], v[12:15]
	s_waitcnt lgkmcnt(3)
	v_mfma_f32_16x16x32_bf16 v[44:47], v[190:193], v[174:177], v[44:47]
	v_mfma_f32_16x16x32_bf16 v[8:11], v[190:193], v[178:181], v[8:11]
	s_waitcnt lgkmcnt(2)
	v_mfma_f32_16x16x32_bf16 v[40:43], v[194:197], v[174:177], v[40:43]
	v_mfma_f32_16x16x32_bf16 v[4:7], v[194:197], v[178:181], v[4:7]
	s_waitcnt lgkmcnt(1)
	v_mfma_f32_16x16x32_bf16 v[36:39], v[198:201], v[174:177], v[36:39]
	v_mfma_f32_16x16x32_bf16 v[0:3], v[198:201], v[178:181], v[0:3]
	s_waitcnt lgkmcnt(0)
	v_mfma_f32_16x16x32_bf16 v[32:35], v[202:205], v[174:177], v[32:35]
	v_mfma_f32_16x16x32_bf16 v[20:23], v[202:205], v[178:181], v[20:23]
	s_cbranch_scc0 .LBB0_1006
	v_add_u32_e32 v138, s36, v80
	v_add_u32_e32 v126, v138, v81
	s_waitcnt vmcnt(0)
	s_barrier
	ds_read_b128 v[74:77], v126 offset:16384
	v_add3_u32 v102, s36, v81, v82
	ds_read_b128 v[94:97], v102
	ds_read_b128 v[98:101], v126 offset:18432
	ds_read_b128 v[102:105], v102 offset:2048
	ds_read_b128 v[106:109], v126 offset:20480
	ds_read_b128 v[110:113], v126 offset:22528
	ds_read_b128 v[114:117], v126 offset:24576
	ds_read_b128 v[118:121], v126 offset:26624
	v_add3_u32 v134, s36, v83, v82
	v_add_u32_e32 v142, v138, v83
	ds_read_b128 v[122:125], v126 offset:28672
	ds_read_b128 v[126:129], v126 offset:30720
	ds_read_b128 v[130:133], v134
	ds_read_b128 v[134:137], v134 offset:2048
	ds_read_b128 v[138:141], v142 offset:16384
	ds_read_b128 v[146:149], v142 offset:18432
	s_waitcnt lgkmcnt(11)
	v_mfma_f32_16x16x32_bf16 v[56:59], v[98:101], v[94:97], v[56:59]
	s_lshl_b32 s36, s34, 7
	s_lshl_b32 s26, s33, 7
	s_ashr_i32 s27, s26, 31
	v_mfma_f32_16x16x32_bf16 v[60:63], v[74:77], v[94:97], v[60:63]
	s_lshl_b64 s[26:27], s[26:27], 1
	s_add_i32 s31, s31, s28
	s_cmpk_gt_i32 s31, 0x107f
	s_waitcnt lgkmcnt(0)
	v_mfma_f32_16x16x32_bf16 v[56:59], v[146:149], v[130:133], v[56:59]
	v_mfma_f32_16x16x32_bf16 v[48:51], v[110:113], v[94:97], v[48:51]
	v_mfma_f32_16x16x32_bf16 v[52:55], v[106:109], v[94:97], v[52:55]
	s_nop 5
	v_max_f32_e32 v56, v56, v56
	v_max_f32_e32 v57, v57, v57
	v_max_f32_e32 v56, 0, v56
	v_mfma_f32_16x16x32_bf16 v[44:47], v[114:117], v[94:97], v[44:47]
	v_max_f32_e32 v57, 0, v57
	v_max_f32_e32 v59, v59, v59
	v_max_f32_e32 v59, 0, v59
	v_mfma_f32_16x16x32_bf16 v[40:43], v[118:121], v[94:97], v[40:43]
	v_mfma_f32_16x16x32_bf16 v[36:39], v[122:125], v[94:97], v[36:39]
	v_mfma_f32_16x16x32_bf16 v[32:35], v[126:129], v[94:97], v[32:35]
	ds_read_b128 v[94:97], v142 offset:20480
	ds_read_b128 v[150:153], v142 offset:22528
	ds_read_b128 v[154:157], v142 offset:24576
	ds_read_b128 v[158:161], v142 offset:26624
	v_mfma_f32_16x16x32_bf16 v[60:63], v[138:141], v[130:133], v[60:63]
	s_waitcnt lgkmcnt(2)
	v_mfma_f32_16x16x32_bf16 v[48:51], v[150:153], v[130:133], v[48:51]
	v_mfma_f32_16x16x32_bf16 v[16:19], v[106:109], v[102:105], v[16:19]
	v_mul_f32_e64 v106, v56, v56
	v_mul_f32_e64 v107, v57, v57
	v_max_f32_e32 v57, v58, v58
	s_nop 1
	v_max_f32_e32 v60, v60, v60
	v_mfma_f32_16x16x32_bf16 v[24:27], v[98:101], v[102:105], v[24:27]
	v_add_u32_e32 v100, s36, v79
	v_mov_b64_e32 v[98:99], s[0:1]
	v_max_f32_e32 v61, v61, v61
	v_max_f32_e32 v56, v62, v62
	v_max_f32_e32 v58, 0, v57
	v_max_f32_e32 v57, v63, v63
	v_mad_i64_i32 v[100:101], s[34:35], v100, s30, v[98:99]
	v_max_f32_e32 v60, 0, v60
	v_max_f32_e32 v61, 0, v61
	v_max_f32_e32 v56, 0, v56
	v_max_f32_e32 v57, 0, v57
	v_mfma_f32_16x16x32_bf16 v[52:55], v[94:97], v[130:133], v[52:55]
	v_lshl_add_u64 v[100:101], v[100:101], 0, s[26:27]
	v_pk_mul_f32 v[60:61], v[60:61], v[60:61]
	v_pk_mul_f32 v[62:63], v[56:57], v[56:57]
	v_mfma_f32_16x16x32_bf16 v[28:31], v[74:77], v[102:105], v[28:31]
	v_max_f32_e32 v48, v48, v48
	v_max_f32_e32 v49, v49, v49
	ds_read_b128 v[74:77], v142 offset:28672
	ds_read_b128 v[162:165], v142 offset:30720
	v_mfma_f32_16x16x32_bf16 v[12:15], v[110:113], v[102:105], v[12:15]
	v_lshl_add_u64 v[100:101], v[100:101], 0, v[64:65]
	v_cvt_pk_bf16_f32 v56, v60, v61
	v_cvt_pk_bf16_f32 v57, v62, v63
	v_mfma_f32_16x16x32_bf16 v[8:11], v[114:117], v[102:105], v[8:11]
	v_max_f32_e32 v48, 0, v48
	v_max_f32_e32 v49, 0, v49
	v_max_f32_e32 v52, v52, v52
	v_mfma_f32_16x16x32_bf16 v[4:7], v[118:121], v[102:105], v[4:7]
	v_max_f32_e32 v53, v53, v53
	v_max_f32_e32 v51, v51, v51
	v_max_f32_e32 v52, 0, v52
	v_mfma_f32_16x16x32_bf16 v[0:3], v[122:125], v[102:105], v[0:3]
	v_max_f32_e32 v53, 0, v53
	v_max_f32_e32 v51, 0, v51
	v_pk_mul_f32 v[52:53], v[52:53], v[52:53]
	v_mfma_f32_16x16x32_bf16 v[20:23], v[126:129], v[102:105], v[20:23]
	v_mul_f32_e64 v102, v58, v58
	v_mul_f32_e64 v103, v59, v59
	v_cvt_pk_bf16_f32 v58, v106, v107
	v_cvt_pk_bf16_f32 v59, v102, v103
	s_waitcnt lgkmcnt(2)
	v_mfma_f32_16x16x32_bf16 v[40:43], v[158:161], v[130:133], v[40:43]
	global_store_dwordx4 v[100:101], v[56:59], off
	s_nop 1
	v_pk_mul_f32 v[56:57], v[48:49], v[48:49]
	v_max_f32_e32 v49, v50, v50
	v_max_f32_e32 v48, v54, v54
	v_max_f32_e32 v50, 0, v49
	v_max_f32_e32 v49, v55, v55
	v_mfma_f32_16x16x32_bf16 v[44:47], v[154:157], v[130:133], v[44:47]
	v_max_f32_e32 v48, 0, v48
	v_max_f32_e32 v49, 0, v49
	v_pk_mul_f32 v[54:55], v[48:49], v[48:49]
	v_pk_mul_f32 v[58:59], v[50:51], v[50:51]
	v_max_f32_e32 v40, v40, v40
	v_max_f32_e32 v41, v41, v41
	s_waitcnt lgkmcnt(0)
	v_mfma_f32_16x16x32_bf16 v[32:35], v[162:165], v[130:133], v[32:35]
	v_cvt_pk_bf16_f32 v48, v52, v53
	v_cvt_pk_bf16_f32 v49, v54, v55
	v_cvt_pk_bf16_f32 v50, v56, v57
	v_cvt_pk_bf16_f32 v51, v58, v59
	v_max_f32_e32 v40, 0, v40
	v_max_f32_e32 v41, 0, v41
	global_store_dwordx4 v[100:101], v[48:51], off offset:64
	v_max_f32_e32 v44, v44, v44
	v_max_f32_e32 v45, v45, v45
	v_pk_mul_f32 v[48:49], v[40:41], v[40:41]
	v_max_f32_e32 v41, v42, v42
	v_max_f32_e32 v40, v46, v46
	v_max_f32_e32 v42, 0, v41
	v_max_f32_e32 v41, v47, v47
	v_max_f32_e32 v43, v43, v43
	v_mfma_f32_16x16x32_bf16 v[36:39], v[74:77], v[130:133], v[36:39]
	v_max_f32_e32 v44, 0, v44
	v_max_f32_e32 v45, 0, v45
	v_max_f32_e32 v40, 0, v40
	v_max_f32_e32 v41, 0, v41
	v_max_f32_e32 v43, 0, v43
	v_pk_mul_f32 v[44:45], v[44:45], v[44:45]
	v_pk_mul_f32 v[46:47], v[40:41], v[40:41]
	v_pk_mul_f32 v[50:51], v[42:43], v[42:43]
	v_max_f32_e32 v32, v32, v32
	v_max_f32_e32 v33, v33, v33
	v_mfma_f32_16x16x32_bf16 v[24:27], v[146:149], v[134:137], v[24:27]
	v_cvt_pk_bf16_f32 v40, v44, v45
	v_cvt_pk_bf16_f32 v41, v46, v47
	v_cvt_pk_bf16_f32 v42, v48, v49
	v_cvt_pk_bf16_f32 v43, v50, v51
	v_max_f32_e32 v32, 0, v32
	v_max_f32_e32 v33, 0, v33
	global_store_dwordx4 v[100:101], v[40:43], off offset:128
	v_max_f32_e32 v36, v36, v36
	v_max_f32_e32 v37, v37, v37
	v_pk_mul_f32 v[40:41], v[32:33], v[32:33]
	v_max_f32_e32 v33, v34, v34
	v_max_f32_e32 v32, v38, v38
	v_max_f32_e32 v34, 0, v33
	v_max_f32_e32 v33, v39, v39
	v_max_f32_e32 v35, v35, v35
	v_mfma_f32_16x16x32_bf16 v[28:31], v[138:141], v[134:137], v[28:31]
	v_max_f32_e32 v36, 0, v36
	v_max_f32_e32 v37, 0, v37
	v_max_f32_e32 v32, 0, v32
	v_max_f32_e32 v33, 0, v33
	v_max_f32_e32 v35, 0, v35
	v_pk_mul_f32 v[36:37], v[36:37], v[36:37]
	v_pk_mul_f32 v[38:39], v[32:33], v[32:33]
	v_pk_mul_f32 v[42:43], v[34:35], v[34:35]
	v_max_f32_e32 v24, v24, v24
	v_max_f32_e32 v25, v25, v25
	v_mfma_f32_16x16x32_bf16 v[12:15], v[150:153], v[134:137], v[12:15]
	v_cvt_pk_bf16_f32 v32, v36, v37
	v_cvt_pk_bf16_f32 v33, v38, v39
	v_cvt_pk_bf16_f32 v34, v40, v41
	v_cvt_pk_bf16_f32 v35, v42, v43
	v_max_f32_e32 v24, 0, v24
	v_max_f32_e32 v25, 0, v25
	global_store_dwordx4 v[100:101], v[32:35], off offset:192
	v_max_f32_e32 v28, v28, v28
	v_max_f32_e32 v29, v29, v29
	v_pk_mul_f32 v[34:35], v[24:25], v[24:25]
	v_max_f32_e32 v25, v26, v26
	v_add_u32_e32 v32, s36, v84
	v_max_f32_e32 v24, v30, v30
	v_max_f32_e32 v26, 0, v25
	v_max_f32_e32 v25, v31, v31
	v_max_f32_e32 v27, v27, v27
	v_mfma_f32_16x16x32_bf16 v[16:19], v[94:97], v[134:137], v[16:19]
	v_mad_i64_i32 v[32:33], s[34:35], v32, s30, v[98:99]
	v_max_f32_e32 v28, 0, v28
	v_max_f32_e32 v29, 0, v29
	v_max_f32_e32 v24, 0, v24
	v_max_f32_e32 v25, 0, v25
	v_max_f32_e32 v27, 0, v27
	v_lshl_add_u64 v[32:33], v[32:33], 0, s[26:27]
	v_pk_mul_f32 v[28:29], v[28:29], v[28:29]
	v_pk_mul_f32 v[30:31], v[24:25], v[24:25]
	v_pk_mul_f32 v[36:37], v[26:27], v[26:27]
	v_max_f32_e32 v12, v12, v12
	v_max_f32_e32 v13, v13, v13
	v_mfma_f32_16x16x32_bf16 v[4:7], v[158:161], v[134:137], v[4:7]
	v_lshl_add_u64 v[32:33], v[32:33], 0, v[64:65]
	v_cvt_pk_bf16_f32 v24, v28, v29
	v_cvt_pk_bf16_f32 v25, v30, v31
	v_cvt_pk_bf16_f32 v26, v34, v35
	v_cvt_pk_bf16_f32 v27, v36, v37
	v_max_f32_e32 v12, 0, v12
	v_max_f32_e32 v13, 0, v13
	global_store_dwordx4 v[32:33], v[24:27], off
	v_max_f32_e32 v16, v16, v16
	v_max_f32_e32 v17, v17, v17
	v_pk_mul_f32 v[24:25], v[12:13], v[12:13]
	v_max_f32_e32 v13, v14, v14
	v_max_f32_e32 v12, v18, v18
	v_max_f32_e32 v14, 0, v13
	v_max_f32_e32 v13, v19, v19
	v_max_f32_e32 v15, v15, v15
	v_mfma_f32_16x16x32_bf16 v[8:11], v[154:157], v[134:137], v[8:11]
	v_max_f32_e32 v16, 0, v16
	v_max_f32_e32 v17, 0, v17
	v_max_f32_e32 v12, 0, v12
	v_max_f32_e32 v13, 0, v13
	v_max_f32_e32 v15, 0, v15
	v_pk_mul_f32 v[16:17], v[16:17], v[16:17]
	v_pk_mul_f32 v[18:19], v[12:13], v[12:13]
	v_pk_mul_f32 v[26:27], v[14:15], v[14:15]
	v_max_f32_e32 v4, v4, v4
	v_max_f32_e32 v5, v5, v5
	v_cvt_pk_bf16_f32 v12, v16, v17
	v_cvt_pk_bf16_f32 v13, v18, v19
	v_cvt_pk_bf16_f32 v14, v24, v25
	v_cvt_pk_bf16_f32 v15, v26, v27
	v_max_f32_e32 v4, 0, v4
	v_max_f32_e32 v5, 0, v5
	global_store_dwordx4 v[32:33], v[12:15], off offset:64
	v_mfma_f32_16x16x32_bf16 v[0:3], v[74:77], v[134:137], v[0:3]
	v_max_f32_e32 v8, v8, v8
	v_pk_mul_f32 v[12:13], v[4:5], v[4:5]
	v_max_f32_e32 v5, v6, v6
	v_mfma_f32_16x16x32_bf16 v[20:23], v[162:165], v[134:137], v[20:23]
	v_max_f32_e32 v9, v9, v9
	v_max_f32_e32 v4, v10, v10
	v_max_f32_e32 v6, 0, v5
	v_max_f32_e32 v5, v11, v11
	v_max_f32_e32 v7, v7, v7
	v_max_f32_e32 v8, 0, v8
	v_max_f32_e32 v9, 0, v9
	v_max_f32_e32 v4, 0, v4
	v_max_f32_e32 v5, 0, v5
	v_max_f32_e32 v7, 0, v7
	v_pk_mul_f32 v[8:9], v[8:9], v[8:9]
	v_pk_mul_f32 v[10:11], v[4:5], v[4:5]
	v_pk_mul_f32 v[14:15], v[6:7], v[6:7]
	v_cvt_pk_bf16_f32 v4, v8, v9
	v_cvt_pk_bf16_f32 v5, v10, v11
	v_cvt_pk_bf16_f32 v6, v12, v13
	v_cvt_pk_bf16_f32 v7, v14, v15
	global_store_dwordx4 v[32:33], v[4:7], off offset:128
	v_max_f32_e32 v0, v0, v0
	v_max_f32_e32 v1, v1, v1
	v_max_f32_e32 v4, v20, v20
	v_max_f32_e32 v5, v21, v21
	v_max_f32_e32 v2, v2, v2
	v_max_f32_e32 v6, v22, v22
	v_max_f32_e32 v3, v3, v3
	v_max_f32_e32 v7, v23, v23
	v_max_f32_e32 v0, 0, v0
	v_max_f32_e32 v4, 0, v4
	v_max_f32_e32 v1, 0, v1
	v_max_f32_e32 v5, 0, v5
	v_max_f32_e32 v2, 0, v2
	v_max_f32_e32 v6, 0, v6
	v_max_f32_e32 v3, 0, v3
	v_max_f32_e32 v7, 0, v7
	v_pk_mul_f32 v[0:1], v[0:1], v[0:1]
	v_pk_mul_f32 v[4:5], v[4:5], v[4:5]
	v_pk_mul_f32 v[2:3], v[2:3], v[2:3]
	v_pk_mul_f32 v[6:7], v[6:7], v[6:7]
	v_cvt_pk_bf16_f32 v0, v0, v1
	v_cvt_pk_bf16_f32 v1, v2, v3
	v_cvt_pk_bf16_f32 v2, v4, v5
	v_cvt_pk_bf16_f32 v3, v6, v7
	global_store_dwordx4 v[32:33], v[0:3], off offset:192
	s_cbranch_scc0 .LBB0_1005

.LBB0_1070:
	s_ashr_i32 s34, s41, 3
	s_add_i32 s34, s43, s34
	s_ashr_i32 s35, s34, 31
	s_lshr_b32 s35, s35, 26
	s_add_i32 s35, s34, s35
	s_ashr_i32 s42, s35, 6
	s_and_b32 s35, s35, 0xffc0
	s_sub_i32 s34, s34, s35
	s_bfe_i32 s35, s34, 0x80000
	s_bfe_u32 s35, s35, 0x3000c
	s_add_i32 s35, s34, s35
	s_bfe_i32 s41, s35, 0x80000
	s_and_b32 s35, s35, 0xf8
	s_sub_i32 s34, s34, s35
	s_lshl_b32 s42, s42, 3
	s_sext_i32_i8 s34, s34
	s_add_i32 s34, s42, s34
	s_ashr_i32 s35, s34, 31
	s_lshr_b32 s35, s35, 26
	s_add_i32 s35, s34, s35
	s_sext_i32_i16 s41, s41
	s_ashr_i32 s42, s35, 6
	s_andn2_b32 s35, s35, 63
	s_ashr_i32 s41, s41, 3
	s_mulk_i32 s42, 0x42
	s_sub_i32 s34, s34, s35
	s_add_i32 s42, s34, s42
	s_mul_i32 s34, s41, 0x82000
	s_add_i32 s42, s42, 2
	s_ashr_i32 s35, s34, 31
	v_readfirstlane_b32 s43, v94
	v_mad_i64_i32 v[0:1], s[44:45], s42, v93, v[64:65]
	s_lshl_b64 s[34:35], s[34:35], 1
	s_mov_b32 m0, s43
	v_readfirstlane_b32 s43, v95
	v_lshl_add_u64 v[2:3], v[66:67], 0, s[34:35]
	s_waitcnt vmcnt(63) expcnt(7) lgkmcnt(15)
	s_barrier
	global_load_lds_dwordx4 v[0:1], off
	s_mov_b32 m0, s43
	v_readfirstlane_b32 s43, v96
	global_load_lds_dwordx4 v[2:3], off
	v_lshl_add_u64 v[4:5], v[0:1], 0, s[8:9]
	s_mov_b32 m0, s43
	v_readfirstlane_b32 s43, v97
	global_load_lds_dwordx4 v[4:5], off
	v_lshl_add_u64 v[4:5], v[2:3], 0, s[8:9]
	s_mov_b32 m0, s43
	v_readfirstlane_b32 s43, v98
	global_load_lds_dwordx4 v[4:5], off
	v_lshl_add_u64 v[4:5], v[0:1], 0, s[10:11]
	s_mov_b32 m0, s43
	v_readfirstlane_b32 s43, v99
	global_load_lds_dwordx4 v[4:5], off
	v_lshl_add_u64 v[4:5], v[2:3], 0, s[10:11]
	s_mov_b32 m0, s43
	v_readfirstlane_b32 s43, v100
	global_load_lds_dwordx4 v[4:5], off
	v_lshl_add_u64 v[0:1], v[0:1], 0, s[12:13]
	s_mov_b32 m0, s43
	v_readfirstlane_b32 s43, v101
	global_load_lds_dwordx4 v[0:1], off
	v_lshl_add_u64 v[0:1], v[2:3], 0, s[12:13]
	s_mov_b32 m0, s43
	v_mov_b32_e32 v36, 0
	global_load_lds_dwordx4 v[0:1], off
	v_mad_i64_i32 v[72:73], s[44:45], s42, v93, v[68:69]
	v_lshl_add_u64 v[74:75], v[70:71], 0, s[34:35]
	s_mov_b64 s[34:35], 0
	s_mov_b32 s43, 0
	v_mov_b32_e32 v37, v36
	v_mov_b32_e32 v38, v36
	v_mov_b32_e32 v39, v36
	v_mov_b32_e32 v0, v36
	v_mov_b32_e32 v1, v36
	v_mov_b32_e32 v2, v36
	v_mov_b32_e32 v3, v36
	v_mov_b32_e32 v4, v36
	v_mov_b32_e32 v5, v36
	v_mov_b32_e32 v6, v36
	v_mov_b32_e32 v7, v36
	v_mov_b32_e32 v8, v36
	v_mov_b32_e32 v9, v36
	v_mov_b32_e32 v10, v36
	v_mov_b32_e32 v11, v36
	v_mov_b32_e32 v12, v36
	v_mov_b32_e32 v13, v36
	v_mov_b32_e32 v14, v36
	v_mov_b32_e32 v15, v36
	v_mov_b32_e32 v16, v36
	v_mov_b32_e32 v17, v36
	v_mov_b32_e32 v18, v36
	v_mov_b32_e32 v19, v36
	v_mov_b32_e32 v20, v36
	v_mov_b32_e32 v21, v36
	v_mov_b32_e32 v22, v36
	v_mov_b32_e32 v23, v36
	v_mov_b32_e32 v24, v36
	v_mov_b32_e32 v25, v36
	v_mov_b32_e32 v26, v36
	v_mov_b32_e32 v27, v36
	v_mov_b32_e32 v28, v36
	v_mov_b32_e32 v29, v36
	v_mov_b32_e32 v30, v36
	v_mov_b32_e32 v31, v36
	v_mov_b32_e32 v32, v36
	v_mov_b32_e32 v33, v36
	v_mov_b32_e32 v34, v36
	v_mov_b32_e32 v35, v36
	v_mov_b32_e32 v40, v36
	v_mov_b32_e32 v41, v36
	v_mov_b32_e32 v42, v36
	v_mov_b32_e32 v43, v36
	v_mov_b32_e32 v44, v36
	v_mov_b32_e32 v45, v36
	v_mov_b32_e32 v46, v36
	v_mov_b32_e32 v47, v36
	v_mov_b32_e32 v48, v36
	v_mov_b32_e32 v49, v36
	v_mov_b32_e32 v50, v36
	v_mov_b32_e32 v51, v36
	v_mov_b32_e32 v52, v36
	v_mov_b32_e32 v53, v36
	v_mov_b32_e32 v54, v36
	v_mov_b32_e32 v55, v36
	v_mov_b32_e32 v56, v36
	v_mov_b32_e32 v57, v36
	v_mov_b32_e32 v58, v36
	v_mov_b32_e32 v59, v36
	v_mov_b32_e32 v60, v36
	v_mov_b32_e32 v61, v36
	v_mov_b32_e32 v62, v36
	v_mov_b32_e32 v63, v36
	v_readfirstlane_b32 s96, v72
	v_readfirstlane_b32 s97, v73
	v_readfirstlane_b32 s88, v74
	v_readfirstlane_b32 s89, v75
	v_readfirstlane_b32 s87, v88
	s_nop 1
	v_subrev_u32_e32 v244, s96, v72
	v_subrev_u32_e32 v245, s88, v74
	v_add_u32_e32 v246, 0x41000, v244
	v_add_u32_e32 v247, 0x41000, v245
	v_add_u32_e32 v248, 0x82000, v244
	v_add_u32_e32 v249, 0x82000, v245
	v_add_u32_e32 v250, 0xc3000, v244
	v_add_u32_e32 v251, 0xc3000, v245
	s_add_u32 s96, s96, 0x4510080
	s_addc_u32 s97, s97, 0
	s_add_u32 s88, s88, 0x1910080
	s_addc_u32 s89, s89, 0
.LBB0_1071:
	s_add_i32 s45, s43, 0x8000
	s_and_b32 s44, s45, 0x8000
	s_add_i32 s44, s44, 0
	s_add_u32 s86, s44, s87
	s_mov_b32 m0, s86
	s_waitcnt vmcnt(0) lgkmcnt(0)
	s_barrier
	global_load_lds_dwordx4 v244, s[96:97]
	s_add_u32 m0, s86, 0x4000
	s_nop 0
	global_load_lds_dwordx4 v245, s[88:89]
	s_add_u32 m0, s86, 0x1000
	s_nop 0
	global_load_lds_dwordx4 v246, s[96:97]
	s_add_u32 m0, s86, 0x5000
	s_nop 0
	global_load_lds_dwordx4 v247, s[88:89]
	s_add_u32 m0, s86, 0x2000
	s_nop 0
	global_load_lds_dwordx4 v248, s[96:97]
	s_add_u32 m0, s86, 0x6000
	s_nop 0
	global_load_lds_dwordx4 v249, s[88:89]
	s_add_u32 m0, s86, 0x3000
	s_nop 0
	global_load_lds_dwordx4 v250, s[96:97]
	s_add_u32 m0, s86, 0x7000
	s_nop 0
	global_load_lds_dwordx4 v251, s[88:89]
	s_add_u32 s96, s96, 0x80
	s_addc_u32 s97, s97, 0
	s_add_u32 s88, s88, 0x80
	s_addc_u32 s89, s89, 0
	s_and_b32 s43, s43, 0x8000
	s_add_i32 s43, s43, 0
	v_add3_u32 v169, s43, v84, v89
	v_add3_u32 v210, s43, v89, v90
	v_add3_u32 v211, s43, v84, v91
	v_add3_u32 v212, s43, v90, v91
	ds_read_b128 v[106:109], v210
	ds_read_b128 v[76:79], v169 offset:16384
	ds_read_b128 v[102:105], v169 offset:18432
	ds_read_b128 v[110:113], v210 offset:2048
	ds_read_b128 v[114:117], v169 offset:20480
	ds_read_b128 v[118:121], v169 offset:22528
	ds_read_b128 v[122:125], v169 offset:24576
	ds_read_b128 v[126:129], v169 offset:26624
	ds_read_b128 v[130:133], v169 offset:28672
	ds_read_b128 v[134:137], v169 offset:30720
	ds_read_b128 v[178:181], v212
	ds_read_b128 v[170:173], v211 offset:16384
	ds_read_b128 v[174:177], v211 offset:18432
	ds_read_b128 v[182:185], v212 offset:2048
	ds_read_b128 v[186:189], v211 offset:20480
	ds_read_b128 v[190:193], v211 offset:22528
	ds_read_b128 v[194:197], v211 offset:24576
	ds_read_b128 v[198:201], v211 offset:26624
	ds_read_b128 v[202:205], v211 offset:28672
	ds_read_b128 v[206:209], v211 offset:30720
	s_add_u32 s34, s34, 0x80
	s_addc_u32 s35, s35, 0
	s_cmpk_eq_i32 s34, 0x1f80
	s_mov_b32 s43, s45
	s_waitcnt lgkmcnt(15)
	v_mfma_f32_16x16x32_bf16 v[60:63], v[76:79], v[106:109], v[60:63]
	v_mfma_f32_16x16x32_bf16 v[56:59], v[102:105], v[106:109], v[56:59]
	v_mfma_f32_16x16x32_bf16 v[24:27], v[76:79], v[110:113], v[24:27]
	v_mfma_f32_16x16x32_bf16 v[20:23], v[102:105], v[110:113], v[20:23]
	v_mfma_f32_16x16x32_bf16 v[52:55], v[114:117], v[106:109], v[52:55]
	v_mfma_f32_16x16x32_bf16 v[16:19], v[114:117], v[110:113], v[16:19]
	s_waitcnt lgkmcnt(14)
	v_mfma_f32_16x16x32_bf16 v[48:51], v[118:121], v[106:109], v[48:51]
	v_mfma_f32_16x16x32_bf16 v[12:15], v[118:121], v[110:113], v[12:15]
	s_waitcnt lgkmcnt(13)
	v_mfma_f32_16x16x32_bf16 v[44:47], v[122:125], v[106:109], v[44:47]
	v_mfma_f32_16x16x32_bf16 v[8:11], v[122:125], v[110:113], v[8:11]
	s_waitcnt lgkmcnt(12)
	v_mfma_f32_16x16x32_bf16 v[40:43], v[126:129], v[106:109], v[40:43]
	v_mfma_f32_16x16x32_bf16 v[4:7], v[126:129], v[110:113], v[4:7]
	s_waitcnt lgkmcnt(11)
	v_mfma_f32_16x16x32_bf16 v[32:35], v[130:133], v[106:109], v[32:35]
	v_mfma_f32_16x16x32_bf16 v[0:3], v[130:133], v[110:113], v[0:3]
	s_waitcnt lgkmcnt(10)
	v_mfma_f32_16x16x32_bf16 v[28:31], v[134:137], v[106:109], v[28:31]
	v_mfma_f32_16x16x32_bf16 v[36:39], v[134:137], v[110:113], v[36:39]
	s_waitcnt lgkmcnt(8)
	v_mfma_f32_16x16x32_bf16 v[60:63], v[170:173], v[178:181], v[60:63]
	s_waitcnt lgkmcnt(7)
	v_mfma_f32_16x16x32_bf16 v[56:59], v[174:177], v[178:181], v[56:59]
	s_waitcnt lgkmcnt(6)
	v_mfma_f32_16x16x32_bf16 v[24:27], v[170:173], v[182:185], v[24:27]
	v_mfma_f32_16x16x32_bf16 v[20:23], v[174:177], v[182:185], v[20:23]
	s_waitcnt lgkmcnt(5)
	v_mfma_f32_16x16x32_bf16 v[52:55], v[186:189], v[178:181], v[52:55]
	v_mfma_f32_16x16x32_bf16 v[16:19], v[186:189], v[182:185], v[16:19]
	s_waitcnt lgkmcnt(4)
	v_mfma_f32_16x16x32_bf16 v[48:51], v[190:193], v[178:181], v[48:51]
	v_mfma_f32_16x16x32_bf16 v[12:15], v[190:193], v[182:185], v[12:15]
	s_waitcnt lgkmcnt(3)
	v_mfma_f32_16x16x32_bf16 v[44:47], v[194:197], v[178:181], v[44:47]
	v_mfma_f32_16x16x32_bf16 v[8:11], v[194:197], v[182:185], v[8:11]
	s_waitcnt lgkmcnt(2)
	v_mfma_f32_16x16x32_bf16 v[40:43], v[198:201], v[178:181], v[40:43]
	v_mfma_f32_16x16x32_bf16 v[4:7], v[198:201], v[182:185], v[4:7]
	s_waitcnt lgkmcnt(1)
	v_mfma_f32_16x16x32_bf16 v[32:35], v[202:205], v[178:181], v[32:35]
	v_mfma_f32_16x16x32_bf16 v[0:3], v[202:205], v[182:185], v[0:3]
	s_waitcnt lgkmcnt(0)
	v_mfma_f32_16x16x32_bf16 v[28:31], v[206:209], v[178:181], v[28:31]
	v_mfma_f32_16x16x32_bf16 v[36:39], v[206:209], v[182:185], v[36:39]
	s_cbranch_scc0 .LBB0_1071
	v_add_u32_e32 v80, s44, v84
	v_add_u32_e32 v81, v80, v89
	v_add3_u32 v106, s44, v89, v90
	s_waitcnt vmcnt(0)
	s_barrier
	ds_read_b128 v[72:75], v81 offset:16384
	ds_read_b128 v[76:79], v81 offset:18432
	ds_read_b128 v[102:105], v106
	ds_read_b128 v[106:109], v106 offset:2048
	ds_read_b128 v[110:113], v81 offset:20480
	ds_read_b128 v[114:117], v81 offset:22528
	ds_read_b128 v[118:121], v81 offset:24576
	ds_read_b128 v[122:125], v81 offset:26624
	ds_read_b128 v[126:129], v81 offset:28672
	ds_read_b128 v[130:133], v81 offset:30720
	v_add_u32_e32 v80, v80, v91
	s_waitcnt lgkmcnt(7)
	v_mfma_f32_16x16x32_bf16 v[60:63], v[72:75], v[102:105], v[60:63]
	s_lshl_b32 s42, s42, 7
	v_mfma_f32_16x16x32_bf16 v[56:59], v[76:79], v[102:105], v[56:59]
	s_waitcnt lgkmcnt(4)
	v_mfma_f32_16x16x32_bf16 v[48:51], v[114:117], v[102:105], v[48:51]
	s_waitcnt lgkmcnt(3)
	v_mfma_f32_16x16x32_bf16 v[44:47], v[118:121], v[102:105], v[44:47]
	s_waitcnt lgkmcnt(2)
	v_mfma_f32_16x16x32_bf16 v[40:43], v[122:125], v[102:105], v[40:43]
	s_waitcnt lgkmcnt(1)
	v_mfma_f32_16x16x32_bf16 v[32:35], v[126:129], v[102:105], v[32:35]
	s_waitcnt lgkmcnt(0)
	v_mfma_f32_16x16x32_bf16 v[28:31], v[130:133], v[102:105], v[28:31]
	v_mfma_f32_16x16x32_bf16 v[24:27], v[72:75], v[106:109], v[24:27]
	ds_read_b128 v[72:75], v80 offset:16384
	v_mfma_f32_16x16x32_bf16 v[52:55], v[110:113], v[102:105], v[52:55]
	v_mfma_f32_16x16x32_bf16 v[20:23], v[76:79], v[106:109], v[20:23]
	v_mfma_f32_16x16x32_bf16 v[16:19], v[110:113], v[106:109], v[16:19]
	v_mfma_f32_16x16x32_bf16 v[12:15], v[114:117], v[106:109], v[12:15]
	v_mfma_f32_16x16x32_bf16 v[8:11], v[118:121], v[106:109], v[8:11]
	v_mfma_f32_16x16x32_bf16 v[4:7], v[122:125], v[106:109], v[4:7]
	v_mfma_f32_16x16x32_bf16 v[0:3], v[126:129], v[106:109], v[0:3]
	v_mfma_f32_16x16x32_bf16 v[102:105], v[130:133], v[106:109], v[36:39]
	s_nop 2
	v_add3_u32 v36, s44, v91, v90
	ds_read_b128 v[76:79], v80 offset:18432
	ds_read_b128 v[106:109], v36
	ds_read_b128 v[110:113], v36 offset:2048
	ds_read_b128 v[130:133], v80 offset:28672
	ds_read_b128 v[134:137], v80 offset:30720
	ds_read_b128 v[114:117], v80 offset:20480
	ds_read_b128 v[118:121], v80 offset:22528
	ds_read_b128 v[122:125], v80 offset:24576
	ds_read_b128 v[126:129], v80 offset:26624
	s_waitcnt lgkmcnt(7)
	v_mfma_f32_16x16x32_bf16 v[60:63], v[72:75], v[106:109], v[60:63]
	s_waitcnt lgkmcnt(5)
	v_mfma_f32_16x16x32_bf16 v[36:39], v[130:133], v[106:109], v[32:35]
	s_waitcnt lgkmcnt(4)
	v_mfma_f32_16x16x32_bf16 v[32:35], v[134:137], v[106:109], v[28:31]
	v_mfma_f32_16x16x32_bf16 v[28:31], v[72:75], v[110:113], v[24:27]
	v_add_u32_e32 v72, s42, v85
	v_mul_hi_i32 v73, v72, s36
	v_mfma_f32_16x16x32_bf16 v[24:27], v[76:79], v[110:113], v[20:23]
	s_waitcnt lgkmcnt(3)
	v_mfma_f32_16x16x32_bf16 v[20:23], v[114:117], v[110:113], v[16:19]
	s_waitcnt lgkmcnt(2)
	v_mfma_f32_16x16x32_bf16 v[16:19], v[118:121], v[110:113], v[12:15]
	s_waitcnt lgkmcnt(1)
	v_mfma_f32_16x16x32_bf16 v[12:15], v[122:125], v[110:113], v[8:11]
	s_waitcnt lgkmcnt(0)
	v_mfma_f32_16x16x32_bf16 v[8:11], v[126:129], v[110:113], v[4:7]
	s_nop 2
	v_lshrrev_b32_e32 v4, 31, v73
	v_ashrrev_i32_e32 v5, 11, v73
	v_mfma_f32_16x16x32_bf16 v[56:59], v[76:79], v[106:109], v[56:59]
	v_add_u32_e32 v73, v5, v4
	v_mad_i32_i24 v78, v73, s37, v72
	v_lshlrev_b32_e32 v75, 13, v73
	v_mfma_f32_16x16x32_bf16 v[52:55], v[114:117], v[106:109], v[52:55]
	v_cmp_lt_i32_e32 vcc, s38, v78
	v_add3_u32 v74, v75, v78, s39
	v_mfma_f32_16x16x32_bf16 v[48:51], v[118:121], v[106:109], v[48:51]
	v_mfma_f32_16x16x32_bf16 v[44:47], v[122:125], v[106:109], v[44:47]
	v_mfma_f32_16x16x32_bf16 v[40:43], v[126:129], v[106:109], v[40:43]
	v_mfma_f32_16x16x32_bf16 v[4:7], v[130:133], v[110:113], v[0:3]
	v_mfma_f32_16x16x32_bf16 v[0:3], v[134:137], v[110:113], v[102:105]
	s_and_saveexec_b64 s[34:35], vcc
	s_xor_b64 s[34:35], exec, s[34:35]
	v_add3_u32 v72, v75, v78, s39
	s_or_saveexec_b64 s[34:35], s[34:35]
	v_mov_b64_e32 v[76:77], s[92:93]
	v_lshl_add_u32 v75, v73, 8, v78
	s_xor_b64 exec, exec, s[34:35]
	v_lshl_add_u32 v72, v73, 8, v78
	v_mov_b64_e32 v[76:77], s[6:7]
	s_or_b64 exec, exec, s[34:35]
	s_and_saveexec_b64 s[34:35], vcc
	s_xor_b64 s[34:35], exec, s[34:35]
	s_cbranch_execz .LBB0_1078
	v_mul_hi_i32_i24_e32 v79, 0x6000, v73
	v_mul_i32_i24_e32 v78, 0x6000, v73
	s_or_saveexec_b64 s[34:35], s[34:35]
	v_mov_b64_e32 v[80:81], s[92:93]
	s_xor_b64 exec, exec, s[34:35]
	s_cbranch_execnz .LBB0_1079
	s_branch .LBB0_1080

.LBB0_1090:
	s_ashr_i32 s37, s43, 6
	s_and_b32 s8, s42, 3
	s_bfe_u32 s45, s43, 0x30002
	s_mulk_i32 s37, 0x42
	s_bfe_u32 s46, s43, 0x10005
	s_lshl_b32 s36, s8, 11
	s_mul_i32 s47, s45, 0x104000
	s_or_b32 s46, s37, s46
	s_or_b32 s8, s47, s36
	s_and_b32 s44, s43, 3
	s_mul_i32 s52, s46, 0x104000
	s_mul_hi_i32 s37, s46, 0x104000
	s_add_u32 s48, s2, s52
	s_addc_u32 s49, s3, s37
	s_lshl_b32 s50, s44, 11
	s_add_u32 s48, s48, s50
	s_addc_u32 s49, s49, 0
	s_add_u32 s47, s4, s47
	s_addc_u32 s51, s5, 0
	s_add_u32 s50, s47, s50
	s_addc_u32 s51, s51, 0
	v_lshl_add_u64 v[0:1], s[48:49], 0, v[78:79]
	v_readfirstlane_b32 s47, v91
	v_lshl_add_u64 v[0:1], v[0:1], 0, v[80:81]
	v_lshl_add_u64 v[2:3], s[50:51], 0, v[82:83]
	s_mov_b32 m0, s47
	v_readfirstlane_b32 s47, v92
	v_lshl_add_u64 v[2:3], v[2:3], 0, v[80:81]
	s_waitcnt vmcnt(63) expcnt(7) lgkmcnt(15)
	s_barrier
	global_load_lds_dwordx4 v[0:1], off
	s_mov_b32 m0, s47
	v_readfirstlane_b32 s47, v93
	global_load_lds_dwordx4 v[2:3], off
	v_lshl_add_u64 v[4:5], v[0:1], 0, s[10:11]
	s_mov_b32 m0, s47
	v_readfirstlane_b32 s47, v94
	global_load_lds_dwordx4 v[4:5], off
	v_lshl_add_u64 v[4:5], v[2:3], 0, s[10:11]
	s_mov_b32 m0, s47
	v_readfirstlane_b32 s47, v95
	global_load_lds_dwordx4 v[4:5], off
	v_lshl_add_u64 v[4:5], v[0:1], 0, s[12:13]
	s_mov_b32 m0, s47
	v_readfirstlane_b32 s47, v96
	global_load_lds_dwordx4 v[4:5], off
	v_lshl_add_u64 v[4:5], v[2:3], 0, s[12:13]
	s_mov_b32 m0, s47
	v_readfirstlane_b32 s47, v97
	global_load_lds_dwordx4 v[4:5], off
	v_lshl_add_u64 v[0:1], v[0:1], 0, s[14:15]
	s_mov_b32 m0, s47
	v_readfirstlane_b32 s47, v98
	global_load_lds_dwordx4 v[0:1], off
	v_lshl_add_u64 v[0:1], v[2:3], 0, s[14:15]
	s_mov_b32 m0, s47
	s_or_b32 s36, s52, s36
	global_load_lds_dwordx4 v[0:1], off
	v_lshl_add_u64 v[64:65], v[76:77], 0, s[8:9]
	v_lshl_add_u64 v[66:67], v[74:75], 0, s[36:37]
	s_mov_b64 s[36:37], 0
	s_mov_b32 s47, 0
	v_mov_b32_e32 v20, 0
	v_mov_b32_e32 v21, v73
	v_mov_b32_e32 v22, v73
	v_mov_b32_e32 v23, v73
	v_mov_b32_e32 v0, 0
	v_mov_b32_e32 v1, v73
	v_mov_b32_e32 v2, v73
	v_mov_b32_e32 v3, v73
	v_mov_b32_e32 v4, 0
	v_mov_b32_e32 v5, v73
	v_mov_b32_e32 v6, v73
	v_mov_b32_e32 v7, v73
	v_mov_b32_e32 v8, 0
	v_mov_b32_e32 v9, v73
	v_mov_b32_e32 v10, v73
	v_mov_b32_e32 v11, v73
	v_mov_b32_e32 v12, 0
	v_mov_b32_e32 v13, v73
	v_mov_b32_e32 v14, v73
	v_mov_b32_e32 v15, v73
	v_mov_b32_e32 v16, 0
	v_mov_b32_e32 v17, v73
	v_mov_b32_e32 v18, v73
	v_mov_b32_e32 v19, v73
	v_mov_b32_e32 v24, 0
	v_mov_b32_e32 v25, v73
	v_mov_b32_e32 v26, v73
	v_mov_b32_e32 v27, v73
	v_mov_b32_e32 v28, 0
	v_mov_b32_e32 v29, v73
	v_mov_b32_e32 v30, v73
	v_mov_b32_e32 v31, v73
	v_mov_b32_e32 v32, 0
	v_mov_b32_e32 v33, v73
	v_mov_b32_e32 v34, v73
	v_mov_b32_e32 v35, v73
	v_mov_b32_e32 v36, 0
	v_mov_b32_e32 v37, v73
	v_mov_b32_e32 v38, v73
	v_mov_b32_e32 v39, v73
	v_mov_b32_e32 v40, 0
	v_mov_b32_e32 v41, v73
	v_mov_b32_e32 v42, v73
	v_mov_b32_e32 v43, v73
	v_mov_b32_e32 v44, 0
	v_mov_b32_e32 v45, v73
	v_mov_b32_e32 v46, v73
	v_mov_b32_e32 v47, v73
	v_mov_b32_e32 v48, 0
	v_mov_b32_e32 v49, v73
	v_mov_b32_e32 v50, v73
	v_mov_b32_e32 v51, v73
	v_mov_b32_e32 v52, 0
	v_mov_b32_e32 v53, v73
	v_mov_b32_e32 v54, v73
	v_mov_b32_e32 v55, v73
	v_mov_b32_e32 v56, 0
	v_mov_b32_e32 v57, v73
	v_mov_b32_e32 v58, v73
	v_mov_b32_e32 v59, v73
	v_mov_b32_e32 v60, 0
	v_mov_b32_e32 v61, v73
	v_mov_b32_e32 v62, v73
	v_mov_b32_e32 v63, v73
	v_readfirstlane_b32 s84, v66
	v_readfirstlane_b32 s85, v67
	v_readfirstlane_b32 s72, v64
	v_readfirstlane_b32 s73, v65
	v_readfirstlane_b32 s75, v88
	s_nop 1
	v_subrev_u32_e32 v236, s84, v66
	v_subrev_u32_e32 v237, s72, v64
	v_add_u32_e32 v238, 0x41000, v236
	v_add_u32_e32 v239, 0x41000, v237
	v_add_u32_e32 v240, 0x82000, v236
	v_add_u32_e32 v241, 0x82000, v237
	v_add_u32_e32 v242, 0xc3000, v236
	v_add_u32_e32 v243, 0xc3000, v237
	s_add_u32 s84, s84, 0x4510080
	s_addc_u32 s85, s85, 0
	s_add_u32 s72, s72, 0x1910080
	s_addc_u32 s73, s73, 0
.LBB0_1091:
	s_add_i32 s48, s47, 0x8000
	s_and_b32 s8, s47, 0x8000
	s_and_b32 s47, s48, 0x8000
	s_add_i32 s49, s8, 0
	s_add_i32 s8, s47, 0
	s_add_u32 s71, s8, s75
	s_mov_b32 m0, s71
	s_waitcnt vmcnt(0) lgkmcnt(0)
	s_barrier
	global_load_lds_dwordx4 v236, s[84:85]
	s_add_u32 m0, s71, 0x4000
	s_nop 0
	global_load_lds_dwordx4 v237, s[72:73]
	s_add_u32 m0, s71, 0x1000
	s_nop 0
	global_load_lds_dwordx4 v238, s[84:85]
	s_add_u32 m0, s71, 0x5000
	s_nop 0
	global_load_lds_dwordx4 v239, s[72:73]
	s_add_u32 m0, s71, 0x2000
	s_nop 0
	global_load_lds_dwordx4 v240, s[84:85]
	s_add_u32 m0, s71, 0x6000
	s_nop 0
	global_load_lds_dwordx4 v241, s[72:73]
	s_add_u32 m0, s71, 0x3000
	s_nop 0
	global_load_lds_dwordx4 v242, s[84:85]
	s_add_u32 m0, s71, 0x7000
	s_nop 0
	global_load_lds_dwordx4 v243, s[72:73]
	s_add_u32 s84, s84, 0x80
	s_addc_u32 s85, s85, 0
	s_add_u32 s72, s72, 0x80
	s_addc_u32 s73, s73, 0
	v_add3_u32 v169, s49, v84, v87
	v_add3_u32 v210, s49, v87, v89
	v_add3_u32 v211, s49, v84, v90
	v_add3_u32 v212, s49, v89, v90
	ds_read_b128 v[104:107], v210
	ds_read_b128 v[68:71], v169 offset:16384
	ds_read_b128 v[100:103], v169 offset:18432
	ds_read_b128 v[108:111], v210 offset:2048
	ds_read_b128 v[112:115], v169 offset:20480
	ds_read_b128 v[116:119], v169 offset:22528
	ds_read_b128 v[120:123], v169 offset:24576
	ds_read_b128 v[124:127], v169 offset:26624
	ds_read_b128 v[128:131], v169 offset:28672
	ds_read_b128 v[132:135], v169 offset:30720
	ds_read_b128 v[178:181], v212
	ds_read_b128 v[170:173], v211 offset:16384
	ds_read_b128 v[174:177], v211 offset:18432
	ds_read_b128 v[182:185], v212 offset:2048
	ds_read_b128 v[186:189], v211 offset:20480
	ds_read_b128 v[190:193], v211 offset:22528
	ds_read_b128 v[194:197], v211 offset:24576
	ds_read_b128 v[198:201], v211 offset:26624
	ds_read_b128 v[202:205], v211 offset:28672
	ds_read_b128 v[206:209], v211 offset:30720
	s_add_u32 s36, s36, 0x80
	s_addc_u32 s37, s37, 0
	s_cmpk_eq_i32 s36, 0x780
	s_mov_b32 s47, s48
	s_waitcnt lgkmcnt(15)
	v_mfma_f32_16x16x32_bf16 v[60:63], v[68:71], v[104:107], v[60:63]
	v_mfma_f32_16x16x32_bf16 v[56:59], v[100:103], v[104:107], v[56:59]
	v_mfma_f32_16x16x32_bf16 v[28:31], v[68:71], v[108:111], v[28:31]
	v_mfma_f32_16x16x32_bf16 v[24:27], v[100:103], v[108:111], v[24:27]
	v_mfma_f32_16x16x32_bf16 v[52:55], v[112:115], v[104:107], v[52:55]
	v_mfma_f32_16x16x32_bf16 v[16:19], v[112:115], v[108:111], v[16:19]
	s_waitcnt lgkmcnt(14)
	v_mfma_f32_16x16x32_bf16 v[48:51], v[116:119], v[104:107], v[48:51]
	v_mfma_f32_16x16x32_bf16 v[12:15], v[116:119], v[108:111], v[12:15]
	s_waitcnt lgkmcnt(13)
	v_mfma_f32_16x16x32_bf16 v[44:47], v[120:123], v[104:107], v[44:47]
	v_mfma_f32_16x16x32_bf16 v[8:11], v[120:123], v[108:111], v[8:11]
	s_waitcnt lgkmcnt(12)
	v_mfma_f32_16x16x32_bf16 v[40:43], v[124:127], v[104:107], v[40:43]
	v_mfma_f32_16x16x32_bf16 v[4:7], v[124:127], v[108:111], v[4:7]
	s_waitcnt lgkmcnt(11)
	v_mfma_f32_16x16x32_bf16 v[36:39], v[128:131], v[104:107], v[36:39]
	v_mfma_f32_16x16x32_bf16 v[0:3], v[128:131], v[108:111], v[0:3]
	s_waitcnt lgkmcnt(10)
	v_mfma_f32_16x16x32_bf16 v[32:35], v[132:135], v[104:107], v[32:35]
	v_mfma_f32_16x16x32_bf16 v[20:23], v[132:135], v[108:111], v[20:23]
	s_waitcnt lgkmcnt(8)
	v_mfma_f32_16x16x32_bf16 v[60:63], v[170:173], v[178:181], v[60:63]
	s_waitcnt lgkmcnt(7)
	v_mfma_f32_16x16x32_bf16 v[56:59], v[174:177], v[178:181], v[56:59]
	s_waitcnt lgkmcnt(6)
	v_mfma_f32_16x16x32_bf16 v[28:31], v[170:173], v[182:185], v[28:31]
	v_mfma_f32_16x16x32_bf16 v[24:27], v[174:177], v[182:185], v[24:27]
	s_waitcnt lgkmcnt(5)
	v_mfma_f32_16x16x32_bf16 v[52:55], v[186:189], v[178:181], v[52:55]
	v_mfma_f32_16x16x32_bf16 v[16:19], v[186:189], v[182:185], v[16:19]
	s_waitcnt lgkmcnt(4)
	v_mfma_f32_16x16x32_bf16 v[48:51], v[190:193], v[178:181], v[48:51]
	v_mfma_f32_16x16x32_bf16 v[12:15], v[190:193], v[182:185], v[12:15]
	s_waitcnt lgkmcnt(3)
	v_mfma_f32_16x16x32_bf16 v[44:47], v[194:197], v[178:181], v[44:47]
	v_mfma_f32_16x16x32_bf16 v[8:11], v[194:197], v[182:185], v[8:11]
	s_waitcnt lgkmcnt(2)
	v_mfma_f32_16x16x32_bf16 v[40:43], v[198:201], v[178:181], v[40:43]
	v_mfma_f32_16x16x32_bf16 v[4:7], v[198:201], v[182:185], v[4:7]
	s_waitcnt lgkmcnt(1)
	v_mfma_f32_16x16x32_bf16 v[36:39], v[202:205], v[178:181], v[36:39]
	v_mfma_f32_16x16x32_bf16 v[0:3], v[202:205], v[182:185], v[0:3]
	s_waitcnt lgkmcnt(0)
	v_mfma_f32_16x16x32_bf16 v[32:35], v[206:209], v[178:181], v[32:35]
	v_mfma_f32_16x16x32_bf16 v[20:23], v[206:209], v[182:185], v[20:23]
	s_cbranch_scc0 .LBB0_1091
	v_lshl_add_u32 v99, s46, 7, v85
	v_mul_hi_i32 v64, v99, s39
	v_lshrrev_b32_e32 v65, 31, v64
	v_ashrrev_i32_e32 v64, 11, v64
	v_add_u32_e32 v64, v64, v65
	v_mad_i32_i24 v65, v64, s40, v99
	v_cmp_lt_i32_e32 vcc, s41, v65
	v_lshl_or_b32 v72, s45, 9, v86
	s_waitcnt vmcnt(0)
	v_cndmask_b32_e32 v64, 2, v64, vcc
	v_mul_hi_i32_i24_e32 v65, 0x6000, v64
	v_mul_i32_i24_e32 v64, 0x6000, v64
	v_lshl_add_u64 v[64:65], s[94:95], 0, v[64:65]
	v_lshl_add_u64 v[150:151], v[64:65], 0, s[34:35]
	v_lshl_add_u64 v[64:65], v[150:151], 0, v[72:73]
	s_barrier
	global_load_dwordx4 v[100:103], v[64:65], off
	v_add3_u32 v64, s8, v87, v89
	v_add_u32_e32 v68, s8, v84
	ds_read_b128 v[104:107], v64
	ds_read_b128 v[108:111], v64 offset:2048
	v_add3_u32 v65, s8, v90, v89
	v_add_u32_e32 v145, v68, v87
	ds_read_b128 v[112:115], v65
	ds_read_b128 v[64:67], v65 offset:2048
	v_add_u32_e32 v168, v68, v90
	ds_read_b128 v[116:119], v145 offset:16384
	ds_read_b128 v[120:123], v145 offset:18432
	ds_read_b128 v[124:127], v168 offset:16384
	ds_read_b128 v[68:71], v168 offset:18432
	v_mul_hi_i32 v128, v99, s38
	s_waitcnt lgkmcnt(3)
	v_mfma_f32_16x16x32_bf16 v[60:63], v[116:119], v[104:107], v[60:63]
	v_lshrrev_b32_e32 v129, 31, v128
	v_lshrrev_b32_e32 v128, 11, v128
	v_add_u32_e32 v128, v128, v129
	v_lshl_add_u32 v128, v128, 13, v99
	s_lshl_b32 s8, s44, 9
	v_ashrrev_i32_e32 v129, 31, v128
	s_waitcnt lgkmcnt(1)
	v_mfma_f32_16x16x32_bf16 v[60:63], v[124:127], v[112:115], v[60:63]
	v_lshl_add_u64 v[128:129], v[128:129], 0, s[8:9]
	v_lshlrev_b64 v[128:129], 12, v[128:129]
	v_lshl_add_u64 v[128:129], s[6:7], 0, v[128:129]
	v_mov_b32_e32 v153, v73
	v_or_b32_e32 v152, 16, v72
	v_lshl_add_u64 v[154:155], v[128:129], 0, v[72:73]
	v_lshl_add_u64 v[128:129], v[150:151], 0, v[152:153]
	v_mfma_f32_16x16x32_bf16 v[56:59], v[120:123], v[104:107], v[56:59]
	v_mov_b32_e32 v157, v73
	v_or_b32_e32 v156, 0x80, v72
	v_mov_b32_e32 v159, v73
	s_waitcnt lgkmcnt(0)
	v_mfma_f32_16x16x32_bf16 v[56:59], v[68:71], v[112:115], v[56:59]
	v_or_b32_e32 v158, 0x90, v72
	v_lshl_add_u64 v[136:137], v[150:151], 0, v[158:159]
	v_mov_b32_e32 v161, v73
	v_or_b32_e32 v160, 0x100, v72
	v_mov_b32_e32 v163, v73
	v_or_b32_e32 v162, 0x110, v72
	v_lshl_add_u64 v[146:147], v[150:151], 0, v[162:163]
	v_mov_b32_e32 v165, v73
	v_or_b32_e32 v164, 0x180, v72
	v_lshl_add_u64 v[166:167], v[150:151], 0, v[164:165]
	v_mfma_f32_16x16x32_bf16 v[28:31], v[116:119], v[108:111], v[28:31]
	v_or_b32_e32 v99, 16, v99
	s_add_i32 s43, s43, s33
	s_add_i32 s42, s42, s33
	v_mfma_f32_16x16x32_bf16 v[28:31], v[124:127], v[64:67], v[28:31]
	s_cmpk_gt_i32 s43, 0x7f
	s_waitcnt vmcnt(0)
	v_pk_mul_f32 v[62:63], v[62:63], v[102:103]
	v_pk_mul_f32 v[60:61], v[60:61], v[100:101]
	global_store_dwordx4 v[154:155], v[60:63], off
	global_load_dwordx4 v[60:63], v[128:129], off
	v_lshl_add_u64 v[100:101], v[150:151], 0, v[156:157]
	v_mfma_f32_16x16x32_bf16 v[24:27], v[120:123], v[108:111], v[24:27]
	s_waitcnt vmcnt(0)
	v_pk_mul_f32 v[58:59], v[58:59], v[62:63]
	v_pk_mul_f32 v[56:57], v[56:57], v[60:61]
	global_store_dwordx4 v[154:155], v[56:59], off offset:16
	global_load_dwordx4 v[56:59], v[100:101], off
	ds_read_b128 v[60:63], v145 offset:20480
	ds_read_b128 v[100:103], v168 offset:20480
	s_waitcnt lgkmcnt(1)
	v_mfma_f32_16x16x32_bf16 v[52:55], v[60:63], v[104:107], v[52:55]
	ds_read_b128 v[128:131], v145 offset:22528
	ds_read_b128 v[132:135], v168 offset:22528
	s_waitcnt lgkmcnt(2)
	v_mfma_f32_16x16x32_bf16 v[52:55], v[100:103], v[112:115], v[52:55]
	s_waitcnt lgkmcnt(1)
	v_mfma_f32_16x16x32_bf16 v[48:51], v[128:131], v[104:107], v[48:51]
	s_waitcnt vmcnt(0)
	s_nop 4
	v_pk_mul_f32 v[54:55], v[54:55], v[58:59]
	v_pk_mul_f32 v[52:53], v[52:53], v[56:57]
	global_store_dwordx4 v[154:155], v[52:55], off offset:128
	global_load_dwordx4 v[52:55], v[136:137], off
	s_waitcnt lgkmcnt(0)
	v_mfma_f32_16x16x32_bf16 v[48:51], v[132:135], v[112:115], v[48:51]
	v_lshl_add_u64 v[56:57], v[150:151], 0, v[160:161]
	v_mfma_f32_16x16x32_bf16 v[24:27], v[68:71], v[64:67], v[24:27]
	v_mfma_f32_16x16x32_bf16 v[16:19], v[60:63], v[108:111], v[16:19]
	s_waitcnt vmcnt(0)
	s_nop 3
	v_pk_mul_f32 v[50:51], v[50:51], v[54:55]
	v_pk_mul_f32 v[48:49], v[48:49], v[52:53]
	global_store_dwordx4 v[154:155], v[48:51], off offset:144
	global_load_dwordx4 v[48:51], v[56:57], off
	ds_read_b128 v[52:55], v145 offset:24576
	ds_read_b128 v[56:59], v168 offset:24576
	s_waitcnt lgkmcnt(1)
	v_mfma_f32_16x16x32_bf16 v[44:47], v[52:55], v[104:107], v[44:47]
	ds_read_b128 v[136:139], v145 offset:26624
	ds_read_b128 v[140:143], v168 offset:26624
	s_waitcnt lgkmcnt(2)
	v_mfma_f32_16x16x32_bf16 v[44:47], v[56:59], v[112:115], v[44:47]
	s_waitcnt lgkmcnt(1)
	v_mfma_f32_16x16x32_bf16 v[40:43], v[136:139], v[104:107], v[40:43]
	s_waitcnt vmcnt(0)
	s_nop 4
	v_pk_mul_f32 v[46:47], v[46:47], v[50:51]
	v_pk_mul_f32 v[44:45], v[44:45], v[48:49]
	global_store_dwordx4 v[154:155], v[44:47], off offset:256
	global_load_dwordx4 v[44:47], v[146:147], off
	s_waitcnt lgkmcnt(0)
	v_mfma_f32_16x16x32_bf16 v[40:43], v[140:143], v[112:115], v[40:43]
	ds_read_b128 v[48:51], v145 offset:28672
	ds_read_b128 v[146:149], v145 offset:30720
	s_waitcnt lgkmcnt(1)
	v_mfma_f32_16x16x32_bf16 v[36:39], v[48:51], v[104:107], v[36:39]
	s_waitcnt vmcnt(0)
	s_nop 2
	v_pk_mul_f32 v[42:43], v[42:43], v[46:47]
	v_pk_mul_f32 v[40:41], v[40:41], v[44:45]
	global_store_dwordx4 v[154:155], v[40:43], off offset:272
	global_load_dwordx4 v[40:43], v[166:167], off
	ds_read_b128 v[44:47], v168 offset:28672
	s_waitcnt lgkmcnt(1)
	v_mfma_f32_16x16x32_bf16 v[32:35], v[146:149], v[104:107], v[32:35]
	ds_read_b128 v[104:107], v168 offset:30720
	v_mov_b32_e32 v167, v73
	v_or_b32_e32 v166, 0x190, v72
	s_waitcnt lgkmcnt(1)
	v_mfma_f32_16x16x32_bf16 v[36:39], v[44:47], v[112:115], v[36:39]
	v_lshl_add_u64 v[116:117], v[150:151], 0, v[166:167]
	s_waitcnt vmcnt(0)
	s_nop 5
	v_pk_mul_f32 v[38:39], v[38:39], v[42:43]
	v_pk_mul_f32 v[36:37], v[36:37], v[40:41]
	global_store_dwordx4 v[154:155], v[36:39], off offset:384
	global_load_dwordx4 v[36:39], v[116:117], off
	v_mul_hi_i32 v40, v99, s39
	v_lshrrev_b32_e32 v41, 31, v40
	v_ashrrev_i32_e32 v40, 11, v40
	v_add_u32_e32 v40, v40, v41
	v_mad_i32_i24 v41, v40, s40, v99
	v_cmp_lt_i32_e32 vcc, s41, v41
	s_waitcnt lgkmcnt(0)
	v_mfma_f32_16x16x32_bf16 v[32:35], v[104:107], v[112:115], v[32:35]
	v_cndmask_b32_e32 v40, 2, v40, vcc
	v_mul_hi_i32_i24_e32 v41, 0x6000, v40
	v_mul_i32_i24_e32 v40, 0x6000, v40
	v_lshl_add_u64 v[40:41], s[94:95], 0, v[40:41]
	v_lshl_add_u64 v[40:41], v[40:41], 0, s[34:35]
	v_lshl_add_u64 v[42:43], v[40:41], 0, v[72:73]
	v_mfma_f32_16x16x32_bf16 v[16:19], v[100:103], v[64:67], v[16:19]
	s_waitcnt vmcnt(0)
	v_pk_mul_f32 v[34:35], v[34:35], v[38:39]
	v_pk_mul_f32 v[32:33], v[32:33], v[36:37]
	global_store_dwordx4 v[154:155], v[32:35], off offset:400
	global_load_dwordx4 v[32:35], v[42:43], off
	v_mul_hi_i32 v36, v99, s38
	v_lshrrev_b32_e32 v37, 31, v36
	v_lshrrev_b32_e32 v36, 11, v36
	v_add_u32_e32 v36, v36, v37
	v_lshl_add_u32 v36, v36, 13, v99
	v_ashrrev_i32_e32 v37, 31, v36
	v_lshl_add_u64 v[36:37], v[36:37], 0, s[8:9]
	v_lshlrev_b64 v[36:37], 12, v[36:37]
	v_lshl_add_u64 v[36:37], s[6:7], 0, v[36:37]
	v_lshl_add_u64 v[36:37], v[36:37], 0, v[72:73]
	v_lshl_add_u64 v[38:39], v[40:41], 0, v[152:153]
	v_mfma_f32_16x16x32_bf16 v[12:15], v[128:131], v[108:111], v[12:15]
	s_waitcnt vmcnt(0)
	v_pk_mul_f32 v[30:31], v[30:31], v[34:35]
	v_pk_mul_f32 v[28:29], v[28:29], v[32:33]
	global_store_dwordx4 v[36:37], v[28:31], off
	global_load_dwordx4 v[28:31], v[38:39], off
	v_lshl_add_u64 v[32:33], v[40:41], 0, v[156:157]
	v_mfma_f32_16x16x32_bf16 v[12:15], v[132:135], v[64:67], v[12:15]
	s_waitcnt vmcnt(0)
	v_pk_mul_f32 v[26:27], v[26:27], v[30:31]
	v_pk_mul_f32 v[24:25], v[24:25], v[28:29]
	global_store_dwordx4 v[36:37], v[24:27], off offset:16
	global_load_dwordx4 v[24:27], v[32:33], off
	v_lshl_add_u64 v[28:29], v[40:41], 0, v[158:159]
	v_mfma_f32_16x16x32_bf16 v[8:11], v[52:55], v[108:111], v[8:11]
	s_waitcnt vmcnt(0)
	v_pk_mul_f32 v[18:19], v[18:19], v[26:27]
	v_pk_mul_f32 v[16:17], v[16:17], v[24:25]
	global_store_dwordx4 v[36:37], v[16:19], off offset:128
	global_load_dwordx4 v[16:19], v[28:29], off
	v_lshl_add_u64 v[24:25], v[40:41], 0, v[160:161]
	v_mfma_f32_16x16x32_bf16 v[8:11], v[56:59], v[64:67], v[8:11]
	s_waitcnt vmcnt(0)
	v_pk_mul_f32 v[14:15], v[14:15], v[18:19]
	v_pk_mul_f32 v[12:13], v[12:13], v[16:17]
	global_store_dwordx4 v[36:37], v[12:15], off offset:144
	global_load_dwordx4 v[12:15], v[24:25], off
	v_lshl_add_u64 v[16:17], v[40:41], 0, v[162:163]
	v_mfma_f32_16x16x32_bf16 v[4:7], v[136:139], v[108:111], v[4:7]
	s_waitcnt vmcnt(0)
	v_pk_mul_f32 v[10:11], v[10:11], v[14:15]
	v_pk_mul_f32 v[8:9], v[8:9], v[12:13]
	global_store_dwordx4 v[36:37], v[8:11], off offset:256
	global_load_dwordx4 v[8:11], v[16:17], off
	v_mfma_f32_16x16x32_bf16 v[4:7], v[140:143], v[64:67], v[4:7]
	v_lshl_add_u64 v[12:13], v[40:41], 0, v[164:165]
	v_mfma_f32_16x16x32_bf16 v[0:3], v[48:51], v[108:111], v[0:3]
	v_mfma_f32_16x16x32_bf16 v[0:3], v[44:47], v[64:67], v[0:3]
	s_waitcnt vmcnt(0)
	s_nop 3
	v_pk_mul_f32 v[6:7], v[6:7], v[10:11]
	v_pk_mul_f32 v[4:5], v[4:5], v[8:9]
	global_store_dwordx4 v[36:37], v[4:7], off offset:272
	global_load_dwordx4 v[4:7], v[12:13], off
	v_lshl_add_u64 v[8:9], v[40:41], 0, v[166:167]
	v_mfma_f32_16x16x32_bf16 v[20:23], v[146:149], v[108:111], v[20:23]
	s_waitcnt vmcnt(0)
	v_pk_mul_f32 v[2:3], v[2:3], v[6:7]
	v_pk_mul_f32 v[0:1], v[0:1], v[4:5]
	global_store_dwordx4 v[36:37], v[0:3], off offset:384
	global_load_dwordx4 v[0:3], v[8:9], off
	v_mfma_f32_16x16x32_bf16 v[4:7], v[104:107], v[64:67], v[20:23]
	s_waitcnt vmcnt(0)
	s_nop 6
	v_pk_mul_f32 v[2:3], v[6:7], v[2:3]
	v_pk_mul_f32 v[0:1], v[4:5], v[0:1]
	global_store_dwordx4 v[36:37], v[0:3], off offset:400
	s_cbranch_scc0 .LBB0_1090

.LBB0_1216:
	s_ashr_i32 s0, s52, 31
	s_lshr_b32 s0, s0, 29
	s_add_i32 s0, s52, s0
	s_ashr_i32 s1, s0, 3
	s_and_b32 s0, s0, -8
	s_sub_i32 s0, s52, s0
	s_cmp_lt_i32 s0, 0
	s_cselect_b32 s2, s47, 0x16b
	s_mul_i32 s0, s2, s0
	s_add_i32 s3, s0, s1
	s_mul_hi_i32 s0, s3, 0x2e8ba2e9
	s_lshr_b32 s1, s0, 31
	s_ashr_i32 s0, s0, 5
	s_add_i32 s0, s0, s1
	s_lshl_b32 s41, s0, 3
	s_mul_i32 s40, s0, 0xb0
	s_sub_i32 s0, 0x84, s41
	s_min_u32 s42, s0, 8
	s_sub_i32 s2, s3, s40
	v_cvt_f32_ubyte0_e32 v1, s42
	v_cvt_f32_i32_e32 v0, s2
	v_rcp_iflag_f32_e32 v2, v1
	s_ashr_i32 s0, s2, 30
	s_or_b32 s38, s0, 1
	s_waitcnt vmcnt(63) expcnt(7) lgkmcnt(15)
	v_mul_f32_e32 v2, v0, v2
	v_trunc_f32_e32 v2, v2
	v_fma_f32 v0, -v2, v1, v0
	v_cvt_i32_f32_e32 v2, v2
	v_cmp_ge_f32_e64 s[0:1], |v0|, v1
	s_and_b64 s[0:1], s[0:1], exec
	s_cselect_b32 s0, s38, 0
	v_readfirstlane_b32 s38, v2
	s_add_i32 s38, s38, s0
	s_mul_i32 s42, s38, s42
	s_sub_i32 s0, s2, s42
	s_sext_i32_i16 s0, s0
	s_sext_i32_i16 s39, s38
	s_add_i32 s2, s41, s0
	v_mad_i64_i32 v[0:1], s[0:1], s2, v93, v[66:67]
	v_mad_i64_i32 v[2:3], s[0:1], s39, v93, v[68:69]
	v_readfirstlane_b32 s0, v94
	s_mov_b32 m0, s0
	v_readfirstlane_b32 s0, v95
	s_barrier
	global_load_lds_dwordx4 v[0:1], off
	s_mov_b32 m0, s0
	v_readfirstlane_b32 s0, v96
	global_load_lds_dwordx4 v[2:3], off
	v_lshl_add_u64 v[4:5], v[0:1], 0, s[12:13]
	s_mov_b32 m0, s0
	v_readfirstlane_b32 s0, v97
	global_load_lds_dwordx4 v[4:5], off
	v_lshl_add_u64 v[4:5], v[2:3], 0, s[12:13]
	s_mov_b32 m0, s0
	v_readfirstlane_b32 s0, v98
	global_load_lds_dwordx4 v[4:5], off
	v_lshl_add_u64 v[4:5], v[0:1], 0, s[14:15]
	s_mov_b32 m0, s0
	v_readfirstlane_b32 s0, v99
	global_load_lds_dwordx4 v[4:5], off
	v_lshl_add_u64 v[4:5], v[2:3], 0, s[14:15]
	s_mov_b32 m0, s0
	v_readfirstlane_b32 s0, v100
	global_load_lds_dwordx4 v[4:5], off
	v_lshl_add_u64 v[0:1], v[0:1], 0, s[16:17]
	s_mov_b32 m0, s0
	v_readfirstlane_b32 s0, v101
	global_load_lds_dwordx4 v[0:1], off
	v_lshl_add_u64 v[0:1], v[2:3], 0, s[16:17]
	s_mov_b32 m0, s0
	s_sub_i32 s0, s3, s42
	global_load_lds_dwordx4 v[0:1], off
	s_sub_i32 s0, s0, s40
	s_sext_i32_i16 s0, s0
	s_add_i32 s41, s41, s0
	v_mad_i64_i32 v[82:83], s[0:1], s41, v93, v[78:79]
	v_mad_i64_i32 v[84:85], s[0:1], s39, v93, v[80:81]
	s_mov_b64 s[0:1], 0
	s_mov_b32 s3, 0
	v_mov_b32_e32 v40, 0
	v_mov_b32_e32 v41, v65
	v_mov_b32_e32 v42, v65
	v_mov_b32_e32 v43, v65
	v_mov_b32_e32 v0, 0
	v_mov_b32_e32 v1, v65
	v_mov_b32_e32 v2, v65
	v_mov_b32_e32 v3, v65
	v_mov_b32_e32 v4, 0
	v_mov_b32_e32 v5, v65
	v_mov_b32_e32 v6, v65
	v_mov_b32_e32 v7, v65
	v_mov_b32_e32 v8, 0
	v_mov_b32_e32 v9, v65
	v_mov_b32_e32 v10, v65
	v_mov_b32_e32 v11, v65
	v_mov_b32_e32 v12, 0
	v_mov_b32_e32 v13, v65
	v_mov_b32_e32 v14, v65
	v_mov_b32_e32 v15, v65
	v_mov_b32_e32 v16, 0
	v_mov_b32_e32 v17, v65
	v_mov_b32_e32 v18, v65
	v_mov_b32_e32 v19, v65
	v_mov_b32_e32 v20, 0
	v_mov_b32_e32 v21, v65
	v_mov_b32_e32 v22, v65
	v_mov_b32_e32 v23, v65
	v_mov_b32_e32 v24, 0
	v_mov_b32_e32 v25, v65
	v_mov_b32_e32 v26, v65
	v_mov_b32_e32 v27, v65
	v_mov_b32_e32 v28, 0
	v_mov_b32_e32 v29, v65
	v_mov_b32_e32 v30, v65
	v_mov_b32_e32 v31, v65
	v_mov_b32_e32 v32, 0
	v_mov_b32_e32 v33, v65
	v_mov_b32_e32 v34, v65
	v_mov_b32_e32 v35, v65
	v_mov_b32_e32 v36, 0
	v_mov_b32_e32 v37, v65
	v_mov_b32_e32 v38, v65
	v_mov_b32_e32 v39, v65
	v_mov_b32_e32 v44, 0
	v_mov_b32_e32 v45, v65
	v_mov_b32_e32 v46, v65
	v_mov_b32_e32 v47, v65
	v_mov_b32_e32 v48, 0
	v_mov_b32_e32 v49, v65
	v_mov_b32_e32 v50, v65
	v_mov_b32_e32 v51, v65
	v_mov_b32_e32 v52, 0
	v_mov_b32_e32 v53, v65
	v_mov_b32_e32 v54, v65
	v_mov_b32_e32 v55, v65
	v_mov_b32_e32 v56, 0
	v_mov_b32_e32 v57, v65
	v_mov_b32_e32 v58, v65
	v_mov_b32_e32 v59, v65
	v_mov_b32_e32 v60, 0
	v_mov_b32_e32 v61, v65
	v_mov_b32_e32 v62, v65
	v_mov_b32_e32 v63, v65
	v_readfirstlane_b32 s96, v82
	v_readfirstlane_b32 s97, v83
	v_readfirstlane_b32 s88, v84
	v_readfirstlane_b32 s89, v85
	v_readfirstlane_b32 s87, v86
	s_nop 1
	v_subrev_u32_e32 v244, s96, v82
	v_subrev_u32_e32 v245, s88, v84
	v_add_u32_e32 v246, 0x11000, v244
	v_add_u32_e32 v247, 0x11000, v245
	v_add_u32_e32 v248, 0x22000, v244
	v_add_u32_e32 v249, 0x22000, v245
	v_add_u32_e32 v250, 0x33000, v244
	v_add_u32_e32 v251, 0x33000, v245
	s_add_u32 s96, s96, 0x2200080
	s_addc_u32 s97, s97, 0
	s_add_u32 s88, s88, 0xd990080
	s_addc_u32 s89, s89, 0
.LBB0_1217:
	s_add_i32 s41, s3, 0x8000
	s_and_b32 s40, s41, 0x8000
	s_add_i32 s40, s40, 0
	s_add_u32 s86, s40, s87
	s_mov_b32 m0, s86
	s_waitcnt vmcnt(0) lgkmcnt(0)
	s_barrier
	global_load_lds_dwordx4 v244, s[96:97]
	s_add_u32 m0, s86, 0x4000
	s_nop 0
	global_load_lds_dwordx4 v245, s[88:89]
	s_add_u32 m0, s86, 0x1000
	s_nop 0
	global_load_lds_dwordx4 v246, s[96:97]
	s_add_u32 m0, s86, 0x5000
	s_nop 0
	global_load_lds_dwordx4 v247, s[88:89]
	s_add_u32 m0, s86, 0x2000
	s_nop 0
	global_load_lds_dwordx4 v248, s[96:97]
	s_add_u32 m0, s86, 0x6000
	s_nop 0
	global_load_lds_dwordx4 v249, s[88:89]
	s_add_u32 m0, s86, 0x3000
	s_nop 0
	global_load_lds_dwordx4 v250, s[96:97]
	s_add_u32 m0, s86, 0x7000
	s_nop 0
	global_load_lds_dwordx4 v251, s[88:89]
	s_add_u32 s96, s96, 0x80
	s_addc_u32 s97, s97, 0
	s_add_u32 s88, s88, 0x80
	s_addc_u32 s89, s89, 0
	s_and_b32 s3, s3, 0x8000
	s_add_i32 s3, s3, 0
	v_add3_u32 v145, s3, v87, v88
	v_add3_u32 v186, s3, v88, v89
	v_add3_u32 v187, s3, v87, v90
	v_add3_u32 v188, s3, v89, v90
	ds_read_b128 v[112:115], v186
	ds_read_b128 v[104:107], v145 offset:16384
	ds_read_b128 v[108:111], v145 offset:18432
	ds_read_b128 v[116:119], v186 offset:2048
	ds_read_b128 v[120:123], v145 offset:20480
	ds_read_b128 v[124:127], v145 offset:22528
	ds_read_b128 v[128:131], v145 offset:24576
	ds_read_b128 v[132:135], v145 offset:26624
	ds_read_b128 v[136:139], v145 offset:28672
	ds_read_b128 v[140:143], v145 offset:30720
	ds_read_b128 v[154:157], v188
	ds_read_b128 v[146:149], v187 offset:16384
	ds_read_b128 v[150:153], v187 offset:18432
	ds_read_b128 v[158:161], v188 offset:2048
	ds_read_b128 v[162:165], v187 offset:20480
	ds_read_b128 v[166:169], v187 offset:22528
	ds_read_b128 v[170:173], v187 offset:24576
	ds_read_b128 v[174:177], v187 offset:26624
	ds_read_b128 v[178:181], v187 offset:28672
	ds_read_b128 v[182:185], v187 offset:30720
	s_add_u32 s0, s0, 0x80
	s_addc_u32 s1, s1, 0
	s_cmpk_eq_i32 s0, 0x780
	s_mov_b32 s3, s41
	s_waitcnt lgkmcnt(15)
	v_mfma_f32_16x16x32_bf16 v[60:63], v[104:107], v[112:115], v[60:63]
	v_mfma_f32_16x16x32_bf16 v[56:59], v[108:111], v[112:115], v[56:59]
	v_mfma_f32_16x16x32_bf16 v[24:27], v[104:107], v[116:119], v[24:27]
	v_mfma_f32_16x16x32_bf16 v[20:23], v[108:111], v[116:119], v[20:23]
	v_mfma_f32_16x16x32_bf16 v[52:55], v[120:123], v[112:115], v[52:55]
	v_mfma_f32_16x16x32_bf16 v[16:19], v[120:123], v[116:119], v[16:19]
	s_waitcnt lgkmcnt(14)
	v_mfma_f32_16x16x32_bf16 v[48:51], v[124:127], v[112:115], v[48:51]
	v_mfma_f32_16x16x32_bf16 v[12:15], v[124:127], v[116:119], v[12:15]
	s_waitcnt lgkmcnt(13)
	v_mfma_f32_16x16x32_bf16 v[44:47], v[128:131], v[112:115], v[44:47]
	v_mfma_f32_16x16x32_bf16 v[8:11], v[128:131], v[116:119], v[8:11]
	s_waitcnt lgkmcnt(12)
	v_mfma_f32_16x16x32_bf16 v[36:39], v[132:135], v[112:115], v[36:39]
	v_mfma_f32_16x16x32_bf16 v[4:7], v[132:135], v[116:119], v[4:7]
	s_waitcnt lgkmcnt(11)
	v_mfma_f32_16x16x32_bf16 v[32:35], v[136:139], v[112:115], v[32:35]
	v_mfma_f32_16x16x32_bf16 v[0:3], v[136:139], v[116:119], v[0:3]
	s_waitcnt lgkmcnt(10)
	v_mfma_f32_16x16x32_bf16 v[28:31], v[140:143], v[112:115], v[28:31]
	v_mfma_f32_16x16x32_bf16 v[40:43], v[140:143], v[116:119], v[40:43]
	s_waitcnt lgkmcnt(8)
	v_mfma_f32_16x16x32_bf16 v[60:63], v[146:149], v[154:157], v[60:63]
	s_waitcnt lgkmcnt(7)
	v_mfma_f32_16x16x32_bf16 v[56:59], v[150:153], v[154:157], v[56:59]
	s_waitcnt lgkmcnt(6)
	v_mfma_f32_16x16x32_bf16 v[24:27], v[146:149], v[158:161], v[24:27]
	v_mfma_f32_16x16x32_bf16 v[20:23], v[150:153], v[158:161], v[20:23]
	s_waitcnt lgkmcnt(5)
	v_mfma_f32_16x16x32_bf16 v[52:55], v[162:165], v[154:157], v[52:55]
	v_mfma_f32_16x16x32_bf16 v[16:19], v[162:165], v[158:161], v[16:19]
	s_waitcnt lgkmcnt(4)
	v_mfma_f32_16x16x32_bf16 v[48:51], v[166:169], v[154:157], v[48:51]
	v_mfma_f32_16x16x32_bf16 v[12:15], v[166:169], v[158:161], v[12:15]
	s_waitcnt lgkmcnt(3)
	v_mfma_f32_16x16x32_bf16 v[44:47], v[170:173], v[154:157], v[44:47]
	v_mfma_f32_16x16x32_bf16 v[8:11], v[170:173], v[158:161], v[8:11]
	s_waitcnt lgkmcnt(2)
	v_mfma_f32_16x16x32_bf16 v[36:39], v[174:177], v[154:157], v[36:39]
	v_mfma_f32_16x16x32_bf16 v[4:7], v[174:177], v[158:161], v[4:7]
	s_waitcnt lgkmcnt(1)
	v_mfma_f32_16x16x32_bf16 v[32:35], v[178:181], v[154:157], v[32:35]
	v_mfma_f32_16x16x32_bf16 v[0:3], v[178:181], v[158:161], v[0:3]
	s_waitcnt lgkmcnt(0)
	v_mfma_f32_16x16x32_bf16 v[28:31], v[182:185], v[154:157], v[28:31]
	v_mfma_f32_16x16x32_bf16 v[40:43], v[182:185], v[158:161], v[40:43]
	s_cbranch_scc0 .LBB0_1217
	v_add_u32_e32 v64, s40, v87
	v_add_u32_e32 v103, v64, v88
	v_add3_u32 v112, s40, v88, v89
	s_waitcnt vmcnt(0)
	s_barrier
	ds_read_b128 v[82:85], v103 offset:16384
	ds_read_b128 v[104:107], v103 offset:18432
	ds_read_b128 v[108:111], v112
	ds_read_b128 v[112:115], v112 offset:2048
	ds_read_b128 v[116:119], v103 offset:20480
	ds_read_b128 v[120:123], v103 offset:22528
	ds_read_b128 v[124:127], v103 offset:24576
	ds_read_b128 v[128:131], v103 offset:26624
	ds_read_b128 v[132:135], v103 offset:28672
	ds_read_b128 v[136:139], v103 offset:30720
	v_add_u32_e32 v64, v64, v90
	s_waitcnt lgkmcnt(7)
	v_mfma_f32_16x16x32_bf16 v[60:63], v[82:85], v[108:111], v[60:63]
	s_mul_hi_i32 s0, s2, 0x3e0f83e1
	s_lshr_b32 s1, s0, 31
	s_ashr_i32 s56, s0, 4
	v_mfma_f32_16x16x32_bf16 v[56:59], v[104:107], v[108:111], v[56:59]
	s_add_i32 s56, s56, s1
	s_cmp_gt_i32 s39, 11
	s_cselect_b64 s[0:1], -1, 0
	s_waitcnt lgkmcnt(4)
	v_mfma_f32_16x16x32_bf16 v[48:51], v[120:123], v[108:111], v[48:51]
	s_lshl_b32 s53, s2, 7
	s_cmp_lt_i32 s39, 12
	s_mul_i32 s54, s56, 0xffffdf00
	s_waitcnt lgkmcnt(3)
	v_mfma_f32_16x16x32_bf16 v[44:47], v[124:127], v[108:111], v[44:47]
	s_waitcnt lgkmcnt(2)
	v_mfma_f32_16x16x32_bf16 v[36:39], v[128:131], v[108:111], v[36:39]
	s_waitcnt lgkmcnt(1)
	v_mfma_f32_16x16x32_bf16 v[32:35], v[132:135], v[108:111], v[32:35]
	s_waitcnt lgkmcnt(0)
	v_mfma_f32_16x16x32_bf16 v[28:31], v[136:139], v[108:111], v[28:31]
	v_mfma_f32_16x16x32_bf16 v[24:27], v[82:85], v[112:115], v[24:27]
	ds_read_b128 v[82:85], v64 offset:16384
	v_mfma_f32_16x16x32_bf16 v[52:55], v[116:119], v[108:111], v[52:55]
	v_mfma_f32_16x16x32_bf16 v[20:23], v[104:107], v[112:115], v[20:23]
	v_mfma_f32_16x16x32_bf16 v[16:19], v[116:119], v[112:115], v[16:19]
	v_mfma_f32_16x16x32_bf16 v[12:15], v[120:123], v[112:115], v[12:15]
	v_mfma_f32_16x16x32_bf16 v[8:11], v[124:127], v[112:115], v[8:11]
	v_mfma_f32_16x16x32_bf16 v[4:7], v[128:131], v[112:115], v[4:7]
	v_mfma_f32_16x16x32_bf16 v[0:3], v[132:135], v[112:115], v[0:3]
	v_mfma_f32_16x16x32_bf16 v[104:107], v[136:139], v[112:115], v[40:43]
	s_nop 2
	v_add3_u32 v40, s40, v90, v89
	ds_read_b128 v[108:111], v64 offset:18432
	ds_read_b128 v[112:115], v40
	ds_read_b128 v[116:119], v40 offset:2048
	ds_read_b128 v[120:123], v64 offset:20480
	ds_read_b128 v[124:127], v64 offset:22528
	ds_read_b128 v[128:131], v64 offset:24576
	ds_read_b128 v[132:135], v64 offset:26624
	ds_read_b128 v[136:139], v64 offset:28672
	ds_read_b128 v[140:143], v64 offset:30720
	s_waitcnt lgkmcnt(7)
	v_mfma_f32_16x16x32_bf16 v[60:63], v[82:85], v[112:115], v[60:63]
	v_mfma_f32_16x16x32_bf16 v[56:59], v[108:111], v[112:115], v[56:59]
	s_waitcnt lgkmcnt(5)
	v_mfma_f32_16x16x32_bf16 v[52:55], v[120:123], v[112:115], v[52:55]
	s_waitcnt lgkmcnt(4)
	v_mfma_f32_16x16x32_bf16 v[48:51], v[124:127], v[112:115], v[48:51]
	s_waitcnt lgkmcnt(3)
	v_mfma_f32_16x16x32_bf16 v[44:47], v[128:131], v[112:115], v[44:47]
	s_waitcnt lgkmcnt(2)
	v_mfma_f32_16x16x32_bf16 v[40:43], v[132:135], v[112:115], v[36:39]
	s_waitcnt lgkmcnt(1)
	v_mfma_f32_16x16x32_bf16 v[36:39], v[136:139], v[112:115], v[32:35]
	s_waitcnt lgkmcnt(0)
	v_mfma_f32_16x16x32_bf16 v[32:35], v[140:143], v[112:115], v[28:31]
	v_mfma_f32_16x16x32_bf16 v[28:31], v[82:85], v[116:119], v[24:27]
	v_mfma_f32_16x16x32_bf16 v[24:27], v[108:111], v[116:119], v[20:23]
	v_mfma_f32_16x16x32_bf16 v[20:23], v[120:123], v[116:119], v[16:19]
	v_mfma_f32_16x16x32_bf16 v[16:19], v[124:127], v[116:119], v[12:15]
	v_mfma_f32_16x16x32_bf16 v[12:15], v[128:131], v[116:119], v[8:11]
	v_mfma_f32_16x16x32_bf16 v[8:11], v[132:135], v[116:119], v[4:7]
	v_mfma_f32_16x16x32_bf16 v[4:7], v[136:139], v[116:119], v[0:3]
	v_mfma_f32_16x16x32_bf16 v[0:3], v[140:143], v[116:119], v[104:107]
	s_cbranch_scc0 .LBB0_1224
	s_add_i32 s40, s54, s53
	v_add_u32_e32 v64, s40, v70
	v_cmp_lt_i32_e32 vcc, s48, v64
	s_and_saveexec_b64 s[2:3], vcc
	s_cbranch_execz .LBB0_1221
	v_lshl_add_u32 v64, v64, 5, v102
	v_lshlrev_b64 v[108:109], 2, v[64:65]
	v_lshl_add_u64 v[104:105], v[76:77], 0, v[108:109]
	global_load_dwordx4 v[82:85], v[104:105], off
	s_nop 0
	global_load_dwordx4 v[104:107], v[104:105], off offset:16
	v_lshl_add_u64 v[112:113], v[74:75], 0, v[108:109]
	global_load_dwordx4 v[108:111], v[112:113], off
	s_nop 0
	global_load_dwordx4 v[112:115], v[112:113], off offset:16
	s_waitcnt vmcnt(3)
	v_pk_mul_f32 v[116:117], v[54:55], v[84:85]
	v_pk_mul_f32 v[118:119], v[52:53], v[82:83]
	v_pk_mul_f32 v[120:121], v[62:63], v[84:85]
	v_pk_mul_f32 v[122:123], v[60:61], v[82:83]
	s_waitcnt vmcnt(2)
	v_pk_mul_f32 v[124:125], v[50:51], v[106:107]
	v_pk_mul_f32 v[126:127], v[48:49], v[104:105]
	v_pk_mul_f32 v[128:129], v[58:59], v[106:107]
	v_pk_mul_f32 v[130:131], v[56:57], v[104:105]
	v_pk_mul_f32 v[132:133], v[38:39], v[84:85]
	v_pk_mul_f32 v[134:135], v[36:37], v[82:83]
	v_pk_mul_f32 v[84:85], v[46:47], v[84:85]
	v_pk_mul_f32 v[82:83], v[44:45], v[82:83]
	v_pk_mul_f32 v[136:137], v[34:35], v[106:107]
	v_pk_mul_f32 v[138:139], v[32:33], v[104:105]
	v_pk_mul_f32 v[106:107], v[42:43], v[106:107]
	v_pk_mul_f32 v[104:105], v[40:41], v[104:105]
	s_waitcnt vmcnt(1)
	v_pk_fma_f32 v[62:63], v[62:63], v[110:111], v[116:117] neg_lo:[0,0,1] neg_hi:[0,0,1]
	v_pk_fma_f32 v[60:61], v[60:61], v[108:109], v[118:119] neg_lo:[0,0,1] neg_hi:[0,0,1]
	v_pk_fma_f32 v[54:55], v[54:55], v[110:111], v[120:121]
	v_pk_fma_f32 v[52:53], v[52:53], v[108:109], v[122:123]
	s_waitcnt vmcnt(0)
	v_pk_fma_f32 v[58:59], v[58:59], v[114:115], v[124:125] neg_lo:[0,0,1] neg_hi:[0,0,1]
	v_pk_fma_f32 v[56:57], v[56:57], v[112:113], v[126:127] neg_lo:[0,0,1] neg_hi:[0,0,1]
	v_pk_fma_f32 v[50:51], v[50:51], v[114:115], v[128:129]
	v_pk_fma_f32 v[48:49], v[48:49], v[112:113], v[130:131]
	v_pk_fma_f32 v[46:47], v[46:47], v[110:111], v[132:133] neg_lo:[0,0,1] neg_hi:[0,0,1]
	v_pk_fma_f32 v[44:45], v[44:45], v[108:109], v[134:135] neg_lo:[0,0,1] neg_hi:[0,0,1]
	v_pk_fma_f32 v[38:39], v[38:39], v[110:111], v[84:85]
	v_pk_fma_f32 v[36:37], v[36:37], v[108:109], v[82:83]
	v_pk_fma_f32 v[42:43], v[42:43], v[114:115], v[136:137] neg_lo:[0,0,1] neg_hi:[0,0,1]
	v_pk_fma_f32 v[40:41], v[40:41], v[112:113], v[138:139] neg_lo:[0,0,1] neg_hi:[0,0,1]
	v_pk_fma_f32 v[34:35], v[34:35], v[114:115], v[106:107]
	v_pk_fma_f32 v[32:33], v[32:33], v[112:113], v[104:105]

.LBB0_1614:
	s_ashr_i32 s28, s37, 3
	s_add_i32 s28, s39, s28
	s_ashr_i32 s29, s28, 31
	s_lshr_b32 s29, s29, 26
	s_add_i32 s29, s28, s29
	s_ashr_i32 s38, s29, 6
	s_and_b32 s29, s29, 0xffc0
	s_sub_i32 s28, s28, s29
	s_bfe_i32 s29, s28, 0x80000
	s_bfe_u32 s29, s29, 0x3000c
	s_add_i32 s29, s28, s29
	s_bfe_i32 s37, s29, 0x80000
	s_and_b32 s29, s29, 0xf8
	s_sub_i32 s28, s28, s29
	s_lshl_b32 s38, s38, 3
	s_sext_i32_i8 s28, s28
	s_add_i32 s28, s38, s28
	s_ashr_i32 s29, s28, 31
	s_lshr_b32 s29, s29, 26
	s_add_i32 s29, s28, s29
	s_sext_i32_i16 s37, s37
	s_ashr_i32 s38, s29, 6
	s_andn2_b32 s29, s29, 63
	s_ashr_i32 s37, s37, 3
	s_mulk_i32 s38, 0x42
	s_sub_i32 s28, s28, s29
	s_add_i32 s38, s28, s38
	s_mul_i32 s28, s37, 0x22000
	s_add_i32 s38, s38, 2
	s_ashr_i32 s29, s28, 31
	v_readfirstlane_b32 s39, v91
	v_mad_i64_i32 v[0:1], s[40:41], s38, v90, v[64:65]
	s_lshl_b64 s[28:29], s[28:29], 1
	s_mov_b32 m0, s39
	v_readfirstlane_b32 s39, v92
	v_lshl_add_u64 v[2:3], v[66:67], 0, s[28:29]
	s_waitcnt lgkmcnt(0)
	s_barrier
	global_load_lds_dwordx4 v[0:1], off
	s_mov_b32 m0, s39
	v_readfirstlane_b32 s39, v93
	global_load_lds_dwordx4 v[2:3], off
	v_lshl_add_u64 v[4:5], v[0:1], 0, s[4:5]
	s_mov_b32 m0, s39
	v_readfirstlane_b32 s39, v94
	global_load_lds_dwordx4 v[4:5], off
	v_lshl_add_u64 v[4:5], v[2:3], 0, s[4:5]
	s_mov_b32 m0, s39
	v_readfirstlane_b32 s39, v95
	global_load_lds_dwordx4 v[4:5], off
	v_lshl_add_u64 v[4:5], v[0:1], 0, s[6:7]
	s_mov_b32 m0, s39
	v_readfirstlane_b32 s39, v96
	global_load_lds_dwordx4 v[4:5], off
	v_lshl_add_u64 v[4:5], v[2:3], 0, s[6:7]
	s_mov_b32 m0, s39
	v_readfirstlane_b32 s39, v97
	global_load_lds_dwordx4 v[4:5], off
	v_lshl_add_u64 v[0:1], v[0:1], 0, s[8:9]
	s_mov_b32 m0, s39
	v_readfirstlane_b32 s39, v98
	global_load_lds_dwordx4 v[0:1], off
	v_lshl_add_u64 v[0:1], v[2:3], 0, s[8:9]
	s_mov_b32 m0, s39
	v_mov_b32_e32 v36, 0
	global_load_lds_dwordx4 v[0:1], off
	v_mad_i64_i32 v[72:73], s[40:41], s38, v90, v[68:69]
	v_lshl_add_u64 v[74:75], v[70:71], 0, s[28:29]
	s_mov_b64 s[28:29], 0
	s_mov_b32 s39, 0
	v_mov_b32_e32 v37, v36
	v_mov_b32_e32 v38, v36
	v_mov_b32_e32 v39, v36
	v_mov_b32_e32 v0, v36
	v_mov_b32_e32 v1, v36
	v_mov_b32_e32 v2, v36
	v_mov_b32_e32 v3, v36
	v_mov_b32_e32 v4, v36
	v_mov_b32_e32 v5, v36
	v_mov_b32_e32 v6, v36
	v_mov_b32_e32 v7, v36
	v_mov_b32_e32 v8, v36
	v_mov_b32_e32 v9, v36
	v_mov_b32_e32 v10, v36
	v_mov_b32_e32 v11, v36
	v_mov_b32_e32 v12, v36
	v_mov_b32_e32 v13, v36
	v_mov_b32_e32 v14, v36
	v_mov_b32_e32 v15, v36
	v_mov_b32_e32 v16, v36
	v_mov_b32_e32 v17, v36
	v_mov_b32_e32 v18, v36
	v_mov_b32_e32 v19, v36
	v_mov_b32_e32 v20, v36
	v_mov_b32_e32 v21, v36
	v_mov_b32_e32 v22, v36
	v_mov_b32_e32 v23, v36
	v_mov_b32_e32 v24, v36
	v_mov_b32_e32 v25, v36
	v_mov_b32_e32 v26, v36
	v_mov_b32_e32 v27, v36
	v_mov_b32_e32 v28, v36
	v_mov_b32_e32 v29, v36
	v_mov_b32_e32 v30, v36
	v_mov_b32_e32 v31, v36
	v_mov_b32_e32 v32, v36
	v_mov_b32_e32 v33, v36
	v_mov_b32_e32 v34, v36
	v_mov_b32_e32 v35, v36
	v_mov_b32_e32 v40, v36
	v_mov_b32_e32 v41, v36
	v_mov_b32_e32 v42, v36
	v_mov_b32_e32 v43, v36
	v_mov_b32_e32 v44, v36
	v_mov_b32_e32 v45, v36
	v_mov_b32_e32 v46, v36
	v_mov_b32_e32 v47, v36
	v_mov_b32_e32 v48, v36
	v_mov_b32_e32 v49, v36
	v_mov_b32_e32 v50, v36
	v_mov_b32_e32 v51, v36
	v_mov_b32_e32 v52, v36
	v_mov_b32_e32 v53, v36
	v_mov_b32_e32 v54, v36
	v_mov_b32_e32 v55, v36
	v_mov_b32_e32 v56, v36
	v_mov_b32_e32 v57, v36
	v_mov_b32_e32 v58, v36
	v_mov_b32_e32 v59, v36
	v_mov_b32_e32 v60, v36
	v_mov_b32_e32 v61, v36
	v_mov_b32_e32 v62, v36
	v_mov_b32_e32 v63, v36
	v_readfirstlane_b32 s96, v72
	v_readfirstlane_b32 s97, v73
	v_readfirstlane_b32 s88, v74
	v_readfirstlane_b32 s89, v75
	v_readfirstlane_b32 s87, v82
	s_nop 1
	v_subrev_u32_e32 v244, s96, v72
	v_subrev_u32_e32 v245, s88, v74
	v_add_u32_e32 v246, 0x11000, v244
	v_add_u32_e32 v247, 0x11000, v245
	v_add_u32_e32 v248, 0x22000, v244
	v_add_u32_e32 v249, 0x22000, v245
	v_add_u32_e32 v250, 0x33000, v244
	v_add_u32_e32 v251, 0x33000, v245
	s_add_u32 s96, s96, 0x2200080
	s_addc_u32 s97, s97, 0
	s_add_u32 s88, s88, 0xe100080
	s_addc_u32 s89, s89, 0
.LBB0_1615:
	s_add_i32 s41, s39, 0x8000
	s_and_b32 s40, s41, 0x8000
	s_add_i32 s40, s40, 0
	s_add_u32 s86, s40, s87
	s_mov_b32 m0, s86
	s_waitcnt vmcnt(0) lgkmcnt(0)
	s_barrier
	global_load_lds_dwordx4 v244, s[96:97]
	s_add_u32 m0, s86, 0x4000
	s_nop 0
	global_load_lds_dwordx4 v245, s[88:89]
	s_add_u32 m0, s86, 0x1000
	s_nop 0
	global_load_lds_dwordx4 v246, s[96:97]
	s_add_u32 m0, s86, 0x5000
	s_nop 0
	global_load_lds_dwordx4 v247, s[88:89]
	s_add_u32 m0, s86, 0x2000
	s_nop 0
	global_load_lds_dwordx4 v248, s[96:97]
	s_add_u32 m0, s86, 0x6000
	s_nop 0
	global_load_lds_dwordx4 v249, s[88:89]
	s_add_u32 m0, s86, 0x3000
	s_nop 0
	global_load_lds_dwordx4 v250, s[96:97]
	s_add_u32 m0, s86, 0x7000
	s_nop 0
	global_load_lds_dwordx4 v251, s[88:89]
	s_add_u32 s96, s96, 0x80
	s_addc_u32 s97, s97, 0
	s_add_u32 s88, s88, 0x80
	s_addc_u32 s89, s89, 0
	s_and_b32 s39, s39, 0x8000
	s_add_i32 s39, s39, 0
	v_add3_u32 v145, s39, v84, v85
	v_add3_u32 v178, s39, v85, v86
	v_add3_u32 v179, s39, v84, v87
	v_add3_u32 v180, s39, v86, v87
	ds_read_b128 v[104:107], v178
	ds_read_b128 v[76:79], v145 offset:16384
	ds_read_b128 v[100:103], v145 offset:18432
	ds_read_b128 v[108:111], v178 offset:2048
	ds_read_b128 v[112:115], v145 offset:20480
	ds_read_b128 v[116:119], v145 offset:22528
	ds_read_b128 v[120:123], v145 offset:24576
	ds_read_b128 v[124:127], v145 offset:26624
	ds_read_b128 v[128:131], v145 offset:28672
	ds_read_b128 v[132:135], v145 offset:30720
	ds_read_b128 v[146:149], v180
	ds_read_b128 v[136:139], v179 offset:16384
	ds_read_b128 v[140:143], v179 offset:18432
	ds_read_b128 v[150:153], v180 offset:2048
	ds_read_b128 v[154:157], v179 offset:20480
	ds_read_b128 v[158:161], v179 offset:22528
	ds_read_b128 v[162:165], v179 offset:24576
	ds_read_b128 v[166:169], v179 offset:26624
	ds_read_b128 v[170:173], v179 offset:28672
	ds_read_b128 v[174:177], v179 offset:30720
	s_add_u32 s28, s28, 0x80
	s_addc_u32 s29, s29, 0
	s_cmpk_eq_i32 s28, 0x780
	s_mov_b32 s39, s41
	s_waitcnt lgkmcnt(15)
	v_mfma_f32_16x16x32_bf16 v[60:63], v[76:79], v[104:107], v[60:63]
	v_mfma_f32_16x16x32_bf16 v[56:59], v[100:103], v[104:107], v[56:59]
	v_mfma_f32_16x16x32_bf16 v[24:27], v[76:79], v[108:111], v[24:27]
	v_mfma_f32_16x16x32_bf16 v[20:23], v[100:103], v[108:111], v[20:23]
	v_mfma_f32_16x16x32_bf16 v[52:55], v[112:115], v[104:107], v[52:55]
	v_mfma_f32_16x16x32_bf16 v[16:19], v[112:115], v[108:111], v[16:19]
	s_waitcnt lgkmcnt(14)
	v_mfma_f32_16x16x32_bf16 v[48:51], v[116:119], v[104:107], v[48:51]
	v_mfma_f32_16x16x32_bf16 v[12:15], v[116:119], v[108:111], v[12:15]
	s_waitcnt lgkmcnt(13)
	v_mfma_f32_16x16x32_bf16 v[44:47], v[120:123], v[104:107], v[44:47]
	v_mfma_f32_16x16x32_bf16 v[8:11], v[120:123], v[108:111], v[8:11]
	s_waitcnt lgkmcnt(12)
	v_mfma_f32_16x16x32_bf16 v[40:43], v[124:127], v[104:107], v[40:43]
	v_mfma_f32_16x16x32_bf16 v[4:7], v[124:127], v[108:111], v[4:7]
	s_waitcnt lgkmcnt(11)
	v_mfma_f32_16x16x32_bf16 v[32:35], v[128:131], v[104:107], v[32:35]
	v_mfma_f32_16x16x32_bf16 v[0:3], v[128:131], v[108:111], v[0:3]
	s_waitcnt lgkmcnt(10)
	v_mfma_f32_16x16x32_bf16 v[28:31], v[132:135], v[104:107], v[28:31]
	v_mfma_f32_16x16x32_bf16 v[36:39], v[132:135], v[108:111], v[36:39]
	s_waitcnt lgkmcnt(8)
	v_mfma_f32_16x16x32_bf16 v[60:63], v[136:139], v[146:149], v[60:63]
	s_waitcnt lgkmcnt(7)
	v_mfma_f32_16x16x32_bf16 v[56:59], v[140:143], v[146:149], v[56:59]
	s_waitcnt lgkmcnt(6)
	v_mfma_f32_16x16x32_bf16 v[24:27], v[136:139], v[150:153], v[24:27]
	v_mfma_f32_16x16x32_bf16 v[20:23], v[140:143], v[150:153], v[20:23]
	s_waitcnt lgkmcnt(5)
	v_mfma_f32_16x16x32_bf16 v[52:55], v[154:157], v[146:149], v[52:55]
	v_mfma_f32_16x16x32_bf16 v[16:19], v[154:157], v[150:153], v[16:19]
	s_waitcnt lgkmcnt(4)
	v_mfma_f32_16x16x32_bf16 v[48:51], v[158:161], v[146:149], v[48:51]
	v_mfma_f32_16x16x32_bf16 v[12:15], v[158:161], v[150:153], v[12:15]
	s_waitcnt lgkmcnt(3)
	v_mfma_f32_16x16x32_bf16 v[44:47], v[162:165], v[146:149], v[44:47]
	v_mfma_f32_16x16x32_bf16 v[8:11], v[162:165], v[150:153], v[8:11]
	s_waitcnt lgkmcnt(2)
	v_mfma_f32_16x16x32_bf16 v[40:43], v[166:169], v[146:149], v[40:43]
	v_mfma_f32_16x16x32_bf16 v[4:7], v[166:169], v[150:153], v[4:7]
	s_waitcnt lgkmcnt(1)
	v_mfma_f32_16x16x32_bf16 v[32:35], v[170:173], v[146:149], v[32:35]
	v_mfma_f32_16x16x32_bf16 v[0:3], v[170:173], v[150:153], v[0:3]
	s_waitcnt lgkmcnt(0)
	v_mfma_f32_16x16x32_bf16 v[28:31], v[174:177], v[146:149], v[28:31]
	v_mfma_f32_16x16x32_bf16 v[36:39], v[174:177], v[150:153], v[36:39]
	s_cbranch_scc0 .LBB0_1615
	v_add_u32_e32 v80, s40, v84
	v_add_u32_e32 v81, v80, v85
	s_waitcnt vmcnt(0)
	s_barrier
	ds_read_b128 v[72:75], v81 offset:16384
	v_add3_u32 v99, s40, v85, v86
	ds_read_b128 v[76:79], v81 offset:18432
	ds_read_b128 v[100:103], v99
	ds_read_b128 v[104:107], v99 offset:2048
	ds_read_b128 v[108:111], v81 offset:20480
	ds_read_b128 v[112:115], v81 offset:22528
	ds_read_b128 v[116:119], v81 offset:24576
	ds_read_b128 v[120:123], v81 offset:26624
	ds_read_b128 v[124:127], v81 offset:28672
	ds_read_b128 v[128:131], v81 offset:30720
	v_add_u32_e32 v80, v80, v87
	s_waitcnt lgkmcnt(7)
	v_mfma_f32_16x16x32_bf16 v[60:63], v[72:75], v[100:103], v[60:63]
	s_lshl_b32 s38, s38, 7
	v_mfma_f32_16x16x32_bf16 v[56:59], v[76:79], v[100:103], v[56:59]
	s_waitcnt lgkmcnt(4)
	v_mfma_f32_16x16x32_bf16 v[48:51], v[112:115], v[100:103], v[48:51]
	s_waitcnt lgkmcnt(3)
	v_mfma_f32_16x16x32_bf16 v[44:47], v[116:119], v[100:103], v[44:47]
	s_waitcnt lgkmcnt(2)
	v_mfma_f32_16x16x32_bf16 v[40:43], v[120:123], v[100:103], v[40:43]
	s_waitcnt lgkmcnt(1)
	v_mfma_f32_16x16x32_bf16 v[32:35], v[124:127], v[100:103], v[32:35]
	s_waitcnt lgkmcnt(0)
	v_mfma_f32_16x16x32_bf16 v[28:31], v[128:131], v[100:103], v[28:31]
	v_mfma_f32_16x16x32_bf16 v[24:27], v[72:75], v[104:107], v[24:27]
	ds_read_b128 v[72:75], v80 offset:16384
	v_mfma_f32_16x16x32_bf16 v[52:55], v[108:111], v[100:103], v[52:55]
	v_mfma_f32_16x16x32_bf16 v[20:23], v[76:79], v[104:107], v[20:23]
	v_mfma_f32_16x16x32_bf16 v[16:19], v[108:111], v[104:107], v[16:19]
	v_mfma_f32_16x16x32_bf16 v[12:15], v[112:115], v[104:107], v[12:15]
	v_mfma_f32_16x16x32_bf16 v[8:11], v[116:119], v[104:107], v[8:11]
	v_mfma_f32_16x16x32_bf16 v[4:7], v[120:123], v[104:107], v[4:7]
	v_mfma_f32_16x16x32_bf16 v[0:3], v[124:127], v[104:107], v[0:3]
	v_mfma_f32_16x16x32_bf16 v[100:103], v[128:131], v[104:107], v[36:39]
	s_nop 2
	v_add3_u32 v36, s40, v87, v86
	ds_read_b128 v[76:79], v80 offset:18432
	ds_read_b128 v[104:107], v36
	ds_read_b128 v[108:111], v36 offset:2048
	ds_read_b128 v[128:131], v80 offset:28672
	ds_read_b128 v[132:135], v80 offset:30720
	ds_read_b128 v[112:115], v80 offset:20480
	ds_read_b128 v[116:119], v80 offset:22528
	ds_read_b128 v[120:123], v80 offset:24576
	ds_read_b128 v[124:127], v80 offset:26624
	s_waitcnt lgkmcnt(7)
	v_mfma_f32_16x16x32_bf16 v[60:63], v[72:75], v[104:107], v[60:63]
	s_waitcnt lgkmcnt(5)
	v_mfma_f32_16x16x32_bf16 v[36:39], v[128:131], v[104:107], v[32:35]
	s_waitcnt lgkmcnt(4)
	v_mfma_f32_16x16x32_bf16 v[32:35], v[132:135], v[104:107], v[28:31]
	v_mfma_f32_16x16x32_bf16 v[28:31], v[72:75], v[108:111], v[24:27]
	v_add_u32_e32 v72, s38, v83
	v_mul_hi_i32 v73, v72, s31
	v_mfma_f32_16x16x32_bf16 v[24:27], v[76:79], v[108:111], v[20:23]
	s_waitcnt lgkmcnt(3)
	v_mfma_f32_16x16x32_bf16 v[20:23], v[112:115], v[108:111], v[16:19]
	s_waitcnt lgkmcnt(2)
	v_mfma_f32_16x16x32_bf16 v[16:19], v[116:119], v[108:111], v[12:15]
	s_waitcnt lgkmcnt(1)
	v_mfma_f32_16x16x32_bf16 v[12:15], v[120:123], v[108:111], v[8:11]
	s_waitcnt lgkmcnt(0)
	v_mfma_f32_16x16x32_bf16 v[8:11], v[124:127], v[108:111], v[4:7]
	s_nop 2
	v_lshrrev_b32_e32 v4, 31, v73
	v_ashrrev_i32_e32 v5, 11, v73
	v_mfma_f32_16x16x32_bf16 v[56:59], v[76:79], v[104:107], v[56:59]
	v_add_u32_e32 v73, v5, v4
	v_mad_i32_i24 v78, v73, s33, v72
	v_lshlrev_b32_e32 v75, 13, v73
	v_mfma_f32_16x16x32_bf16 v[52:55], v[112:115], v[104:107], v[52:55]
	v_cmp_lt_i32_e32 vcc, s34, v78
	v_add3_u32 v74, v75, v78, s35
	v_mfma_f32_16x16x32_bf16 v[48:51], v[116:119], v[104:107], v[48:51]
	v_mfma_f32_16x16x32_bf16 v[44:47], v[120:123], v[104:107], v[44:47]
	v_mfma_f32_16x16x32_bf16 v[40:43], v[124:127], v[104:107], v[40:43]
	v_mfma_f32_16x16x32_bf16 v[4:7], v[128:131], v[108:111], v[0:3]
	v_mfma_f32_16x16x32_bf16 v[0:3], v[132:135], v[108:111], v[100:103]
	s_and_saveexec_b64 s[28:29], vcc
	s_xor_b64 s[28:29], exec, s[28:29]
	v_add3_u32 v72, v75, v78, s35
	s_or_saveexec_b64 s[28:29], s[28:29]
	v_mov_b64_e32 v[76:77], s[92:93]
	v_lshl_add_u32 v75, v73, 8, v78
	s_xor_b64 exec, exec, s[28:29]
	v_lshl_add_u32 v72, v73, 8, v78
	v_mov_b64_e32 v[76:77], s[2:3]
	s_or_b64 exec, exec, s[28:29]
	s_and_saveexec_b64 s[28:29], vcc
	s_xor_b64 s[28:29], exec, s[28:29]
	s_cbranch_execz .LBB0_1622
	v_add_u32_e32 v73, 3, v73
	v_mul_hi_i32_i24_e32 v79, 0x6000, v73
	v_mul_i32_i24_e32 v78, 0x6000, v73
	s_or_saveexec_b64 s[28:29], s[28:29]
	v_mov_b64_e32 v[80:81], s[92:93]
	s_xor_b64 exec, exec, s[28:29]
	s_cbranch_execnz .LBB0_1623
	s_branch .LBB0_1624

.LBB0_1758:
	s_ashr_i32 s26, s31, 3
	s_add_i32 s26, s34, s26
	s_ashr_i32 s27, s26, 31
	s_lshr_b32 s27, s27, 24
	s_add_i32 s27, s26, s27
	s_ashr_i32 s33, s27, 8
	s_and_b32 s27, s27, 0xff00
	s_sub_i32 s26, s26, s27
	s_sext_i32_i16 s27, s26
	s_bfe_u32 s27, s27, 0x3001c
	s_add_i32 s27, s26, s27
	s_sext_i32_i16 s31, s27
	s_and_b32 s27, s27, 0xfff8
	s_sub_i32 s26, s26, s27
	s_lshl_b32 s33, s33, 3
	s_sext_i32_i16 s26, s26
	s_add_i32 s26, s33, s26
	s_ashr_i32 s27, s26, 31
	s_lshr_b32 s27, s27, 26
	s_add_i32 s27, s26, s27
	s_ashr_i32 s33, s27, 6
	s_andn2_b32 s27, s27, 63
	s_mulk_i32 s33, 0x42
	s_sub_i32 s26, s26, s27
	s_add_i32 s33, s26, s33
	s_ashr_i32 s31, s31, 3
	s_add_i32 s33, s33, 2
	s_mul_i32 s26, s31, 0x22000
	v_mad_i64_i32 v[0:1], s[34:35], s33, v85, v[66:67]
	s_ashr_i32 s27, s26, 31
	v_readfirstlane_b32 s34, v86
	s_lshl_b64 s[26:27], s[26:27], 1
	s_mov_b32 m0, s34
	v_readfirstlane_b32 s34, v87
	v_lshl_add_u64 v[2:3], v[68:69], 0, s[26:27]
	s_waitcnt lgkmcnt(0)
	s_barrier
	global_load_lds_dwordx4 v[0:1], off
	s_mov_b32 m0, s34
	v_readfirstlane_b32 s34, v88
	global_load_lds_dwordx4 v[2:3], off
	v_lshl_add_u64 v[4:5], v[0:1], 0, s[4:5]
	s_mov_b32 m0, s34
	v_readfirstlane_b32 s34, v89
	global_load_lds_dwordx4 v[4:5], off
	v_lshl_add_u64 v[4:5], v[2:3], 0, s[4:5]
	s_mov_b32 m0, s34
	v_readfirstlane_b32 s34, v90
	global_load_lds_dwordx4 v[4:5], off
	v_lshl_add_u64 v[4:5], v[0:1], 0, s[6:7]
	s_mov_b32 m0, s34
	v_readfirstlane_b32 s34, v91
	global_load_lds_dwordx4 v[4:5], off
	v_lshl_add_u64 v[4:5], v[2:3], 0, s[6:7]
	s_mov_b32 m0, s34
	v_readfirstlane_b32 s34, v92
	global_load_lds_dwordx4 v[4:5], off
	v_lshl_add_u64 v[0:1], v[0:1], 0, s[8:9]
	s_mov_b32 m0, s34
	v_readfirstlane_b32 s34, v93
	global_load_lds_dwordx4 v[0:1], off
	v_lshl_add_u64 v[0:1], v[2:3], 0, s[8:9]
	s_mov_b32 m0, s34
	v_mad_i64_i32 v[74:75], s[34:35], s33, v85, v[70:71]
	global_load_lds_dwordx4 v[0:1], off
	v_mov_b32_e32 v16, 0
	v_lshl_add_u64 v[76:77], v[72:73], 0, s[26:27]
	s_mov_b64 s[26:27], 0
	s_mov_b32 s34, 0
	v_mov_b32_e32 v17, v16
	v_mov_b32_e32 v18, v16
	v_mov_b32_e32 v19, v16
	v_mov_b32_e32 v0, v16
	v_mov_b32_e32 v1, v16
	v_mov_b32_e32 v2, v16
	v_mov_b32_e32 v3, v16
	v_mov_b32_e32 v4, v16
	v_mov_b32_e32 v5, v16
	v_mov_b32_e32 v6, v16
	v_mov_b32_e32 v7, v16
	v_mov_b32_e32 v8, v16
	v_mov_b32_e32 v9, v16
	v_mov_b32_e32 v10, v16
	v_mov_b32_e32 v11, v16
	v_mov_b32_e32 v12, v16
	v_mov_b32_e32 v13, v16
	v_mov_b32_e32 v14, v16
	v_mov_b32_e32 v15, v16
	v_mov_b32_e32 v20, v16
	v_mov_b32_e32 v21, v16
	v_mov_b32_e32 v22, v16
	v_mov_b32_e32 v23, v16
	v_mov_b32_e32 v24, v16
	v_mov_b32_e32 v25, v16
	v_mov_b32_e32 v26, v16
	v_mov_b32_e32 v27, v16
	v_mov_b32_e32 v28, v16
	v_mov_b32_e32 v29, v16
	v_mov_b32_e32 v30, v16
	v_mov_b32_e32 v31, v16
	v_mov_b32_e32 v32, v16
	v_mov_b32_e32 v33, v16
	v_mov_b32_e32 v34, v16
	v_mov_b32_e32 v35, v16
	v_mov_b32_e32 v36, v16
	v_mov_b32_e32 v37, v16
	v_mov_b32_e32 v38, v16
	v_mov_b32_e32 v39, v16
	v_mov_b32_e32 v40, v16
	v_mov_b32_e32 v41, v16
	v_mov_b32_e32 v42, v16
	v_mov_b32_e32 v43, v16
	v_mov_b32_e32 v44, v16
	v_mov_b32_e32 v45, v16
	v_mov_b32_e32 v46, v16
	v_mov_b32_e32 v47, v16
	v_mov_b32_e32 v48, v16
	v_mov_b32_e32 v49, v16
	v_mov_b32_e32 v50, v16
	v_mov_b32_e32 v51, v16
	v_mov_b32_e32 v52, v16
	v_mov_b32_e32 v53, v16
	v_mov_b32_e32 v54, v16
	v_mov_b32_e32 v55, v16
	v_mov_b32_e32 v56, v16
	v_mov_b32_e32 v57, v16
	v_mov_b32_e32 v58, v16
	v_mov_b32_e32 v59, v16
	v_mov_b32_e32 v60, v16
	v_mov_b32_e32 v61, v16
	v_mov_b32_e32 v62, v16
	v_mov_b32_e32 v63, v16
	v_readfirstlane_b32 s96, v74
	v_readfirstlane_b32 s97, v75
	v_readfirstlane_b32 s88, v76
	v_readfirstlane_b32 s89, v77
	v_readfirstlane_b32 s87, v78
	s_nop 1
	v_subrev_u32_e32 v244, s96, v74
	v_subrev_u32_e32 v245, s88, v76
	v_add_u32_e32 v246, 0x11000, v244
	v_add_u32_e32 v247, 0x11000, v245
	v_add_u32_e32 v248, 0x22000, v244
	v_add_u32_e32 v249, 0x22000, v245
	v_add_u32_e32 v250, 0x33000, v244
	v_add_u32_e32 v251, 0x33000, v245
	s_add_u32 s96, s96, 0x2200080
	s_addc_u32 s97, s97, 0
	s_add_u32 s88, s88, 0xe320080
	s_addc_u32 s89, s89, 0
.LBB0_1759:
	s_add_i32 s36, s34, 0x8000
	s_and_b32 s35, s36, 0x8000
	s_add_i32 s35, s35, 0
	s_add_u32 s86, s35, s87
	s_mov_b32 m0, s86
	s_waitcnt vmcnt(0) lgkmcnt(0)
	s_barrier
	global_load_lds_dwordx4 v244, s[96:97]
	s_add_u32 m0, s86, 0x4000
	s_nop 0
	global_load_lds_dwordx4 v245, s[88:89]
	s_add_u32 m0, s86, 0x1000
	s_nop 0
	global_load_lds_dwordx4 v246, s[96:97]
	s_add_u32 m0, s86, 0x5000
	s_nop 0
	global_load_lds_dwordx4 v247, s[88:89]
	s_add_u32 m0, s86, 0x2000
	s_nop 0
	global_load_lds_dwordx4 v248, s[96:97]
	s_add_u32 m0, s86, 0x6000
	s_nop 0
	global_load_lds_dwordx4 v249, s[88:89]
	s_add_u32 m0, s86, 0x3000
	s_nop 0
	global_load_lds_dwordx4 v250, s[96:97]
	s_add_u32 m0, s86, 0x7000
	s_nop 0
	global_load_lds_dwordx4 v251, s[88:89]
	s_add_u32 s96, s96, 0x80
	s_addc_u32 s97, s97, 0
	s_add_u32 s88, s88, 0x80
	s_addc_u32 s89, s89, 0
	s_and_b32 s34, s34, 0x8000
	s_add_i32 s34, s34, 0
	v_add3_u32 v143, s34, v80, v81
	v_add3_u32 v145, s34, v81, v82
	v_add3_u32 v206, s34, v80, v83
	v_add3_u32 v207, s34, v82, v83
	ds_read_b128 v[102:105], v145
	ds_read_b128 v[94:97], v143 offset:16384
	ds_read_b128 v[98:101], v143 offset:18432
	ds_read_b128 v[106:109], v145 offset:2048
	ds_read_b128 v[110:113], v143 offset:20480
	ds_read_b128 v[114:117], v143 offset:22528
	ds_read_b128 v[118:121], v143 offset:24576
	ds_read_b128 v[122:125], v143 offset:26624
	ds_read_b128 v[126:129], v143 offset:28672
	ds_read_b128 v[130:133], v143 offset:30720
	ds_read_b128 v[174:177], v207
	ds_read_b128 v[166:169], v206 offset:16384
	ds_read_b128 v[170:173], v206 offset:18432
	ds_read_b128 v[178:181], v207 offset:2048
	ds_read_b128 v[182:185], v206 offset:20480
	ds_read_b128 v[186:189], v206 offset:22528
	ds_read_b128 v[190:193], v206 offset:24576
	ds_read_b128 v[194:197], v206 offset:26624
	ds_read_b128 v[198:201], v206 offset:28672
	ds_read_b128 v[202:205], v206 offset:30720
	s_add_u32 s26, s26, 0x80
	s_addc_u32 s27, s27, 0
	s_cmpk_eq_i32 s26, 0x780
	s_mov_b32 s34, s36
	s_waitcnt lgkmcnt(15)
	v_mfma_f32_16x16x32_bf16 v[60:63], v[94:97], v[102:105], v[60:63]
	v_mfma_f32_16x16x32_bf16 v[56:59], v[98:101], v[102:105], v[56:59]
	v_mfma_f32_16x16x32_bf16 v[28:31], v[94:97], v[106:109], v[28:31]
	v_mfma_f32_16x16x32_bf16 v[24:27], v[98:101], v[106:109], v[24:27]
	v_mfma_f32_16x16x32_bf16 v[52:55], v[110:113], v[102:105], v[52:55]
	v_mfma_f32_16x16x32_bf16 v[20:23], v[110:113], v[106:109], v[20:23]
	s_waitcnt lgkmcnt(14)
	v_mfma_f32_16x16x32_bf16 v[48:51], v[114:117], v[102:105], v[48:51]
	v_mfma_f32_16x16x32_bf16 v[12:15], v[114:117], v[106:109], v[12:15]
	s_waitcnt lgkmcnt(13)
	v_mfma_f32_16x16x32_bf16 v[44:47], v[118:121], v[102:105], v[44:47]
	v_mfma_f32_16x16x32_bf16 v[8:11], v[118:121], v[106:109], v[8:11]
	s_waitcnt lgkmcnt(12)
	v_mfma_f32_16x16x32_bf16 v[40:43], v[122:125], v[102:105], v[40:43]
	v_mfma_f32_16x16x32_bf16 v[4:7], v[122:125], v[106:109], v[4:7]
	s_waitcnt lgkmcnt(11)
	v_mfma_f32_16x16x32_bf16 v[36:39], v[126:129], v[102:105], v[36:39]
	v_mfma_f32_16x16x32_bf16 v[0:3], v[126:129], v[106:109], v[0:3]
	s_waitcnt lgkmcnt(10)
	v_mfma_f32_16x16x32_bf16 v[32:35], v[130:133], v[102:105], v[32:35]
	v_mfma_f32_16x16x32_bf16 v[16:19], v[130:133], v[106:109], v[16:19]
	s_waitcnt lgkmcnt(8)
	v_mfma_f32_16x16x32_bf16 v[60:63], v[166:169], v[174:177], v[60:63]
	s_waitcnt lgkmcnt(7)
	v_mfma_f32_16x16x32_bf16 v[56:59], v[170:173], v[174:177], v[56:59]
	s_waitcnt lgkmcnt(6)
	v_mfma_f32_16x16x32_bf16 v[28:31], v[166:169], v[178:181], v[28:31]
	v_mfma_f32_16x16x32_bf16 v[24:27], v[170:173], v[178:181], v[24:27]
	s_waitcnt lgkmcnt(5)
	v_mfma_f32_16x16x32_bf16 v[52:55], v[182:185], v[174:177], v[52:55]
	v_mfma_f32_16x16x32_bf16 v[20:23], v[182:185], v[178:181], v[20:23]
	s_waitcnt lgkmcnt(4)
	v_mfma_f32_16x16x32_bf16 v[48:51], v[186:189], v[174:177], v[48:51]
	v_mfma_f32_16x16x32_bf16 v[12:15], v[186:189], v[178:181], v[12:15]
	s_waitcnt lgkmcnt(3)
	v_mfma_f32_16x16x32_bf16 v[44:47], v[190:193], v[174:177], v[44:47]
	v_mfma_f32_16x16x32_bf16 v[8:11], v[190:193], v[178:181], v[8:11]
	s_waitcnt lgkmcnt(2)
	v_mfma_f32_16x16x32_bf16 v[40:43], v[194:197], v[174:177], v[40:43]
	v_mfma_f32_16x16x32_bf16 v[4:7], v[194:197], v[178:181], v[4:7]
	s_waitcnt lgkmcnt(1)
	v_mfma_f32_16x16x32_bf16 v[36:39], v[198:201], v[174:177], v[36:39]
	v_mfma_f32_16x16x32_bf16 v[0:3], v[198:201], v[178:181], v[0:3]
	s_waitcnt lgkmcnt(0)
	v_mfma_f32_16x16x32_bf16 v[32:35], v[202:205], v[174:177], v[32:35]
	v_mfma_f32_16x16x32_bf16 v[16:19], v[202:205], v[178:181], v[16:19]
	s_cbranch_scc0 .LBB0_1759
	v_add_u32_e32 v138, s35, v80
	v_add_u32_e32 v126, v138, v81
	s_waitcnt vmcnt(0)
	s_barrier
	ds_read_b128 v[74:77], v126 offset:16384
	v_add3_u32 v102, s35, v81, v82
	ds_read_b128 v[94:97], v102
	ds_read_b128 v[98:101], v126 offset:18432
	ds_read_b128 v[102:105], v102 offset:2048
	ds_read_b128 v[106:109], v126 offset:20480
	ds_read_b128 v[110:113], v126 offset:22528
	ds_read_b128 v[114:117], v126 offset:24576
	ds_read_b128 v[118:121], v126 offset:26624
	v_add3_u32 v134, s35, v83, v82
	v_add_u32_e32 v142, v138, v83
	ds_read_b128 v[122:125], v126 offset:28672
	ds_read_b128 v[126:129], v126 offset:30720
	ds_read_b128 v[130:133], v134
	ds_read_b128 v[134:137], v134 offset:2048
	ds_read_b128 v[138:141], v142 offset:16384
	ds_read_b128 v[146:149], v142 offset:18432
	s_waitcnt lgkmcnt(11)
	v_mfma_f32_16x16x32_bf16 v[56:59], v[98:101], v[94:97], v[56:59]
	s_lshl_b32 s33, s33, 7
	s_lshl_b32 s26, s31, 7
	s_ashr_i32 s27, s26, 31
	v_mfma_f32_16x16x32_bf16 v[60:63], v[74:77], v[94:97], v[60:63]
	s_lshl_b64 s[26:27], s[26:27], 1
	s_add_i32 s30, s30, s28
	s_cmpk_gt_i32 s30, 0xfff
	s_waitcnt lgkmcnt(0)
	v_mfma_f32_16x16x32_bf16 v[56:59], v[146:149], v[130:133], v[56:59]
	v_mfma_f32_16x16x32_bf16 v[48:51], v[110:113], v[94:97], v[48:51]
	v_mfma_f32_16x16x32_bf16 v[52:55], v[106:109], v[94:97], v[52:55]
	s_nop 5
	v_max_f32_e32 v56, v56, v56
	v_max_f32_e32 v57, v57, v57
	v_max_f32_e32 v56, 0, v56
	v_mfma_f32_16x16x32_bf16 v[44:47], v[114:117], v[94:97], v[44:47]
	v_max_f32_e32 v57, 0, v57
	v_max_f32_e32 v59, v59, v59
	v_max_f32_e32 v59, 0, v59
	v_mfma_f32_16x16x32_bf16 v[40:43], v[118:121], v[94:97], v[40:43]
	v_mfma_f32_16x16x32_bf16 v[36:39], v[122:125], v[94:97], v[36:39]
	v_mfma_f32_16x16x32_bf16 v[32:35], v[126:129], v[94:97], v[32:35]
	ds_read_b128 v[94:97], v142 offset:20480
	ds_read_b128 v[150:153], v142 offset:22528
	ds_read_b128 v[154:157], v142 offset:24576
	ds_read_b128 v[158:161], v142 offset:26624
	v_mfma_f32_16x16x32_bf16 v[60:63], v[138:141], v[130:133], v[60:63]
	s_waitcnt lgkmcnt(2)
	v_mfma_f32_16x16x32_bf16 v[48:51], v[150:153], v[130:133], v[48:51]
	v_mfma_f32_16x16x32_bf16 v[20:23], v[106:109], v[102:105], v[20:23]
	v_mul_f32_e64 v106, v56, v56
	v_mul_f32_e64 v107, v57, v57
	v_max_f32_e32 v57, v58, v58
	s_nop 1
	v_max_f32_e32 v60, v60, v60
	v_mfma_f32_16x16x32_bf16 v[24:27], v[98:101], v[102:105], v[24:27]
	v_add_u32_e32 v100, s33, v79
	v_mov_b64_e32 v[98:99], s[0:1]
	v_max_f32_e32 v61, v61, v61
	v_max_f32_e32 v56, v62, v62
	v_max_f32_e32 v58, 0, v57
	v_max_f32_e32 v57, v63, v63
	v_mad_i64_i32 v[100:101], s[34:35], v100, s29, v[98:99]
	v_max_f32_e32 v60, 0, v60
	v_max_f32_e32 v61, 0, v61
	v_max_f32_e32 v56, 0, v56
	v_max_f32_e32 v57, 0, v57
	v_mfma_f32_16x16x32_bf16 v[52:55], v[94:97], v[130:133], v[52:55]
	v_lshl_add_u64 v[100:101], v[100:101], 0, s[26:27]
	v_pk_mul_f32 v[60:61], v[60:61], v[60:61]
	v_pk_mul_f32 v[62:63], v[56:57], v[56:57]
	v_mfma_f32_16x16x32_bf16 v[28:31], v[74:77], v[102:105], v[28:31]
	v_max_f32_e32 v48, v48, v48
	v_max_f32_e32 v49, v49, v49
	ds_read_b128 v[74:77], v142 offset:28672
	ds_read_b128 v[162:165], v142 offset:30720
	v_mfma_f32_16x16x32_bf16 v[12:15], v[110:113], v[102:105], v[12:15]
	v_lshl_add_u64 v[100:101], v[100:101], 0, v[64:65]
	v_cvt_pk_bf16_f32 v56, v60, v61
	v_cvt_pk_bf16_f32 v57, v62, v63
	v_mfma_f32_16x16x32_bf16 v[8:11], v[114:117], v[102:105], v[8:11]
	v_max_f32_e32 v48, 0, v48
	v_max_f32_e32 v49, 0, v49
	v_max_f32_e32 v52, v52, v52
	v_mfma_f32_16x16x32_bf16 v[4:7], v[118:121], v[102:105], v[4:7]
	v_max_f32_e32 v53, v53, v53
	v_max_f32_e32 v51, v51, v51
	v_max_f32_e32 v52, 0, v52
	v_mfma_f32_16x16x32_bf16 v[0:3], v[122:125], v[102:105], v[0:3]
	v_max_f32_e32 v53, 0, v53
	v_max_f32_e32 v51, 0, v51
	v_pk_mul_f32 v[52:53], v[52:53], v[52:53]
	v_mfma_f32_16x16x32_bf16 v[16:19], v[126:129], v[102:105], v[16:19]
	v_mul_f32_e64 v102, v58, v58
	v_mul_f32_e64 v103, v59, v59
	v_cvt_pk_bf16_f32 v58, v106, v107
	v_cvt_pk_bf16_f32 v59, v102, v103
	s_waitcnt lgkmcnt(2)
	v_mfma_f32_16x16x32_bf16 v[40:43], v[158:161], v[130:133], v[40:43]
	global_store_dwordx4 v[100:101], v[56:59], off
	s_nop 1
	v_pk_mul_f32 v[56:57], v[48:49], v[48:49]
	v_max_f32_e32 v49, v50, v50
	v_max_f32_e32 v48, v54, v54
	v_max_f32_e32 v50, 0, v49
	v_max_f32_e32 v49, v55, v55
	v_mfma_f32_16x16x32_bf16 v[44:47], v[154:157], v[130:133], v[44:47]
	v_max_f32_e32 v48, 0, v48
	v_max_f32_e32 v49, 0, v49
	v_pk_mul_f32 v[54:55], v[48:49], v[48:49]
	v_pk_mul_f32 v[58:59], v[50:51], v[50:51]
	v_max_f32_e32 v40, v40, v40
	v_max_f32_e32 v41, v41, v41
	s_waitcnt lgkmcnt(0)
	v_mfma_f32_16x16x32_bf16 v[32:35], v[162:165], v[130:133], v[32:35]
	v_cvt_pk_bf16_f32 v48, v52, v53
	v_cvt_pk_bf16_f32 v49, v54, v55
	v_cvt_pk_bf16_f32 v50, v56, v57
	v_cvt_pk_bf16_f32 v51, v58, v59
	v_max_f32_e32 v40, 0, v40
	v_max_f32_e32 v41, 0, v41
	global_store_dwordx4 v[100:101], v[48:51], off offset:64
	v_max_f32_e32 v44, v44, v44
	v_max_f32_e32 v45, v45, v45
	v_pk_mul_f32 v[48:49], v[40:41], v[40:41]
	v_max_f32_e32 v41, v42, v42
	v_max_f32_e32 v40, v46, v46
	v_max_f32_e32 v42, 0, v41
	v_max_f32_e32 v41, v47, v47
	v_max_f32_e32 v43, v43, v43
	v_mfma_f32_16x16x32_bf16 v[36:39], v[74:77], v[130:133], v[36:39]
	v_max_f32_e32 v44, 0, v44
	v_max_f32_e32 v45, 0, v45
	v_max_f32_e32 v40, 0, v40
	v_max_f32_e32 v41, 0, v41
	v_max_f32_e32 v43, 0, v43
	v_pk_mul_f32 v[44:45], v[44:45], v[44:45]
	v_pk_mul_f32 v[46:47], v[40:41], v[40:41]
	v_pk_mul_f32 v[50:51], v[42:43], v[42:43]
	v_max_f32_e32 v32, v32, v32
	v_max_f32_e32 v33, v33, v33
	v_mfma_f32_16x16x32_bf16 v[24:27], v[146:149], v[134:137], v[24:27]
	v_cvt_pk_bf16_f32 v40, v44, v45
	v_cvt_pk_bf16_f32 v41, v46, v47
	v_cvt_pk_bf16_f32 v42, v48, v49
	v_cvt_pk_bf16_f32 v43, v50, v51
	v_max_f32_e32 v32, 0, v32
	v_max_f32_e32 v33, 0, v33
	global_store_dwordx4 v[100:101], v[40:43], off offset:128
	v_max_f32_e32 v36, v36, v36
	v_max_f32_e32 v37, v37, v37
	v_pk_mul_f32 v[40:41], v[32:33], v[32:33]
	v_max_f32_e32 v33, v34, v34
	v_max_f32_e32 v32, v38, v38
	v_max_f32_e32 v34, 0, v33
	v_max_f32_e32 v33, v39, v39
	v_max_f32_e32 v35, v35, v35
	v_mfma_f32_16x16x32_bf16 v[28:31], v[138:141], v[134:137], v[28:31]
	v_max_f32_e32 v36, 0, v36
	v_max_f32_e32 v37, 0, v37
	v_max_f32_e32 v32, 0, v32
	v_max_f32_e32 v33, 0, v33
	v_max_f32_e32 v35, 0, v35
	v_pk_mul_f32 v[36:37], v[36:37], v[36:37]
	v_pk_mul_f32 v[38:39], v[32:33], v[32:33]
	v_pk_mul_f32 v[42:43], v[34:35], v[34:35]
	v_max_f32_e32 v24, v24, v24
	v_max_f32_e32 v25, v25, v25
	v_mfma_f32_16x16x32_bf16 v[12:15], v[150:153], v[134:137], v[12:15]
	v_cvt_pk_bf16_f32 v32, v36, v37
	v_cvt_pk_bf16_f32 v33, v38, v39
	v_cvt_pk_bf16_f32 v34, v40, v41
	v_cvt_pk_bf16_f32 v35, v42, v43
	v_max_f32_e32 v24, 0, v24
	v_max_f32_e32 v25, 0, v25
	global_store_dwordx4 v[100:101], v[32:35], off offset:192
	v_max_f32_e32 v28, v28, v28
	v_max_f32_e32 v29, v29, v29
	v_pk_mul_f32 v[34:35], v[24:25], v[24:25]
	v_max_f32_e32 v25, v26, v26
	v_add_u32_e32 v32, s33, v84
	v_max_f32_e32 v24, v30, v30
	v_max_f32_e32 v26, 0, v25
	v_max_f32_e32 v25, v31, v31
	v_max_f32_e32 v27, v27, v27
	v_mfma_f32_16x16x32_bf16 v[20:23], v[94:97], v[134:137], v[20:23]
	v_mad_i64_i32 v[32:33], s[34:35], v32, s29, v[98:99]
	v_max_f32_e32 v28, 0, v28
	v_max_f32_e32 v29, 0, v29
	v_max_f32_e32 v24, 0, v24
	v_max_f32_e32 v25, 0, v25
	v_max_f32_e32 v27, 0, v27
	v_lshl_add_u64 v[32:33], v[32:33], 0, s[26:27]
	v_pk_mul_f32 v[28:29], v[28:29], v[28:29]
	v_pk_mul_f32 v[30:31], v[24:25], v[24:25]
	v_pk_mul_f32 v[36:37], v[26:27], v[26:27]
	v_max_f32_e32 v12, v12, v12
	v_max_f32_e32 v13, v13, v13
	v_mfma_f32_16x16x32_bf16 v[4:7], v[158:161], v[134:137], v[4:7]
	v_lshl_add_u64 v[32:33], v[32:33], 0, v[64:65]
	v_cvt_pk_bf16_f32 v24, v28, v29
	v_cvt_pk_bf16_f32 v25, v30, v31
	v_cvt_pk_bf16_f32 v26, v34, v35
	v_cvt_pk_bf16_f32 v27, v36, v37
	v_max_f32_e32 v12, 0, v12
	v_max_f32_e32 v13, 0, v13
	global_store_dwordx4 v[32:33], v[24:27], off
	v_max_f32_e32 v20, v20, v20
	v_max_f32_e32 v21, v21, v21
	v_pk_mul_f32 v[24:25], v[12:13], v[12:13]
	v_max_f32_e32 v13, v14, v14
	v_max_f32_e32 v12, v22, v22
	v_max_f32_e32 v14, 0, v13
	v_max_f32_e32 v13, v23, v23
	v_max_f32_e32 v15, v15, v15
	v_mfma_f32_16x16x32_bf16 v[8:11], v[154:157], v[134:137], v[8:11]
	v_max_f32_e32 v20, 0, v20
	v_max_f32_e32 v21, 0, v21
	v_max_f32_e32 v12, 0, v12
	v_max_f32_e32 v13, 0, v13
	v_max_f32_e32 v15, 0, v15
	v_pk_mul_f32 v[20:21], v[20:21], v[20:21]
	v_pk_mul_f32 v[22:23], v[12:13], v[12:13]
	v_pk_mul_f32 v[26:27], v[14:15], v[14:15]
	v_max_f32_e32 v4, v4, v4
	v_max_f32_e32 v5, v5, v5
	v_cvt_pk_bf16_f32 v12, v20, v21
	v_cvt_pk_bf16_f32 v13, v22, v23
	v_cvt_pk_bf16_f32 v14, v24, v25
	v_cvt_pk_bf16_f32 v15, v26, v27
	v_max_f32_e32 v4, 0, v4
	v_max_f32_e32 v5, 0, v5
	global_store_dwordx4 v[32:33], v[12:15], off offset:64
	v_mfma_f32_16x16x32_bf16 v[0:3], v[74:77], v[134:137], v[0:3]
	v_max_f32_e32 v8, v8, v8
	v_pk_mul_f32 v[12:13], v[4:5], v[4:5]
	v_max_f32_e32 v5, v6, v6
	v_mfma_f32_16x16x32_bf16 v[16:19], v[162:165], v[134:137], v[16:19]
	v_max_f32_e32 v9, v9, v9
	v_max_f32_e32 v4, v10, v10
	v_max_f32_e32 v6, 0, v5
	v_max_f32_e32 v5, v11, v11
	v_max_f32_e32 v7, v7, v7
	v_max_f32_e32 v8, 0, v8
	v_max_f32_e32 v9, 0, v9
	v_max_f32_e32 v4, 0, v4
	v_max_f32_e32 v5, 0, v5
	v_max_f32_e32 v7, 0, v7
	v_pk_mul_f32 v[8:9], v[8:9], v[8:9]
	v_pk_mul_f32 v[10:11], v[4:5], v[4:5]
	v_pk_mul_f32 v[14:15], v[6:7], v[6:7]
	v_cvt_pk_bf16_f32 v4, v8, v9
	v_cvt_pk_bf16_f32 v5, v10, v11
	v_cvt_pk_bf16_f32 v6, v12, v13
	v_cvt_pk_bf16_f32 v7, v14, v15
	global_store_dwordx4 v[32:33], v[4:7], off offset:128
	v_max_f32_e32 v0, v0, v0
	v_max_f32_e32 v1, v1, v1
	v_max_f32_e32 v4, v16, v16
	v_max_f32_e32 v5, v17, v17
	v_max_f32_e32 v2, v2, v2
	v_max_f32_e32 v6, v18, v18
	v_max_f32_e32 v3, v3, v3
	v_max_f32_e32 v7, v19, v19
	v_max_f32_e32 v0, 0, v0
	v_max_f32_e32 v4, 0, v4
	v_max_f32_e32 v1, 0, v1
	v_max_f32_e32 v5, 0, v5
	v_max_f32_e32 v2, 0, v2
	v_max_f32_e32 v6, 0, v6
	v_max_f32_e32 v3, 0, v3
	v_max_f32_e32 v7, 0, v7
	v_pk_mul_f32 v[0:1], v[0:1], v[0:1]
	v_pk_mul_f32 v[4:5], v[4:5], v[4:5]
	v_pk_mul_f32 v[2:3], v[2:3], v[2:3]
	v_pk_mul_f32 v[6:7], v[6:7], v[6:7]
	v_cvt_pk_bf16_f32 v0, v0, v1
	v_cvt_pk_bf16_f32 v1, v2, v3
	v_cvt_pk_bf16_f32 v2, v4, v5
	v_cvt_pk_bf16_f32 v3, v6, v7
	global_store_dwordx4 v[32:33], v[0:3], off offset:192
	s_cbranch_scc0 .LBB0_1754

.LBB0_1823:
	s_ashr_i32 s28, s37, 3
	s_add_i32 s28, s39, s28
	s_ashr_i32 s29, s28, 31
	s_lshr_b32 s29, s29, 26
	s_add_i32 s29, s28, s29
	s_ashr_i32 s38, s29, 6
	s_and_b32 s29, s29, 0xffc0
	s_sub_i32 s28, s28, s29
	s_bfe_i32 s29, s28, 0x80000
	s_bfe_u32 s29, s29, 0x3000c
	s_add_i32 s29, s28, s29
	s_bfe_i32 s37, s29, 0x80000
	s_and_b32 s29, s29, 0xf8
	s_sub_i32 s28, s28, s29
	s_lshl_b32 s38, s38, 3
	s_sext_i32_i8 s28, s28
	s_add_i32 s28, s38, s28
	s_ashr_i32 s29, s28, 31
	s_lshr_b32 s29, s29, 26
	s_add_i32 s29, s28, s29
	s_sext_i32_i16 s37, s37
	s_ashr_i32 s38, s29, 6
	s_andn2_b32 s29, s29, 63
	s_ashr_i32 s37, s37, 3
	s_mulk_i32 s38, 0x42
	s_sub_i32 s28, s28, s29
	s_add_i32 s38, s28, s38
	s_mul_i32 s28, s37, 0x82000
	s_add_i32 s38, s38, 2
	s_ashr_i32 s29, s28, 31
	v_readfirstlane_b32 s39, v91
	v_mad_i64_i32 v[0:1], s[40:41], s38, v90, v[64:65]
	s_lshl_b64 s[28:29], s[28:29], 1
	s_mov_b32 m0, s39
	v_readfirstlane_b32 s39, v92
	v_lshl_add_u64 v[2:3], v[66:67], 0, s[28:29]
	s_waitcnt lgkmcnt(0)
	s_barrier
	global_load_lds_dwordx4 v[0:1], off
	s_mov_b32 m0, s39
	v_readfirstlane_b32 s39, v93
	global_load_lds_dwordx4 v[2:3], off
	v_lshl_add_u64 v[4:5], v[0:1], 0, s[4:5]
	s_mov_b32 m0, s39
	v_readfirstlane_b32 s39, v94
	global_load_lds_dwordx4 v[4:5], off
	v_lshl_add_u64 v[4:5], v[2:3], 0, s[4:5]
	s_mov_b32 m0, s39
	v_readfirstlane_b32 s39, v95
	global_load_lds_dwordx4 v[4:5], off
	v_lshl_add_u64 v[4:5], v[0:1], 0, s[6:7]
	s_mov_b32 m0, s39
	v_readfirstlane_b32 s39, v96
	global_load_lds_dwordx4 v[4:5], off
	v_lshl_add_u64 v[4:5], v[2:3], 0, s[6:7]
	s_mov_b32 m0, s39
	v_readfirstlane_b32 s39, v97
	global_load_lds_dwordx4 v[4:5], off
	v_lshl_add_u64 v[0:1], v[0:1], 0, s[8:9]
	s_mov_b32 m0, s39
	v_readfirstlane_b32 s39, v98
	global_load_lds_dwordx4 v[0:1], off
	v_lshl_add_u64 v[0:1], v[2:3], 0, s[8:9]
	s_mov_b32 m0, s39
	v_mov_b32_e32 v36, 0
	global_load_lds_dwordx4 v[0:1], off
	v_mad_i64_i32 v[72:73], s[40:41], s38, v90, v[68:69]
	v_lshl_add_u64 v[74:75], v[70:71], 0, s[28:29]
	s_mov_b64 s[28:29], 0
	s_mov_b32 s39, 0
	v_mov_b32_e32 v37, v36
	v_mov_b32_e32 v38, v36
	v_mov_b32_e32 v39, v36
	v_mov_b32_e32 v0, v36
	v_mov_b32_e32 v1, v36
	v_mov_b32_e32 v2, v36
	v_mov_b32_e32 v3, v36
	v_mov_b32_e32 v4, v36
	v_mov_b32_e32 v5, v36
	v_mov_b32_e32 v6, v36
	v_mov_b32_e32 v7, v36
	v_mov_b32_e32 v8, v36
	v_mov_b32_e32 v9, v36
	v_mov_b32_e32 v10, v36
	v_mov_b32_e32 v11, v36
	v_mov_b32_e32 v12, v36
	v_mov_b32_e32 v13, v36
	v_mov_b32_e32 v14, v36
	v_mov_b32_e32 v15, v36
	v_mov_b32_e32 v16, v36
	v_mov_b32_e32 v17, v36
	v_mov_b32_e32 v18, v36
	v_mov_b32_e32 v19, v36
	v_mov_b32_e32 v20, v36
	v_mov_b32_e32 v21, v36
	v_mov_b32_e32 v22, v36
	v_mov_b32_e32 v23, v36
	v_mov_b32_e32 v24, v36
	v_mov_b32_e32 v25, v36
	v_mov_b32_e32 v26, v36
	v_mov_b32_e32 v27, v36
	v_mov_b32_e32 v28, v36
	v_mov_b32_e32 v29, v36
	v_mov_b32_e32 v30, v36
	v_mov_b32_e32 v31, v36
	v_mov_b32_e32 v32, v36
	v_mov_b32_e32 v33, v36
	v_mov_b32_e32 v34, v36
	v_mov_b32_e32 v35, v36
	v_mov_b32_e32 v40, v36
	v_mov_b32_e32 v41, v36
	v_mov_b32_e32 v42, v36
	v_mov_b32_e32 v43, v36
	v_mov_b32_e32 v44, v36
	v_mov_b32_e32 v45, v36
	v_mov_b32_e32 v46, v36
	v_mov_b32_e32 v47, v36
	v_mov_b32_e32 v48, v36
	v_mov_b32_e32 v49, v36
	v_mov_b32_e32 v50, v36
	v_mov_b32_e32 v51, v36
	v_mov_b32_e32 v52, v36
	v_mov_b32_e32 v53, v36
	v_mov_b32_e32 v54, v36
	v_mov_b32_e32 v55, v36
	v_mov_b32_e32 v56, v36
	v_mov_b32_e32 v57, v36
	v_mov_b32_e32 v58, v36
	v_mov_b32_e32 v59, v36
	v_mov_b32_e32 v60, v36
	v_mov_b32_e32 v61, v36
	v_mov_b32_e32 v62, v36
	v_mov_b32_e32 v63, v36
	v_readfirstlane_b32 s96, v72
	v_readfirstlane_b32 s97, v73
	v_readfirstlane_b32 s88, v74
	v_readfirstlane_b32 s89, v75
	v_readfirstlane_b32 s87, v82
	s_nop 1
	v_subrev_u32_e32 v244, s96, v72
	v_subrev_u32_e32 v245, s88, v74
	v_add_u32_e32 v246, 0x41000, v244
	v_add_u32_e32 v247, 0x41000, v245
	v_add_u32_e32 v248, 0x82000, v244
	v_add_u32_e32 v249, 0x82000, v245
	v_add_u32_e32 v250, 0xc3000, v244
	v_add_u32_e32 v251, 0xc3000, v245
	s_add_u32 s96, s96, 0x4510080
	s_addc_u32 s97, s97, 0
	s_add_u32 s88, s88, 0xeba0080
	s_addc_u32 s89, s89, 0
.LBB0_1824:
	s_add_i32 s41, s39, 0x8000
	s_and_b32 s40, s41, 0x8000
	s_add_i32 s40, s40, 0
	s_add_u32 s86, s40, s87
	s_mov_b32 m0, s86
	s_waitcnt vmcnt(0) lgkmcnt(0)
	s_barrier
	global_load_lds_dwordx4 v244, s[96:97]
	s_add_u32 m0, s86, 0x4000
	s_nop 0
	global_load_lds_dwordx4 v245, s[88:89]
	s_add_u32 m0, s86, 0x1000
	s_nop 0
	global_load_lds_dwordx4 v246, s[96:97]
	s_add_u32 m0, s86, 0x5000
	s_nop 0
	global_load_lds_dwordx4 v247, s[88:89]
	s_add_u32 m0, s86, 0x2000
	s_nop 0
	global_load_lds_dwordx4 v248, s[96:97]
	s_add_u32 m0, s86, 0x6000
	s_nop 0
	global_load_lds_dwordx4 v249, s[88:89]
	s_add_u32 m0, s86, 0x3000
	s_nop 0
	global_load_lds_dwordx4 v250, s[96:97]
	s_add_u32 m0, s86, 0x7000
	s_nop 0
	global_load_lds_dwordx4 v251, s[88:89]
	s_add_u32 s96, s96, 0x80
	s_addc_u32 s97, s97, 0
	s_add_u32 s88, s88, 0x80
	s_addc_u32 s89, s89, 0
	s_and_b32 s39, s39, 0x8000
	s_add_i32 s39, s39, 0
	v_add3_u32 v145, s39, v84, v85
	v_add3_u32 v178, s39, v85, v86
	v_add3_u32 v179, s39, v84, v87
	v_add3_u32 v180, s39, v86, v87
	ds_read_b128 v[104:107], v178
	ds_read_b128 v[76:79], v145 offset:16384
	ds_read_b128 v[100:103], v145 offset:18432
	ds_read_b128 v[108:111], v178 offset:2048
	ds_read_b128 v[112:115], v145 offset:20480
	ds_read_b128 v[116:119], v145 offset:22528
	ds_read_b128 v[120:123], v145 offset:24576
	ds_read_b128 v[124:127], v145 offset:26624
	ds_read_b128 v[128:131], v145 offset:28672
	ds_read_b128 v[132:135], v145 offset:30720
	ds_read_b128 v[146:149], v180
	ds_read_b128 v[136:139], v179 offset:16384
	ds_read_b128 v[140:143], v179 offset:18432
	ds_read_b128 v[150:153], v180 offset:2048
	ds_read_b128 v[154:157], v179 offset:20480
	ds_read_b128 v[158:161], v179 offset:22528
	ds_read_b128 v[162:165], v179 offset:24576
	ds_read_b128 v[166:169], v179 offset:26624
	ds_read_b128 v[170:173], v179 offset:28672
	ds_read_b128 v[174:177], v179 offset:30720
	s_add_u32 s28, s28, 0x80
	s_addc_u32 s29, s29, 0
	s_cmpk_eq_i32 s28, 0x1f80
	s_mov_b32 s39, s41
	s_waitcnt lgkmcnt(15)
	v_mfma_f32_16x16x32_bf16 v[60:63], v[76:79], v[104:107], v[60:63]
	v_mfma_f32_16x16x32_bf16 v[56:59], v[100:103], v[104:107], v[56:59]
	v_mfma_f32_16x16x32_bf16 v[24:27], v[76:79], v[108:111], v[24:27]
	v_mfma_f32_16x16x32_bf16 v[20:23], v[100:103], v[108:111], v[20:23]
	v_mfma_f32_16x16x32_bf16 v[52:55], v[112:115], v[104:107], v[52:55]
	v_mfma_f32_16x16x32_bf16 v[16:19], v[112:115], v[108:111], v[16:19]
	s_waitcnt lgkmcnt(14)
	v_mfma_f32_16x16x32_bf16 v[48:51], v[116:119], v[104:107], v[48:51]
	v_mfma_f32_16x16x32_bf16 v[12:15], v[116:119], v[108:111], v[12:15]
	s_waitcnt lgkmcnt(13)
	v_mfma_f32_16x16x32_bf16 v[44:47], v[120:123], v[104:107], v[44:47]
	v_mfma_f32_16x16x32_bf16 v[8:11], v[120:123], v[108:111], v[8:11]
	s_waitcnt lgkmcnt(12)
	v_mfma_f32_16x16x32_bf16 v[40:43], v[124:127], v[104:107], v[40:43]
	v_mfma_f32_16x16x32_bf16 v[4:7], v[124:127], v[108:111], v[4:7]
	s_waitcnt lgkmcnt(11)
	v_mfma_f32_16x16x32_bf16 v[32:35], v[128:131], v[104:107], v[32:35]
	v_mfma_f32_16x16x32_bf16 v[0:3], v[128:131], v[108:111], v[0:3]
	s_waitcnt lgkmcnt(10)
	v_mfma_f32_16x16x32_bf16 v[28:31], v[132:135], v[104:107], v[28:31]
	v_mfma_f32_16x16x32_bf16 v[36:39], v[132:135], v[108:111], v[36:39]
	s_waitcnt lgkmcnt(8)
	v_mfma_f32_16x16x32_bf16 v[60:63], v[136:139], v[146:149], v[60:63]
	s_waitcnt lgkmcnt(7)
	v_mfma_f32_16x16x32_bf16 v[56:59], v[140:143], v[146:149], v[56:59]
	s_waitcnt lgkmcnt(6)
	v_mfma_f32_16x16x32_bf16 v[24:27], v[136:139], v[150:153], v[24:27]
	v_mfma_f32_16x16x32_bf16 v[20:23], v[140:143], v[150:153], v[20:23]
	s_waitcnt lgkmcnt(5)
	v_mfma_f32_16x16x32_bf16 v[52:55], v[154:157], v[146:149], v[52:55]
	v_mfma_f32_16x16x32_bf16 v[16:19], v[154:157], v[150:153], v[16:19]
	s_waitcnt lgkmcnt(4)
	v_mfma_f32_16x16x32_bf16 v[48:51], v[158:161], v[146:149], v[48:51]
	v_mfma_f32_16x16x32_bf16 v[12:15], v[158:161], v[150:153], v[12:15]
	s_waitcnt lgkmcnt(3)
	v_mfma_f32_16x16x32_bf16 v[44:47], v[162:165], v[146:149], v[44:47]
	v_mfma_f32_16x16x32_bf16 v[8:11], v[162:165], v[150:153], v[8:11]
	s_waitcnt lgkmcnt(2)
	v_mfma_f32_16x16x32_bf16 v[40:43], v[166:169], v[146:149], v[40:43]
	v_mfma_f32_16x16x32_bf16 v[4:7], v[166:169], v[150:153], v[4:7]
	s_waitcnt lgkmcnt(1)
	v_mfma_f32_16x16x32_bf16 v[32:35], v[170:173], v[146:149], v[32:35]
	v_mfma_f32_16x16x32_bf16 v[0:3], v[170:173], v[150:153], v[0:3]
	s_waitcnt lgkmcnt(0)
	v_mfma_f32_16x16x32_bf16 v[28:31], v[174:177], v[146:149], v[28:31]
	v_mfma_f32_16x16x32_bf16 v[36:39], v[174:177], v[150:153], v[36:39]
	s_cbranch_scc0 .LBB0_1824
	v_add_u32_e32 v80, s40, v84
	v_add_u32_e32 v81, v80, v85
	s_waitcnt vmcnt(0)
	s_barrier
	ds_read_b128 v[72:75], v81 offset:16384
	v_add3_u32 v99, s40, v85, v86
	ds_read_b128 v[76:79], v81 offset:18432
	ds_read_b128 v[100:103], v99
	ds_read_b128 v[104:107], v99 offset:2048
	ds_read_b128 v[108:111], v81 offset:20480
	ds_read_b128 v[112:115], v81 offset:22528
	ds_read_b128 v[116:119], v81 offset:24576
	ds_read_b128 v[120:123], v81 offset:26624
	ds_read_b128 v[124:127], v81 offset:28672
	ds_read_b128 v[128:131], v81 offset:30720
	v_add_u32_e32 v80, v80, v87
	s_waitcnt lgkmcnt(7)
	v_mfma_f32_16x16x32_bf16 v[60:63], v[72:75], v[100:103], v[60:63]
	s_lshl_b32 s38, s38, 7
	v_mfma_f32_16x16x32_bf16 v[56:59], v[76:79], v[100:103], v[56:59]
	s_waitcnt lgkmcnt(4)
	v_mfma_f32_16x16x32_bf16 v[48:51], v[112:115], v[100:103], v[48:51]
	s_waitcnt lgkmcnt(3)
	v_mfma_f32_16x16x32_bf16 v[44:47], v[116:119], v[100:103], v[44:47]
	s_waitcnt lgkmcnt(2)
	v_mfma_f32_16x16x32_bf16 v[40:43], v[120:123], v[100:103], v[40:43]
	s_waitcnt lgkmcnt(1)
	v_mfma_f32_16x16x32_bf16 v[32:35], v[124:127], v[100:103], v[32:35]
	s_waitcnt lgkmcnt(0)
	v_mfma_f32_16x16x32_bf16 v[28:31], v[128:131], v[100:103], v[28:31]
	v_mfma_f32_16x16x32_bf16 v[24:27], v[72:75], v[104:107], v[24:27]
	ds_read_b128 v[72:75], v80 offset:16384
	v_mfma_f32_16x16x32_bf16 v[52:55], v[108:111], v[100:103], v[52:55]
	v_mfma_f32_16x16x32_bf16 v[20:23], v[76:79], v[104:107], v[20:23]
	v_mfma_f32_16x16x32_bf16 v[16:19], v[108:111], v[104:107], v[16:19]
	v_mfma_f32_16x16x32_bf16 v[12:15], v[112:115], v[104:107], v[12:15]
	v_mfma_f32_16x16x32_bf16 v[8:11], v[116:119], v[104:107], v[8:11]
	v_mfma_f32_16x16x32_bf16 v[4:7], v[120:123], v[104:107], v[4:7]
	v_mfma_f32_16x16x32_bf16 v[0:3], v[124:127], v[104:107], v[0:3]
	v_mfma_f32_16x16x32_bf16 v[100:103], v[128:131], v[104:107], v[36:39]
	s_nop 2
	v_add3_u32 v36, s40, v87, v86
	ds_read_b128 v[76:79], v80 offset:18432
	ds_read_b128 v[104:107], v36
	ds_read_b128 v[108:111], v36 offset:2048
	ds_read_b128 v[128:131], v80 offset:28672
	ds_read_b128 v[132:135], v80 offset:30720
	ds_read_b128 v[112:115], v80 offset:20480
	ds_read_b128 v[116:119], v80 offset:22528
	ds_read_b128 v[120:123], v80 offset:24576
	ds_read_b128 v[124:127], v80 offset:26624
	s_waitcnt lgkmcnt(7)
	v_mfma_f32_16x16x32_bf16 v[60:63], v[72:75], v[104:107], v[60:63]
	s_waitcnt lgkmcnt(5)
	v_mfma_f32_16x16x32_bf16 v[36:39], v[128:131], v[104:107], v[32:35]
	s_waitcnt lgkmcnt(4)
	v_mfma_f32_16x16x32_bf16 v[32:35], v[132:135], v[104:107], v[28:31]
	v_mfma_f32_16x16x32_bf16 v[28:31], v[72:75], v[108:111], v[24:27]
	v_add_u32_e32 v72, s38, v83
	v_mul_hi_i32 v73, v72, s31
	v_mfma_f32_16x16x32_bf16 v[24:27], v[76:79], v[108:111], v[20:23]
	s_waitcnt lgkmcnt(3)
	v_mfma_f32_16x16x32_bf16 v[20:23], v[112:115], v[108:111], v[16:19]
	s_waitcnt lgkmcnt(2)
	v_mfma_f32_16x16x32_bf16 v[16:19], v[116:119], v[108:111], v[12:15]
	s_waitcnt lgkmcnt(1)
	v_mfma_f32_16x16x32_bf16 v[12:15], v[120:123], v[108:111], v[8:11]
	s_waitcnt lgkmcnt(0)
	v_mfma_f32_16x16x32_bf16 v[8:11], v[124:127], v[108:111], v[4:7]
	s_nop 2
	v_lshrrev_b32_e32 v4, 31, v73
	v_ashrrev_i32_e32 v5, 11, v73
	v_mfma_f32_16x16x32_bf16 v[56:59], v[76:79], v[104:107], v[56:59]
	v_add_u32_e32 v73, v5, v4
	v_mad_i32_i24 v78, v73, s33, v72
	v_lshlrev_b32_e32 v75, 13, v73
	v_mfma_f32_16x16x32_bf16 v[52:55], v[112:115], v[104:107], v[52:55]
	v_cmp_lt_i32_e32 vcc, s34, v78
	v_add3_u32 v74, v75, v78, s35
	v_mfma_f32_16x16x32_bf16 v[48:51], v[116:119], v[104:107], v[48:51]
	v_mfma_f32_16x16x32_bf16 v[44:47], v[120:123], v[104:107], v[44:47]
	v_mfma_f32_16x16x32_bf16 v[40:43], v[124:127], v[104:107], v[40:43]
	v_mfma_f32_16x16x32_bf16 v[4:7], v[128:131], v[108:111], v[0:3]
	v_mfma_f32_16x16x32_bf16 v[0:3], v[132:135], v[108:111], v[100:103]
	s_and_saveexec_b64 s[28:29], vcc
	s_xor_b64 s[28:29], exec, s[28:29]
	v_add3_u32 v72, v75, v78, s35
	s_or_saveexec_b64 s[28:29], s[28:29]
	v_mov_b64_e32 v[76:77], s[92:93]
	v_lshl_add_u32 v75, v73, 8, v78
	s_xor_b64 exec, exec, s[28:29]
	v_lshl_add_u32 v72, v73, 8, v78
	v_mov_b64_e32 v[76:77], s[2:3]
	s_or_b64 exec, exec, s[28:29]
	s_and_saveexec_b64 s[28:29], vcc
	s_xor_b64 s[28:29], exec, s[28:29]
	s_cbranch_execz .LBB0_1831
	v_add_u32_e32 v73, 3, v73
	v_mul_hi_i32_i24_e32 v79, 0x6000, v73
	v_mul_i32_i24_e32 v78, 0x6000, v73
	s_or_saveexec_b64 s[28:29], s[28:29]
	v_mov_b64_e32 v[80:81], s[92:93]
	s_xor_b64 exec, exec, s[28:29]
	s_cbranch_execnz .LBB0_1832
	s_branch .LBB0_1833
